# stack: handover + merged closing wait (prio raise in front) + s_nop wait states replaced by the DMA address VALU
# speedup vs baseline: 1.0060x; 1.0060x over previous
.LBB0_297:
	s_add_u32 s0, s36, 0xfff80080
	s_addc_u32 s6, s37, -1
	s_add_i32 s49, 0, 0x10000
	s_cmp_eq_u32 s55, 28
	s_cselect_b32 s35, s25, s6
	s_cselect_b32 s34, s33, s0
	v_add_u32_e32 v156, s49, v159
	s_cselect_b32 s31, s40, s39
	s_cselect_b32 s30, s50, s38
	s_add_i32 s0, 0, 0x14000
	ds_read_b128 v[144:147], v156
	ds_read_b128 v[148:151], v156 offset:1024
	ds_read_b128 v[152:155], v156 offset:2048
	ds_read_b128 v[164:167], v156 offset:3072
	v_add_u32_e32 v156, s0, v159
	ds_read_b128 v[168:171], v156
	ds_read_b128 v[172:175], v156 offset:1024
	ds_read_b128 v[176:179], v156 offset:2048
	ds_read_b128 v[180:183], v156 offset:3072
	v_lshl_add_u64 v[156:157], s[36:37], 0, v[140:141]
	s_add_i32 m0, s47, 0xc000
	ds_read_b128 v[184:187], v163
	ds_read_b128 v[188:191], v163 offset:1024
	ds_read_b128 v[192:195], v163 offset:2048
	ds_read_b128 v[200:203], v163 offset:3072
	ds_read_b128 v[204:207], v163 offset:4096
	ds_read_b128 v[208:211], v163 offset:5120
	ds_read_b128 v[212:215], v163 offset:6144
	ds_read_b128 v[216:219], v163 offset:7168
	global_load_lds_dwordx4 v[156:157], off
	s_add_i32 m0, s47, 0xe000
	v_lshl_add_u64 v[156:157], s[36:37], 0, v[142:143]
	global_load_lds_dwordx4 v[156:157], off
	s_setprio 1
	s_waitcnt vmcnt(8) lgkmcnt(0)
	s_barrier
	v_mfma_f32_16x16x32_bf16 v[128:131], v[144:147], v[184:187], v[128:131]
	v_mfma_f32_16x16x32_bf16 v[124:127], v[152:155], v[184:187], v[124:127]
	v_mfma_f32_16x16x32_bf16 v[112:115], v[144:147], v[192:195], v[112:115]
	v_mfma_f32_16x16x32_bf16 v[108:111], v[152:155], v[192:195], v[108:111]
	v_mfma_f32_16x16x32_bf16 v[96:99], v[144:147], v[204:207], v[96:99]
	v_mfma_f32_16x16x32_bf16 v[92:95], v[152:155], v[204:207], v[92:95]
	v_mfma_f32_16x16x32_bf16 v[80:83], v[144:147], v[212:215], v[80:83]
	v_mfma_f32_16x16x32_bf16 v[76:79], v[152:155], v[212:215], v[76:79]
	v_mfma_f32_16x16x32_bf16 v[128:131], v[148:151], v[188:191], v[128:131]
	v_mfma_f32_16x16x32_bf16 v[124:127], v[164:167], v[188:191], v[124:127]
	v_mfma_f32_16x16x32_bf16 v[112:115], v[148:151], v[200:203], v[112:115]
	v_mfma_f32_16x16x32_bf16 v[108:111], v[164:167], v[200:203], v[108:111]
	v_mfma_f32_16x16x32_bf16 v[96:99], v[148:151], v[208:211], v[96:99]
	v_mfma_f32_16x16x32_bf16 v[92:95], v[164:167], v[208:211], v[92:95]
	v_mfma_f32_16x16x32_bf16 v[80:83], v[148:151], v[216:219], v[80:83]
	v_mfma_f32_16x16x32_bf16 v[76:79], v[164:167], v[216:219], v[76:79]
	s_setprio 0
	s_setprio 1
	v_mfma_f32_16x16x32_bf16 v[120:123], v[168:171], v[184:187], v[120:123]
	v_mfma_f32_16x16x32_bf16 v[116:119], v[176:179], v[184:187], v[116:119]
	v_mfma_f32_16x16x32_bf16 v[104:107], v[168:171], v[192:195], v[104:107]
	v_mfma_f32_16x16x32_bf16 v[100:103], v[176:179], v[192:195], v[100:103]
	v_mfma_f32_16x16x32_bf16 v[88:91], v[168:171], v[204:207], v[88:91]
	v_mfma_f32_16x16x32_bf16 v[84:87], v[176:179], v[204:207], v[84:87]
	v_mfma_f32_16x16x32_bf16 v[72:75], v[168:171], v[212:215], v[72:75]
	v_mfma_f32_16x16x32_bf16 v[68:71], v[176:179], v[212:215], v[68:71]
	v_mfma_f32_16x16x32_bf16 v[120:123], v[172:175], v[188:191], v[120:123]
	v_mfma_f32_16x16x32_bf16 v[116:119], v[180:183], v[188:191], v[116:119]
	v_mfma_f32_16x16x32_bf16 v[104:107], v[172:175], v[200:203], v[104:107]
	v_mfma_f32_16x16x32_bf16 v[100:103], v[180:183], v[200:203], v[100:103]
	v_mfma_f32_16x16x32_bf16 v[88:91], v[172:175], v[208:211], v[88:91]
	v_mfma_f32_16x16x32_bf16 v[84:87], v[180:183], v[208:211], v[84:87]
	v_mfma_f32_16x16x32_bf16 v[72:75], v[172:175], v[216:219], v[72:75]
	v_mfma_f32_16x16x32_bf16 v[68:71], v[180:183], v[216:219], v[68:71]
	s_barrier
	s_setprio 0
	s_add_i32 s6, s49, s46
	v_lshl_add_u64 v[156:157], s[30:31], 0, v[136:137]
	s_mov_b32 m0, s6
	ds_read_b128 v[184:187], v163 offset:16384
	ds_read_b128 v[188:191], v163 offset:17408
	ds_read_b128 v[192:195], v163 offset:18432
	ds_read_b128 v[200:203], v163 offset:19456
	ds_read_b128 v[204:207], v163 offset:20480
	ds_read_b128 v[208:211], v163 offset:21504
	ds_read_b128 v[212:215], v163 offset:22528
	ds_read_b128 v[216:219], v163 offset:23552
	global_load_lds_dwordx4 v[156:157], off
	s_add_i32 m0, s6, 0x2000
	s_add_u32 s66, s30, 0x80000
	v_lshl_add_u64 v[220:221], s[30:31], 0, v[132:133]
	s_addc_u32 s67, s31, 0
	s_add_i32 s0, s0, s46
	global_load_lds_dwordx4 v[220:221], off
	v_lshl_add_u64 v[222:223], s[66:67], 0, v[136:137]
	s_mov_b32 m0, s0
	global_load_lds_dwordx4 v[222:223], off
	s_add_i32 m0, s0, 0x2000
	v_lshl_add_u64 v[222:223], s[66:67], 0, v[132:133]
	global_load_lds_dwordx4 v[222:223], off
	s_mov_b32 m0, s47
	v_lshl_add_u64 v[222:223], s[34:35], 0, v[138:139]
	global_load_lds_dwordx4 v[222:223], off
	s_mov_b32 m0, s52
	v_lshl_add_u64 v[224:225], s[34:35], 0, v[134:135]
	global_load_lds_dwordx4 v[224:225], off
	s_setprio 1
	s_waitcnt vmcnt(8) lgkmcnt(0)
	s_barrier
	v_mfma_f32_16x16x32_bf16 v[64:67], v[144:147], v[184:187], v[64:67]
	v_mfma_f32_16x16x32_bf16 v[60:63], v[152:155], v[184:187], v[60:63]
	v_mfma_f32_16x16x32_bf16 v[48:51], v[144:147], v[192:195], v[48:51]
	v_mfma_f32_16x16x32_bf16 v[44:47], v[152:155], v[192:195], v[44:47]
	v_mfma_f32_16x16x32_bf16 v[32:35], v[144:147], v[204:207], v[32:35]
	v_mfma_f32_16x16x32_bf16 v[28:31], v[152:155], v[204:207], v[28:31]
	v_mfma_f32_16x16x32_bf16 v[16:19], v[144:147], v[212:215], v[16:19]
	v_mfma_f32_16x16x32_bf16 v[12:15], v[152:155], v[212:215], v[12:15]
	v_mfma_f32_16x16x32_bf16 v[64:67], v[148:151], v[188:191], v[64:67]
	v_mfma_f32_16x16x32_bf16 v[60:63], v[164:167], v[188:191], v[60:63]
	v_mfma_f32_16x16x32_bf16 v[48:51], v[148:151], v[200:203], v[48:51]
	v_mfma_f32_16x16x32_bf16 v[44:47], v[164:167], v[200:203], v[44:47]
	v_mfma_f32_16x16x32_bf16 v[32:35], v[148:151], v[208:211], v[32:35]
	v_mfma_f32_16x16x32_bf16 v[28:31], v[164:167], v[208:211], v[28:31]
	v_mfma_f32_16x16x32_bf16 v[16:19], v[148:151], v[216:219], v[16:19]
	v_mfma_f32_16x16x32_bf16 v[12:15], v[164:167], v[216:219], v[12:15]
	s_setprio 0
	s_setprio 1
	v_mfma_f32_16x16x32_bf16 v[56:59], v[168:171], v[184:187], v[56:59]
	v_mfma_f32_16x16x32_bf16 v[52:55], v[176:179], v[184:187], v[52:55]
	v_mfma_f32_16x16x32_bf16 v[40:43], v[168:171], v[192:195], v[40:43]
	v_mfma_f32_16x16x32_bf16 v[36:39], v[176:179], v[192:195], v[36:39]
	v_mfma_f32_16x16x32_bf16 v[24:27], v[168:171], v[204:207], v[24:27]
	v_mfma_f32_16x16x32_bf16 v[20:23], v[176:179], v[204:207], v[20:23]
	v_mfma_f32_16x16x32_bf16 v[8:11], v[168:171], v[212:215], v[8:11]
	v_mfma_f32_16x16x32_bf16 v[4:7], v[176:179], v[212:215], v[4:7]
	v_mfma_f32_16x16x32_bf16 v[56:59], v[172:175], v[188:191], v[56:59]
	v_mfma_f32_16x16x32_bf16 v[52:55], v[180:183], v[188:191], v[52:55]
	v_mfma_f32_16x16x32_bf16 v[40:43], v[172:175], v[200:203], v[40:43]
	v_mfma_f32_16x16x32_bf16 v[36:39], v[180:183], v[200:203], v[36:39]
	v_mfma_f32_16x16x32_bf16 v[24:27], v[172:175], v[208:211], v[24:27]
	v_mfma_f32_16x16x32_bf16 v[20:23], v[180:183], v[208:211], v[20:23]
	v_mfma_f32_16x16x32_bf16 v[8:11], v[172:175], v[216:219], v[8:11]
	v_mfma_f32_16x16x32_bf16 v[4:7], v[180:183], v[216:219], v[4:7]
	s_barrier
	s_setprio 0
	s_add_i32 s0, 0, 0x18000
	v_add_u32_e32 v158, s0, v159
	s_add_i32 s6, 0, 0x1c000
	ds_read_b128 v[144:147], v158
	ds_read_b128 v[148:151], v158 offset:1024
	ds_read_b128 v[152:155], v158 offset:2048
	ds_read_b128 v[164:167], v158 offset:3072
	v_add_u32_e32 v158, s6, v159
	ds_read_b128 v[168:171], v158
	ds_read_b128 v[172:175], v158 offset:1024
	ds_read_b128 v[176:179], v158 offset:2048
	ds_read_b128 v[180:183], v158 offset:3072
	s_add_u32 s34, s34, 0x80000
	s_addc_u32 s35, s35, 0
	s_mov_b32 m0, s53
	v_lshl_add_u64 v[226:227], s[34:35], 0, v[138:139]
	ds_read_b128 v[184:187], v163 offset:32768
	ds_read_b128 v[188:191], v163 offset:33792
	ds_read_b128 v[192:195], v163 offset:34816
	ds_read_b128 v[200:203], v163 offset:35840
	ds_read_b128 v[204:207], v163 offset:36864
	ds_read_b128 v[208:211], v163 offset:37888
	ds_read_b128 v[212:215], v163 offset:38912
	ds_read_b128 v[216:219], v163 offset:39936
	global_load_lds_dwordx4 v[226:227], off
	s_mov_b32 m0, s60
	v_lshl_add_u64 v[226:227], s[34:35], 0, v[134:135]
	global_load_lds_dwordx4 v[226:227], off
	s_setprio 1
	s_waitcnt vmcnt(8) lgkmcnt(0)
	s_barrier
	v_mfma_f32_16x16x32_bf16 v[128:131], v[144:147], v[184:187], v[128:131]
	v_mfma_f32_16x16x32_bf16 v[124:127], v[152:155], v[184:187], v[124:127]
	v_mfma_f32_16x16x32_bf16 v[112:115], v[144:147], v[192:195], v[112:115]
	v_mfma_f32_16x16x32_bf16 v[108:111], v[152:155], v[192:195], v[108:111]
	v_mfma_f32_16x16x32_bf16 v[96:99], v[144:147], v[204:207], v[96:99]
	v_mfma_f32_16x16x32_bf16 v[92:95], v[152:155], v[204:207], v[92:95]
	v_mfma_f32_16x16x32_bf16 v[80:83], v[144:147], v[212:215], v[80:83]
	v_mfma_f32_16x16x32_bf16 v[76:79], v[152:155], v[212:215], v[76:79]
	v_mfma_f32_16x16x32_bf16 v[128:131], v[148:151], v[188:191], v[128:131]
	v_mfma_f32_16x16x32_bf16 v[124:127], v[164:167], v[188:191], v[124:127]
	v_mfma_f32_16x16x32_bf16 v[112:115], v[148:151], v[200:203], v[112:115]
	v_mfma_f32_16x16x32_bf16 v[108:111], v[164:167], v[200:203], v[108:111]
	v_mfma_f32_16x16x32_bf16 v[96:99], v[148:151], v[208:211], v[96:99]
	v_mfma_f32_16x16x32_bf16 v[92:95], v[164:167], v[208:211], v[92:95]
	v_mfma_f32_16x16x32_bf16 v[80:83], v[148:151], v[216:219], v[80:83]
	v_mfma_f32_16x16x32_bf16 v[76:79], v[164:167], v[216:219], v[76:79]
	s_setprio 0
	s_setprio 1
	v_mfma_f32_16x16x32_bf16 v[120:123], v[168:171], v[184:187], v[120:123]
	v_mfma_f32_16x16x32_bf16 v[116:119], v[176:179], v[184:187], v[116:119]
	v_mfma_f32_16x16x32_bf16 v[104:107], v[168:171], v[192:195], v[104:107]
	v_mfma_f32_16x16x32_bf16 v[100:103], v[176:179], v[192:195], v[100:103]
	v_mfma_f32_16x16x32_bf16 v[88:91], v[168:171], v[204:207], v[88:91]
	v_mfma_f32_16x16x32_bf16 v[84:87], v[176:179], v[204:207], v[84:87]
	v_mfma_f32_16x16x32_bf16 v[72:75], v[168:171], v[212:215], v[72:75]
	v_mfma_f32_16x16x32_bf16 v[68:71], v[176:179], v[212:215], v[68:71]
	v_mfma_f32_16x16x32_bf16 v[120:123], v[172:175], v[188:191], v[120:123]
	v_mfma_f32_16x16x32_bf16 v[116:119], v[180:183], v[188:191], v[116:119]
	v_mfma_f32_16x16x32_bf16 v[104:107], v[172:175], v[200:203], v[104:107]
	v_mfma_f32_16x16x32_bf16 v[100:103], v[180:183], v[200:203], v[100:103]
	v_mfma_f32_16x16x32_bf16 v[88:91], v[172:175], v[208:211], v[88:91]
	v_mfma_f32_16x16x32_bf16 v[84:87], v[180:183], v[208:211], v[84:87]
	v_mfma_f32_16x16x32_bf16 v[72:75], v[172:175], v[216:219], v[72:75]
	v_mfma_f32_16x16x32_bf16 v[68:71], v[180:183], v[216:219], v[68:71]
	s_barrier
	s_setprio 0
	s_add_i32 s0, s0, s46
	v_lshl_add_u64 v[156:157], v[156:157], 0, s[90:91]
	s_mov_b32 m0, s0
	ds_read_b128 v[184:187], v163 offset:49152
	ds_read_b128 v[188:191], v163 offset:50176
	ds_read_b128 v[192:195], v163 offset:51200
	ds_read_b128 v[200:203], v163 offset:52224
	ds_read_b128 v[204:207], v163 offset:53248
	ds_read_b128 v[208:211], v163 offset:54272
	ds_read_b128 v[212:215], v163 offset:55296
	ds_read_b128 v[216:219], v163 offset:56320
	global_load_lds_dwordx4 v[156:157], off
	s_add_i32 m0, s0, 0x2000
	s_add_u32 s30, s30, 0x80080
	v_lshl_add_u64 v[156:157], v[220:221], 0, s[90:91]
	s_addc_u32 s31, s31, 0
	s_add_i32 s0, s6, s46
	global_load_lds_dwordx4 v[156:157], off
	s_mov_b32 m0, s0
	v_lshl_add_u64 v[156:157], s[30:31], 0, v[136:137]
	global_load_lds_dwordx4 v[156:157], off
	s_add_i32 m0, s0, 0x2000
	v_lshl_add_u64 v[156:157], s[30:31], 0, v[132:133]
	global_load_lds_dwordx4 v[156:157], off
	s_mov_b32 m0, s62
	v_lshl_add_u64 v[156:157], v[222:223], 0, s[90:91]
	global_load_lds_dwordx4 v[156:157], off
	s_mov_b32 m0, s51
	v_lshl_add_u64 v[156:157], v[224:225], 0, s[90:91]
	global_load_lds_dwordx4 v[156:157], off
	s_setprio 1
	s_waitcnt vmcnt(8) lgkmcnt(0)
	s_barrier
	v_mfma_f32_16x16x32_bf16 v[64:67], v[144:147], v[184:187], v[64:67]
	v_mfma_f32_16x16x32_bf16 v[60:63], v[152:155], v[184:187], v[60:63]
	v_mfma_f32_16x16x32_bf16 v[48:51], v[144:147], v[192:195], v[48:51]
	v_mfma_f32_16x16x32_bf16 v[44:47], v[152:155], v[192:195], v[44:47]
	v_mfma_f32_16x16x32_bf16 v[32:35], v[144:147], v[204:207], v[32:35]
	v_mfma_f32_16x16x32_bf16 v[28:31], v[152:155], v[204:207], v[28:31]
	v_mfma_f32_16x16x32_bf16 v[16:19], v[144:147], v[212:215], v[16:19]
	v_mfma_f32_16x16x32_bf16 v[12:15], v[152:155], v[212:215], v[12:15]
	v_mfma_f32_16x16x32_bf16 v[64:67], v[148:151], v[188:191], v[64:67]
	v_mfma_f32_16x16x32_bf16 v[60:63], v[164:167], v[188:191], v[60:63]
	v_mfma_f32_16x16x32_bf16 v[48:51], v[148:151], v[200:203], v[48:51]
	v_mfma_f32_16x16x32_bf16 v[44:47], v[164:167], v[200:203], v[44:47]
	v_mfma_f32_16x16x32_bf16 v[32:35], v[148:151], v[208:211], v[32:35]
	v_mfma_f32_16x16x32_bf16 v[28:31], v[164:167], v[208:211], v[28:31]
	v_mfma_f32_16x16x32_bf16 v[16:19], v[148:151], v[216:219], v[16:19]
	v_mfma_f32_16x16x32_bf16 v[12:15], v[164:167], v[216:219], v[12:15]
	s_setprio 0
	s_setprio 1
	v_mfma_f32_16x16x32_bf16 v[56:59], v[168:171], v[184:187], v[56:59]
	v_mfma_f32_16x16x32_bf16 v[52:55], v[176:179], v[184:187], v[52:55]
	v_mfma_f32_16x16x32_bf16 v[40:43], v[168:171], v[192:195], v[40:43]
	v_mfma_f32_16x16x32_bf16 v[36:39], v[176:179], v[192:195], v[36:39]
	v_mfma_f32_16x16x32_bf16 v[24:27], v[168:171], v[204:207], v[24:27]
	v_mfma_f32_16x16x32_bf16 v[20:23], v[176:179], v[204:207], v[20:23]
	v_mfma_f32_16x16x32_bf16 v[8:11], v[168:171], v[212:215], v[8:11]
	v_mfma_f32_16x16x32_bf16 v[4:7], v[176:179], v[212:215], v[4:7]
	v_mfma_f32_16x16x32_bf16 v[56:59], v[172:175], v[188:191], v[56:59]
	v_mfma_f32_16x16x32_bf16 v[52:55], v[180:183], v[188:191], v[52:55]
	v_mfma_f32_16x16x32_bf16 v[40:43], v[172:175], v[200:203], v[40:43]
	v_mfma_f32_16x16x32_bf16 v[36:39], v[180:183], v[200:203], v[36:39]
	v_mfma_f32_16x16x32_bf16 v[24:27], v[172:175], v[208:211], v[24:27]
	v_mfma_f32_16x16x32_bf16 v[20:23], v[180:183], v[208:211], v[20:23]
	v_mfma_f32_16x16x32_bf16 v[8:11], v[172:175], v[216:219], v[8:11]
	v_mfma_f32_16x16x32_bf16 v[4:7], v[180:183], v[216:219], v[4:7]
	s_barrier
	s_setprio 0
	s_add_i32 s55, s55, 2
	s_add_u32 s36, s36, 0x100
	s_addc_u32 s37, s37, 0
	s_add_u32 s38, s38, 0x100
	s_addc_u32 s39, s39, 0
	s_cmp_gt_u32 s55, 29
	s_cbranch_scc0 .LBB0_297
	s_and_b64 vcc, exec, s[22:23]
	s_cbranch_vccz .LBB0_300
	s_barrier

.LBB0_336:
	s_add_u32 s0, s36, 0xfff80080
	s_addc_u32 s6, s37, -1
	s_add_i32 s49, 0, 0x10000
	s_cmp_eq_u32 s50, 28
	s_cselect_b32 s35, s24, s6
	s_cselect_b32 s34, s25, s0
	v_add_u32_e32 v156, s49, v159
	s_cselect_b32 s31, s33, s39
	s_cselect_b32 s30, s40, s38
	s_add_i32 s0, 0, 0x14000
	ds_read_b128 v[144:147], v156
	ds_read_b128 v[148:151], v156 offset:1024
	ds_read_b128 v[152:155], v156 offset:2048
	ds_read_b128 v[164:167], v156 offset:3072
	v_add_u32_e32 v156, s0, v159
	ds_read_b128 v[168:171], v156
	ds_read_b128 v[172:175], v156 offset:1024
	ds_read_b128 v[176:179], v156 offset:2048
	ds_read_b128 v[180:183], v156 offset:3072
	v_lshl_add_u64 v[156:157], s[36:37], 0, v[140:141]
	s_add_i32 m0, s45, 0xc000
	ds_read_b128 v[184:187], v163
	ds_read_b128 v[188:191], v163 offset:1024
	ds_read_b128 v[192:195], v163 offset:2048
	ds_read_b128 v[200:203], v163 offset:3072
	ds_read_b128 v[204:207], v163 offset:4096
	ds_read_b128 v[208:211], v163 offset:5120
	ds_read_b128 v[212:215], v163 offset:6144
	ds_read_b128 v[216:219], v163 offset:7168
	global_load_lds_dwordx4 v[156:157], off
	s_add_i32 m0, s45, 0xe000
	v_lshl_add_u64 v[156:157], s[36:37], 0, v[142:143]
	global_load_lds_dwordx4 v[156:157], off
	s_setprio 1
	s_waitcnt vmcnt(8) lgkmcnt(0)
	s_barrier
	v_mfma_f32_16x16x32_bf16 v[128:131], v[144:147], v[184:187], v[128:131]
	v_mfma_f32_16x16x32_bf16 v[124:127], v[152:155], v[184:187], v[124:127]
	v_mfma_f32_16x16x32_bf16 v[112:115], v[144:147], v[192:195], v[112:115]
	v_mfma_f32_16x16x32_bf16 v[108:111], v[152:155], v[192:195], v[108:111]
	v_mfma_f32_16x16x32_bf16 v[96:99], v[144:147], v[204:207], v[96:99]
	v_mfma_f32_16x16x32_bf16 v[92:95], v[152:155], v[204:207], v[92:95]
	v_mfma_f32_16x16x32_bf16 v[80:83], v[144:147], v[212:215], v[80:83]
	v_mfma_f32_16x16x32_bf16 v[76:79], v[152:155], v[212:215], v[76:79]
	v_mfma_f32_16x16x32_bf16 v[128:131], v[148:151], v[188:191], v[128:131]
	v_mfma_f32_16x16x32_bf16 v[124:127], v[164:167], v[188:191], v[124:127]
	v_mfma_f32_16x16x32_bf16 v[112:115], v[148:151], v[200:203], v[112:115]
	v_mfma_f32_16x16x32_bf16 v[108:111], v[164:167], v[200:203], v[108:111]
	v_mfma_f32_16x16x32_bf16 v[96:99], v[148:151], v[208:211], v[96:99]
	v_mfma_f32_16x16x32_bf16 v[92:95], v[164:167], v[208:211], v[92:95]
	v_mfma_f32_16x16x32_bf16 v[80:83], v[148:151], v[216:219], v[80:83]
	v_mfma_f32_16x16x32_bf16 v[76:79], v[164:167], v[216:219], v[76:79]
	s_setprio 0
	s_setprio 1
	v_mfma_f32_16x16x32_bf16 v[120:123], v[168:171], v[184:187], v[120:123]
	v_mfma_f32_16x16x32_bf16 v[116:119], v[176:179], v[184:187], v[116:119]
	v_mfma_f32_16x16x32_bf16 v[104:107], v[168:171], v[192:195], v[104:107]
	v_mfma_f32_16x16x32_bf16 v[100:103], v[176:179], v[192:195], v[100:103]
	v_mfma_f32_16x16x32_bf16 v[88:91], v[168:171], v[204:207], v[88:91]
	v_mfma_f32_16x16x32_bf16 v[84:87], v[176:179], v[204:207], v[84:87]
	v_mfma_f32_16x16x32_bf16 v[72:75], v[168:171], v[212:215], v[72:75]
	v_mfma_f32_16x16x32_bf16 v[68:71], v[176:179], v[212:215], v[68:71]
	v_mfma_f32_16x16x32_bf16 v[120:123], v[172:175], v[188:191], v[120:123]
	v_mfma_f32_16x16x32_bf16 v[116:119], v[180:183], v[188:191], v[116:119]
	v_mfma_f32_16x16x32_bf16 v[104:107], v[172:175], v[200:203], v[104:107]
	v_mfma_f32_16x16x32_bf16 v[100:103], v[180:183], v[200:203], v[100:103]
	v_mfma_f32_16x16x32_bf16 v[88:91], v[172:175], v[208:211], v[88:91]
	v_mfma_f32_16x16x32_bf16 v[84:87], v[180:183], v[208:211], v[84:87]
	v_mfma_f32_16x16x32_bf16 v[72:75], v[172:175], v[216:219], v[72:75]
	v_mfma_f32_16x16x32_bf16 v[68:71], v[180:183], v[216:219], v[68:71]
	s_barrier
	s_setprio 0
	s_add_i32 s6, s49, s47
	v_lshl_add_u64 v[156:157], s[30:31], 0, v[136:137]
	s_mov_b32 m0, s6
	ds_read_b128 v[184:187], v163 offset:16384
	ds_read_b128 v[188:191], v163 offset:17408
	ds_read_b128 v[192:195], v163 offset:18432
	ds_read_b128 v[200:203], v163 offset:19456
	ds_read_b128 v[204:207], v163 offset:20480
	ds_read_b128 v[208:211], v163 offset:21504
	ds_read_b128 v[212:215], v163 offset:22528
	ds_read_b128 v[216:219], v163 offset:23552
	global_load_lds_dwordx4 v[156:157], off
	s_add_i32 m0, s6, 0x2000
	s_add_u32 s54, s30, 0x80000
	v_lshl_add_u64 v[220:221], s[30:31], 0, v[132:133]
	s_addc_u32 s55, s31, 0
	s_add_i32 s0, s0, s47
	global_load_lds_dwordx4 v[220:221], off
	v_lshl_add_u64 v[222:223], s[54:55], 0, v[136:137]
	s_mov_b32 m0, s0
	global_load_lds_dwordx4 v[222:223], off
	s_add_i32 m0, s0, 0x2000
	v_lshl_add_u64 v[222:223], s[54:55], 0, v[132:133]
	global_load_lds_dwordx4 v[222:223], off
	s_mov_b32 m0, s45
	v_lshl_add_u64 v[222:223], s[34:35], 0, v[138:139]
	global_load_lds_dwordx4 v[222:223], off
	s_mov_b32 m0, s61
	v_lshl_add_u64 v[224:225], s[34:35], 0, v[134:135]
	global_load_lds_dwordx4 v[224:225], off
	s_setprio 1
	s_waitcnt vmcnt(8) lgkmcnt(0)
	s_barrier
	v_mfma_f32_16x16x32_bf16 v[64:67], v[144:147], v[184:187], v[64:67]
	v_mfma_f32_16x16x32_bf16 v[60:63], v[152:155], v[184:187], v[60:63]
	v_mfma_f32_16x16x32_bf16 v[48:51], v[144:147], v[192:195], v[48:51]
	v_mfma_f32_16x16x32_bf16 v[44:47], v[152:155], v[192:195], v[44:47]
	v_mfma_f32_16x16x32_bf16 v[32:35], v[144:147], v[204:207], v[32:35]
	v_mfma_f32_16x16x32_bf16 v[28:31], v[152:155], v[204:207], v[28:31]
	v_mfma_f32_16x16x32_bf16 v[16:19], v[144:147], v[212:215], v[16:19]
	v_mfma_f32_16x16x32_bf16 v[12:15], v[152:155], v[212:215], v[12:15]
	v_mfma_f32_16x16x32_bf16 v[64:67], v[148:151], v[188:191], v[64:67]
	v_mfma_f32_16x16x32_bf16 v[60:63], v[164:167], v[188:191], v[60:63]
	v_mfma_f32_16x16x32_bf16 v[48:51], v[148:151], v[200:203], v[48:51]
	v_mfma_f32_16x16x32_bf16 v[44:47], v[164:167], v[200:203], v[44:47]
	v_mfma_f32_16x16x32_bf16 v[32:35], v[148:151], v[208:211], v[32:35]
	v_mfma_f32_16x16x32_bf16 v[28:31], v[164:167], v[208:211], v[28:31]
	v_mfma_f32_16x16x32_bf16 v[16:19], v[148:151], v[216:219], v[16:19]
	v_mfma_f32_16x16x32_bf16 v[12:15], v[164:167], v[216:219], v[12:15]
	s_setprio 0
	s_setprio 1
	v_mfma_f32_16x16x32_bf16 v[56:59], v[168:171], v[184:187], v[56:59]
	v_mfma_f32_16x16x32_bf16 v[52:55], v[176:179], v[184:187], v[52:55]
	v_mfma_f32_16x16x32_bf16 v[40:43], v[168:171], v[192:195], v[40:43]
	v_mfma_f32_16x16x32_bf16 v[36:39], v[176:179], v[192:195], v[36:39]
	v_mfma_f32_16x16x32_bf16 v[24:27], v[168:171], v[204:207], v[24:27]
	v_mfma_f32_16x16x32_bf16 v[20:23], v[176:179], v[204:207], v[20:23]
	v_mfma_f32_16x16x32_bf16 v[8:11], v[168:171], v[212:215], v[8:11]
	v_mfma_f32_16x16x32_bf16 v[4:7], v[176:179], v[212:215], v[4:7]
	v_mfma_f32_16x16x32_bf16 v[56:59], v[172:175], v[188:191], v[56:59]
	v_mfma_f32_16x16x32_bf16 v[52:55], v[180:183], v[188:191], v[52:55]
	v_mfma_f32_16x16x32_bf16 v[40:43], v[172:175], v[200:203], v[40:43]
	v_mfma_f32_16x16x32_bf16 v[36:39], v[180:183], v[200:203], v[36:39]
	v_mfma_f32_16x16x32_bf16 v[24:27], v[172:175], v[208:211], v[24:27]
	v_mfma_f32_16x16x32_bf16 v[20:23], v[180:183], v[208:211], v[20:23]
	v_mfma_f32_16x16x32_bf16 v[8:11], v[172:175], v[216:219], v[8:11]
	v_mfma_f32_16x16x32_bf16 v[4:7], v[180:183], v[216:219], v[4:7]
	s_barrier
	s_setprio 0
	s_add_i32 s0, 0, 0x18000
	v_add_u32_e32 v158, s0, v159
	s_add_i32 s6, 0, 0x1c000
	ds_read_b128 v[144:147], v158
	ds_read_b128 v[148:151], v158 offset:1024
	ds_read_b128 v[152:155], v158 offset:2048
	ds_read_b128 v[164:167], v158 offset:3072
	v_add_u32_e32 v158, s6, v159
	ds_read_b128 v[168:171], v158
	ds_read_b128 v[172:175], v158 offset:1024
	ds_read_b128 v[176:179], v158 offset:2048
	ds_read_b128 v[180:183], v158 offset:3072
	s_add_u32 s34, s34, 0x80000
	s_addc_u32 s35, s35, 0
	s_mov_b32 m0, s62
	v_lshl_add_u64 v[226:227], s[34:35], 0, v[138:139]
	ds_read_b128 v[184:187], v163 offset:32768
	ds_read_b128 v[188:191], v163 offset:33792
	ds_read_b128 v[192:195], v163 offset:34816
	ds_read_b128 v[200:203], v163 offset:35840
	ds_read_b128 v[204:207], v163 offset:36864
	ds_read_b128 v[208:211], v163 offset:37888
	ds_read_b128 v[212:215], v163 offset:38912
	ds_read_b128 v[216:219], v163 offset:39936
	global_load_lds_dwordx4 v[226:227], off
	s_mov_b32 m0, s63
	v_lshl_add_u64 v[226:227], s[34:35], 0, v[134:135]
	global_load_lds_dwordx4 v[226:227], off
	s_setprio 1
	s_waitcnt vmcnt(8) lgkmcnt(0)
	s_barrier
	v_mfma_f32_16x16x32_bf16 v[128:131], v[144:147], v[184:187], v[128:131]
	v_mfma_f32_16x16x32_bf16 v[124:127], v[152:155], v[184:187], v[124:127]
	v_mfma_f32_16x16x32_bf16 v[112:115], v[144:147], v[192:195], v[112:115]
	v_mfma_f32_16x16x32_bf16 v[108:111], v[152:155], v[192:195], v[108:111]
	v_mfma_f32_16x16x32_bf16 v[96:99], v[144:147], v[204:207], v[96:99]
	v_mfma_f32_16x16x32_bf16 v[92:95], v[152:155], v[204:207], v[92:95]
	v_mfma_f32_16x16x32_bf16 v[80:83], v[144:147], v[212:215], v[80:83]
	v_mfma_f32_16x16x32_bf16 v[76:79], v[152:155], v[212:215], v[76:79]
	v_mfma_f32_16x16x32_bf16 v[128:131], v[148:151], v[188:191], v[128:131]
	v_mfma_f32_16x16x32_bf16 v[124:127], v[164:167], v[188:191], v[124:127]
	v_mfma_f32_16x16x32_bf16 v[112:115], v[148:151], v[200:203], v[112:115]
	v_mfma_f32_16x16x32_bf16 v[108:111], v[164:167], v[200:203], v[108:111]
	v_mfma_f32_16x16x32_bf16 v[96:99], v[148:151], v[208:211], v[96:99]
	v_mfma_f32_16x16x32_bf16 v[92:95], v[164:167], v[208:211], v[92:95]
	v_mfma_f32_16x16x32_bf16 v[80:83], v[148:151], v[216:219], v[80:83]
	v_mfma_f32_16x16x32_bf16 v[76:79], v[164:167], v[216:219], v[76:79]
	s_setprio 0
	s_setprio 1
	v_mfma_f32_16x16x32_bf16 v[120:123], v[168:171], v[184:187], v[120:123]
	v_mfma_f32_16x16x32_bf16 v[116:119], v[176:179], v[184:187], v[116:119]
	v_mfma_f32_16x16x32_bf16 v[104:107], v[168:171], v[192:195], v[104:107]
	v_mfma_f32_16x16x32_bf16 v[100:103], v[176:179], v[192:195], v[100:103]
	v_mfma_f32_16x16x32_bf16 v[88:91], v[168:171], v[204:207], v[88:91]
	v_mfma_f32_16x16x32_bf16 v[84:87], v[176:179], v[204:207], v[84:87]
	v_mfma_f32_16x16x32_bf16 v[72:75], v[168:171], v[212:215], v[72:75]
	v_mfma_f32_16x16x32_bf16 v[68:71], v[176:179], v[212:215], v[68:71]
	v_mfma_f32_16x16x32_bf16 v[120:123], v[172:175], v[188:191], v[120:123]
	v_mfma_f32_16x16x32_bf16 v[116:119], v[180:183], v[188:191], v[116:119]
	v_mfma_f32_16x16x32_bf16 v[104:107], v[172:175], v[200:203], v[104:107]
	v_mfma_f32_16x16x32_bf16 v[100:103], v[180:183], v[200:203], v[100:103]
	v_mfma_f32_16x16x32_bf16 v[88:91], v[172:175], v[208:211], v[88:91]
	v_mfma_f32_16x16x32_bf16 v[84:87], v[180:183], v[208:211], v[84:87]
	v_mfma_f32_16x16x32_bf16 v[72:75], v[172:175], v[216:219], v[72:75]
	v_mfma_f32_16x16x32_bf16 v[68:71], v[180:183], v[216:219], v[68:71]
	s_barrier
	s_setprio 0
	s_add_i32 s0, s0, s47
	v_lshl_add_u64 v[156:157], v[156:157], 0, s[90:91]
	s_mov_b32 m0, s0
	ds_read_b128 v[184:187], v163 offset:49152
	ds_read_b128 v[188:191], v163 offset:50176
	ds_read_b128 v[192:195], v163 offset:51200
	ds_read_b128 v[200:203], v163 offset:52224
	ds_read_b128 v[204:207], v163 offset:53248
	ds_read_b128 v[208:211], v163 offset:54272
	ds_read_b128 v[212:215], v163 offset:55296
	ds_read_b128 v[216:219], v163 offset:56320
	global_load_lds_dwordx4 v[156:157], off
	s_add_i32 m0, s0, 0x2000
	s_add_u32 s30, s30, 0x80080
	v_lshl_add_u64 v[156:157], v[220:221], 0, s[90:91]
	s_addc_u32 s31, s31, 0
	s_add_i32 s0, s6, s47
	global_load_lds_dwordx4 v[156:157], off
	s_mov_b32 m0, s0
	v_lshl_add_u64 v[156:157], s[30:31], 0, v[136:137]
	global_load_lds_dwordx4 v[156:157], off
	s_add_i32 m0, s0, 0x2000
	v_lshl_add_u64 v[156:157], s[30:31], 0, v[132:133]
	global_load_lds_dwordx4 v[156:157], off
	s_mov_b32 m0, s51
	v_lshl_add_u64 v[156:157], v[222:223], 0, s[90:91]
	global_load_lds_dwordx4 v[156:157], off
	s_mov_b32 m0, s4
	v_lshl_add_u64 v[156:157], v[224:225], 0, s[90:91]
	global_load_lds_dwordx4 v[156:157], off
	s_setprio 1
	s_waitcnt vmcnt(8) lgkmcnt(0)
	s_barrier
	v_mfma_f32_16x16x32_bf16 v[64:67], v[144:147], v[184:187], v[64:67]
	v_mfma_f32_16x16x32_bf16 v[60:63], v[152:155], v[184:187], v[60:63]
	v_mfma_f32_16x16x32_bf16 v[48:51], v[144:147], v[192:195], v[48:51]
	v_mfma_f32_16x16x32_bf16 v[44:47], v[152:155], v[192:195], v[44:47]
	v_mfma_f32_16x16x32_bf16 v[32:35], v[144:147], v[204:207], v[32:35]
	v_mfma_f32_16x16x32_bf16 v[28:31], v[152:155], v[204:207], v[28:31]
	v_mfma_f32_16x16x32_bf16 v[16:19], v[144:147], v[212:215], v[16:19]
	v_mfma_f32_16x16x32_bf16 v[12:15], v[152:155], v[212:215], v[12:15]
	v_mfma_f32_16x16x32_bf16 v[64:67], v[148:151], v[188:191], v[64:67]
	v_mfma_f32_16x16x32_bf16 v[60:63], v[164:167], v[188:191], v[60:63]
	v_mfma_f32_16x16x32_bf16 v[48:51], v[148:151], v[200:203], v[48:51]
	v_mfma_f32_16x16x32_bf16 v[44:47], v[164:167], v[200:203], v[44:47]
	v_mfma_f32_16x16x32_bf16 v[32:35], v[148:151], v[208:211], v[32:35]
	v_mfma_f32_16x16x32_bf16 v[28:31], v[164:167], v[208:211], v[28:31]
	v_mfma_f32_16x16x32_bf16 v[16:19], v[148:151], v[216:219], v[16:19]
	v_mfma_f32_16x16x32_bf16 v[12:15], v[164:167], v[216:219], v[12:15]
	s_setprio 0
	s_setprio 1
	v_mfma_f32_16x16x32_bf16 v[56:59], v[168:171], v[184:187], v[56:59]
	v_mfma_f32_16x16x32_bf16 v[52:55], v[176:179], v[184:187], v[52:55]
	v_mfma_f32_16x16x32_bf16 v[40:43], v[168:171], v[192:195], v[40:43]
	v_mfma_f32_16x16x32_bf16 v[36:39], v[176:179], v[192:195], v[36:39]
	v_mfma_f32_16x16x32_bf16 v[24:27], v[168:171], v[204:207], v[24:27]
	v_mfma_f32_16x16x32_bf16 v[20:23], v[176:179], v[204:207], v[20:23]
	v_mfma_f32_16x16x32_bf16 v[8:11], v[168:171], v[212:215], v[8:11]
	v_mfma_f32_16x16x32_bf16 v[4:7], v[176:179], v[212:215], v[4:7]
	v_mfma_f32_16x16x32_bf16 v[56:59], v[172:175], v[188:191], v[56:59]
	v_mfma_f32_16x16x32_bf16 v[52:55], v[180:183], v[188:191], v[52:55]
	v_mfma_f32_16x16x32_bf16 v[40:43], v[172:175], v[200:203], v[40:43]
	v_mfma_f32_16x16x32_bf16 v[36:39], v[180:183], v[200:203], v[36:39]
	v_mfma_f32_16x16x32_bf16 v[24:27], v[172:175], v[208:211], v[24:27]
	v_mfma_f32_16x16x32_bf16 v[20:23], v[180:183], v[208:211], v[20:23]
	v_mfma_f32_16x16x32_bf16 v[8:11], v[172:175], v[216:219], v[8:11]
	v_mfma_f32_16x16x32_bf16 v[4:7], v[180:183], v[216:219], v[4:7]
	s_barrier
	s_setprio 0
	s_add_i32 s50, s50, 2
	s_add_u32 s36, s36, 0x100
	s_addc_u32 s37, s37, 0
	s_add_u32 s38, s38, 0x100
	s_addc_u32 s39, s39, 0
	s_cmp_gt_u32 s50, 29
	s_cbranch_scc0 .LBB0_336
	s_and_b64 vcc, exec, s[22:23]
	s_cbranch_vccz .LBB0_339
	s_barrier

.LBB0_747:
	s_add_i32 s0, s6, 2
	s_add_u32 s25, s66, 0xfffc0080
	s_addc_u32 s29, s67, -1
	s_add_i32 s33, 0, 0x10000
	s_cmp_eq_u32 s13, s6
	s_cselect_b32 s35, s45, s29
	s_cselect_b32 s34, s44, s25
	v_add_u32_e32 v3, s33, v237
	s_cselect_b32 s31, s61, s24
	s_cselect_b32 s30, s60, s15
	s_add_i32 s6, 0, 0x14000
	ds_read_b128 v[146:149], v3
	ds_read_b128 v[150:153], v3 offset:1024
	ds_read_b128 v[154:157], v3 offset:2048
	ds_read_b128 v[158:161], v3 offset:3072
	v_add_u32_e32 v3, s6, v237
	ds_read_b128 v[162:165], v3
	ds_read_b128 v[166:169], v3 offset:1024
	ds_read_b128 v[170:173], v3 offset:2048
	ds_read_b128 v[174:177], v3 offset:3072
	v_lshl_add_u64 v[4:5], s[66:67], 0, v[142:143]
	s_add_i32 m0, s52, 0xc000
	ds_read_b128 v[178:181], v249
	ds_read_b128 v[182:185], v249 offset:1024
	ds_read_b128 v[186:189], v249 offset:2048
	ds_read_b128 v[190:193], v249 offset:3072
	ds_read_b128 v[200:203], v249 offset:4096
	ds_read_b128 v[204:207], v249 offset:5120
	ds_read_b128 v[208:211], v249 offset:6144
	ds_read_b128 v[212:215], v249 offset:7168
	global_load_lds_dwordx4 v[4:5], off
	s_add_i32 m0, s52, 0xe000
	v_lshl_add_u64 v[4:5], s[66:67], 0, v[144:145]
	global_load_lds_dwordx4 v[4:5], off
	s_setprio 1
	s_waitcnt vmcnt(8) lgkmcnt(0)
	s_barrier
	v_mfma_f32_16x16x32_bf16 v[130:133], v[146:149], v[178:181], v[130:133]
	v_mfma_f32_16x16x32_bf16 v[126:129], v[154:157], v[178:181], v[126:129]
	v_mfma_f32_16x16x32_bf16 v[122:125], v[146:149], v[186:189], v[122:125]
	v_mfma_f32_16x16x32_bf16 v[118:121], v[154:157], v[186:189], v[118:121]
	v_mfma_f32_16x16x32_bf16 v[114:117], v[146:149], v[200:203], v[114:117]
	v_mfma_f32_16x16x32_bf16 v[110:113], v[154:157], v[200:203], v[110:113]
	v_mfma_f32_16x16x32_bf16 v[106:109], v[146:149], v[208:211], v[106:109]
	v_mfma_f32_16x16x32_bf16 v[102:105], v[154:157], v[208:211], v[102:105]
	v_mfma_f32_16x16x32_bf16 v[130:133], v[150:153], v[182:185], v[130:133]
	v_mfma_f32_16x16x32_bf16 v[126:129], v[158:161], v[182:185], v[126:129]
	v_mfma_f32_16x16x32_bf16 v[122:125], v[150:153], v[190:193], v[122:125]
	v_mfma_f32_16x16x32_bf16 v[118:121], v[158:161], v[190:193], v[118:121]
	v_mfma_f32_16x16x32_bf16 v[114:117], v[150:153], v[204:207], v[114:117]
	v_mfma_f32_16x16x32_bf16 v[110:113], v[158:161], v[204:207], v[110:113]
	v_mfma_f32_16x16x32_bf16 v[106:109], v[150:153], v[212:215], v[106:109]
	v_mfma_f32_16x16x32_bf16 v[102:105], v[158:161], v[212:215], v[102:105]
	s_setprio 0
	s_setprio 1
	v_mfma_f32_16x16x32_bf16 v[98:101], v[162:165], v[178:181], v[98:101]
	v_mfma_f32_16x16x32_bf16 v[94:97], v[170:173], v[178:181], v[94:97]
	v_mfma_f32_16x16x32_bf16 v[90:93], v[162:165], v[186:189], v[90:93]
	v_mfma_f32_16x16x32_bf16 v[86:89], v[170:173], v[186:189], v[86:89]
	v_mfma_f32_16x16x32_bf16 v[82:85], v[162:165], v[200:203], v[82:85]
	v_mfma_f32_16x16x32_bf16 v[78:81], v[170:173], v[200:203], v[78:81]
	v_mfma_f32_16x16x32_bf16 v[74:77], v[162:165], v[208:211], v[74:77]
	v_mfma_f32_16x16x32_bf16 v[70:73], v[170:173], v[208:211], v[70:73]
	v_mfma_f32_16x16x32_bf16 v[98:101], v[166:169], v[182:185], v[98:101]
	v_mfma_f32_16x16x32_bf16 v[94:97], v[174:177], v[182:185], v[94:97]
	v_mfma_f32_16x16x32_bf16 v[90:93], v[166:169], v[190:193], v[90:93]
	v_mfma_f32_16x16x32_bf16 v[86:89], v[174:177], v[190:193], v[86:89]
	v_mfma_f32_16x16x32_bf16 v[82:85], v[166:169], v[204:207], v[82:85]
	v_mfma_f32_16x16x32_bf16 v[78:81], v[174:177], v[204:207], v[78:81]
	v_mfma_f32_16x16x32_bf16 v[74:77], v[166:169], v[212:215], v[74:77]
	v_mfma_f32_16x16x32_bf16 v[70:73], v[174:177], v[212:215], v[70:73]
	s_barrier
	s_setprio 0
	s_add_i32 s25, s33, s47
	v_lshl_add_u64 v[194:195], s[30:31], 0, v[136:137]
	s_mov_b32 m0, s25
	ds_read_b128 v[178:181], v249 offset:16384
	ds_read_b128 v[182:185], v249 offset:17408
	ds_read_b128 v[186:189], v249 offset:18432
	ds_read_b128 v[190:193], v249 offset:19456
	ds_read_b128 v[200:203], v249 offset:20480
	ds_read_b128 v[204:207], v249 offset:21504
	ds_read_b128 v[208:211], v249 offset:22528
	ds_read_b128 v[212:215], v249 offset:23552
	global_load_lds_dwordx4 v[194:195], off
	s_add_i32 m0, s25, 0x2000
	s_add_u32 s36, s30, 0x40000
	v_lshl_add_u64 v[216:217], s[30:31], 0, v[140:141]
	s_addc_u32 s37, s31, 0
	s_add_i32 s6, s6, s47
	global_load_lds_dwordx4 v[216:217], off
	v_lshl_add_u64 v[4:5], s[36:37], 0, v[136:137]
	s_mov_b32 m0, s6
	global_load_lds_dwordx4 v[4:5], off
	v_lshl_add_u64 v[4:5], s[36:37], 0, v[140:141]
	s_add_i32 m0, s6, 0x2000
	global_load_lds_dwordx4 v[4:5], off
	s_mov_b32 m0, s52
	v_lshl_add_u64 v[218:219], s[34:35], 0, v[134:135]
	global_load_lds_dwordx4 v[218:219], off
	s_mov_b32 m0, s53
	v_lshl_add_u64 v[220:221], s[34:35], 0, v[138:139]
	global_load_lds_dwordx4 v[220:221], off
	s_setprio 1
	s_waitcnt vmcnt(8) lgkmcnt(0)
	s_barrier
	v_mfma_f32_16x16x32_bf16 v[66:69], v[146:149], v[178:181], v[66:69]
	v_mfma_f32_16x16x32_bf16 v[62:65], v[154:157], v[178:181], v[62:65]
	v_mfma_f32_16x16x32_bf16 v[58:61], v[146:149], v[186:189], v[58:61]
	v_mfma_f32_16x16x32_bf16 v[54:57], v[154:157], v[186:189], v[54:57]
	v_mfma_f32_16x16x32_bf16 v[50:53], v[146:149], v[200:203], v[50:53]
	v_mfma_f32_16x16x32_bf16 v[46:49], v[154:157], v[200:203], v[46:49]
	v_mfma_f32_16x16x32_bf16 v[42:45], v[146:149], v[208:211], v[42:45]
	v_mfma_f32_16x16x32_bf16 v[38:41], v[154:157], v[208:211], v[38:41]
	v_mfma_f32_16x16x32_bf16 v[66:69], v[150:153], v[182:185], v[66:69]
	v_mfma_f32_16x16x32_bf16 v[62:65], v[158:161], v[182:185], v[62:65]
	v_mfma_f32_16x16x32_bf16 v[58:61], v[150:153], v[190:193], v[58:61]
	v_mfma_f32_16x16x32_bf16 v[54:57], v[158:161], v[190:193], v[54:57]
	v_mfma_f32_16x16x32_bf16 v[50:53], v[150:153], v[204:207], v[50:53]
	v_mfma_f32_16x16x32_bf16 v[46:49], v[158:161], v[204:207], v[46:49]
	v_mfma_f32_16x16x32_bf16 v[42:45], v[150:153], v[212:215], v[42:45]
	v_mfma_f32_16x16x32_bf16 v[38:41], v[158:161], v[212:215], v[38:41]
	s_setprio 0
	s_setprio 1
	v_mfma_f32_16x16x32_bf16 v[34:37], v[162:165], v[178:181], v[34:37]
	v_mfma_f32_16x16x32_bf16 v[30:33], v[170:173], v[178:181], v[30:33]
	v_mfma_f32_16x16x32_bf16 v[26:29], v[162:165], v[186:189], v[26:29]
	v_mfma_f32_16x16x32_bf16 v[22:25], v[170:173], v[186:189], v[22:25]
	v_mfma_f32_16x16x32_bf16 v[18:21], v[162:165], v[200:203], v[18:21]
	v_mfma_f32_16x16x32_bf16 v[14:17], v[170:173], v[200:203], v[14:17]
	v_mfma_f32_16x16x32_bf16 v[10:13], v[162:165], v[208:211], v[10:13]
	v_mfma_f32_16x16x32_bf16 v[4:7], v[170:173], v[208:211], v[6:9]
	v_mfma_f32_16x16x32_bf16 v[34:37], v[166:169], v[182:185], v[34:37]
	v_mfma_f32_16x16x32_bf16 v[30:33], v[174:177], v[182:185], v[30:33]
	v_mfma_f32_16x16x32_bf16 v[26:29], v[166:169], v[190:193], v[26:29]
	v_mfma_f32_16x16x32_bf16 v[22:25], v[174:177], v[190:193], v[22:25]
	v_mfma_f32_16x16x32_bf16 v[18:21], v[166:169], v[204:207], v[18:21]
	v_mfma_f32_16x16x32_bf16 v[14:17], v[174:177], v[204:207], v[14:17]
	v_mfma_f32_16x16x32_bf16 v[10:13], v[166:169], v[212:215], v[10:13]
	v_mfma_f32_16x16x32_bf16 v[4:7], v[174:177], v[212:215], v[4:7]
	s_barrier
	s_setprio 0
	s_add_i32 s6, 0, 0x18000
	v_add_u32_e32 v3, s6, v237
	s_add_i32 s25, 0, 0x1c000
	ds_read_b128 v[146:149], v3
	ds_read_b128 v[150:153], v3 offset:1024
	ds_read_b128 v[154:157], v3 offset:2048
	ds_read_b128 v[158:161], v3 offset:3072
	v_add_u32_e32 v3, s25, v237
	ds_read_b128 v[162:165], v3
	ds_read_b128 v[166:169], v3 offset:1024
	ds_read_b128 v[170:173], v3 offset:2048
	ds_read_b128 v[174:177], v3 offset:3072
	s_add_u32 s34, s34, 0x40000
	s_addc_u32 s35, s35, 0
	s_mov_b32 m0, s59
	v_lshl_add_u64 v[8:9], s[34:35], 0, v[134:135]
	ds_read_b128 v[178:181], v249 offset:32768
	ds_read_b128 v[182:185], v249 offset:33792
	ds_read_b128 v[186:189], v249 offset:34816
	ds_read_b128 v[190:193], v249 offset:35840
	ds_read_b128 v[200:203], v249 offset:36864
	ds_read_b128 v[204:207], v249 offset:37888
	ds_read_b128 v[208:211], v249 offset:38912
	ds_read_b128 v[212:215], v249 offset:39936
	global_load_lds_dwordx4 v[8:9], off
	s_mov_b32 m0, s63
	v_lshl_add_u64 v[8:9], s[34:35], 0, v[138:139]
	global_load_lds_dwordx4 v[8:9], off
	s_setprio 1
	s_waitcnt vmcnt(8) lgkmcnt(0)
	s_barrier
	v_mfma_f32_16x16x32_bf16 v[130:133], v[146:149], v[178:181], v[130:133]
	v_mfma_f32_16x16x32_bf16 v[126:129], v[154:157], v[178:181], v[126:129]
	v_mfma_f32_16x16x32_bf16 v[122:125], v[146:149], v[186:189], v[122:125]
	v_mfma_f32_16x16x32_bf16 v[118:121], v[154:157], v[186:189], v[118:121]
	v_mfma_f32_16x16x32_bf16 v[114:117], v[146:149], v[200:203], v[114:117]
	v_mfma_f32_16x16x32_bf16 v[110:113], v[154:157], v[200:203], v[110:113]
	v_mfma_f32_16x16x32_bf16 v[106:109], v[146:149], v[208:211], v[106:109]
	v_mfma_f32_16x16x32_bf16 v[102:105], v[154:157], v[208:211], v[102:105]
	v_mfma_f32_16x16x32_bf16 v[130:133], v[150:153], v[182:185], v[130:133]
	v_mfma_f32_16x16x32_bf16 v[126:129], v[158:161], v[182:185], v[126:129]
	v_mfma_f32_16x16x32_bf16 v[122:125], v[150:153], v[190:193], v[122:125]
	v_mfma_f32_16x16x32_bf16 v[118:121], v[158:161], v[190:193], v[118:121]
	v_mfma_f32_16x16x32_bf16 v[114:117], v[150:153], v[204:207], v[114:117]
	v_mfma_f32_16x16x32_bf16 v[110:113], v[158:161], v[204:207], v[110:113]
	v_mfma_f32_16x16x32_bf16 v[106:109], v[150:153], v[212:215], v[106:109]
	v_mfma_f32_16x16x32_bf16 v[102:105], v[158:161], v[212:215], v[102:105]
	s_setprio 0
	s_setprio 1
	v_mfma_f32_16x16x32_bf16 v[98:101], v[162:165], v[178:181], v[98:101]
	v_mfma_f32_16x16x32_bf16 v[94:97], v[170:173], v[178:181], v[94:97]
	v_mfma_f32_16x16x32_bf16 v[90:93], v[162:165], v[186:189], v[90:93]
	v_mfma_f32_16x16x32_bf16 v[86:89], v[170:173], v[186:189], v[86:89]
	v_mfma_f32_16x16x32_bf16 v[82:85], v[162:165], v[200:203], v[82:85]
	v_mfma_f32_16x16x32_bf16 v[78:81], v[170:173], v[200:203], v[78:81]
	v_mfma_f32_16x16x32_bf16 v[74:77], v[162:165], v[208:211], v[74:77]
	v_mfma_f32_16x16x32_bf16 v[70:73], v[170:173], v[208:211], v[70:73]
	v_mfma_f32_16x16x32_bf16 v[98:101], v[166:169], v[182:185], v[98:101]
	v_mfma_f32_16x16x32_bf16 v[94:97], v[174:177], v[182:185], v[94:97]
	v_mfma_f32_16x16x32_bf16 v[90:93], v[166:169], v[190:193], v[90:93]
	v_mfma_f32_16x16x32_bf16 v[86:89], v[174:177], v[190:193], v[86:89]
	v_mfma_f32_16x16x32_bf16 v[82:85], v[166:169], v[204:207], v[82:85]
	v_mfma_f32_16x16x32_bf16 v[78:81], v[174:177], v[204:207], v[78:81]
	v_mfma_f32_16x16x32_bf16 v[74:77], v[166:169], v[212:215], v[74:77]
	v_mfma_f32_16x16x32_bf16 v[70:73], v[174:177], v[212:215], v[70:73]
	s_barrier
	s_setprio 0
	s_add_i32 s6, s6, s47
	v_lshl_add_u64 v[8:9], v[194:195], 0, s[90:91]
	s_mov_b32 m0, s6
	ds_read_b128 v[178:181], v249 offset:49152
	ds_read_b128 v[182:185], v249 offset:50176
	ds_read_b128 v[186:189], v249 offset:51200
	ds_read_b128 v[190:193], v249 offset:52224
	ds_read_b128 v[200:203], v249 offset:53248
	ds_read_b128 v[204:207], v249 offset:54272
	ds_read_b128 v[208:211], v249 offset:55296
	ds_read_b128 v[212:215], v249 offset:56320
	global_load_lds_dwordx4 v[8:9], off
	s_add_i32 m0, s6, 0x2000
	s_add_u32 s30, s30, 0x40080
	v_lshl_add_u64 v[8:9], v[216:217], 0, s[90:91]
	s_addc_u32 s31, s31, 0
	s_add_i32 s6, s25, s47
	global_load_lds_dwordx4 v[8:9], off
	s_mov_b32 m0, s6
	v_lshl_add_u64 v[8:9], s[30:31], 0, v[136:137]
	global_load_lds_dwordx4 v[8:9], off
	s_add_i32 m0, s6, 0x2000
	v_lshl_add_u64 v[8:9], s[30:31], 0, v[140:141]
	global_load_lds_dwordx4 v[8:9], off
	s_mov_b32 m0, s80
	v_lshl_add_u64 v[8:9], v[218:219], 0, s[90:91]
	global_load_lds_dwordx4 v[8:9], off
	s_mov_b32 m0, s81
	v_lshl_add_u64 v[8:9], v[220:221], 0, s[90:91]
	global_load_lds_dwordx4 v[8:9], off
	s_setprio 1
	s_waitcnt vmcnt(8) lgkmcnt(0)
	s_barrier
	v_mfma_f32_16x16x32_bf16 v[66:69], v[146:149], v[178:181], v[66:69]
	v_mfma_f32_16x16x32_bf16 v[62:65], v[154:157], v[178:181], v[62:65]
	v_mfma_f32_16x16x32_bf16 v[58:61], v[146:149], v[186:189], v[58:61]
	v_mfma_f32_16x16x32_bf16 v[54:57], v[154:157], v[186:189], v[54:57]
	v_mfma_f32_16x16x32_bf16 v[50:53], v[146:149], v[200:203], v[50:53]
	v_mfma_f32_16x16x32_bf16 v[46:49], v[154:157], v[200:203], v[46:49]
	v_mfma_f32_16x16x32_bf16 v[42:45], v[146:149], v[208:211], v[42:45]
	v_mfma_f32_16x16x32_bf16 v[38:41], v[154:157], v[208:211], v[38:41]
	v_mfma_f32_16x16x32_bf16 v[66:69], v[150:153], v[182:185], v[66:69]
	v_mfma_f32_16x16x32_bf16 v[62:65], v[158:161], v[182:185], v[62:65]
	v_mfma_f32_16x16x32_bf16 v[58:61], v[150:153], v[190:193], v[58:61]
	v_mfma_f32_16x16x32_bf16 v[54:57], v[158:161], v[190:193], v[54:57]
	v_mfma_f32_16x16x32_bf16 v[50:53], v[150:153], v[204:207], v[50:53]
	v_mfma_f32_16x16x32_bf16 v[46:49], v[158:161], v[204:207], v[46:49]
	v_mfma_f32_16x16x32_bf16 v[42:45], v[150:153], v[212:215], v[42:45]
	v_mfma_f32_16x16x32_bf16 v[38:41], v[158:161], v[212:215], v[38:41]
	s_setprio 0
	s_setprio 1
	v_mfma_f32_16x16x32_bf16 v[34:37], v[162:165], v[178:181], v[34:37]
	v_mfma_f32_16x16x32_bf16 v[30:33], v[170:173], v[178:181], v[30:33]
	v_mfma_f32_16x16x32_bf16 v[26:29], v[162:165], v[186:189], v[26:29]
	v_mfma_f32_16x16x32_bf16 v[22:25], v[170:173], v[186:189], v[22:25]
	v_mfma_f32_16x16x32_bf16 v[18:21], v[162:165], v[200:203], v[18:21]
	v_mfma_f32_16x16x32_bf16 v[14:17], v[170:173], v[200:203], v[14:17]
	v_mfma_f32_16x16x32_bf16 v[8:11], v[162:165], v[208:211], v[10:13]
	v_mfma_f32_16x16x32_bf16 v[4:7], v[170:173], v[208:211], v[4:7]
	v_mfma_f32_16x16x32_bf16 v[34:37], v[166:169], v[182:185], v[34:37]
	v_mfma_f32_16x16x32_bf16 v[30:33], v[174:177], v[182:185], v[30:33]
	v_mfma_f32_16x16x32_bf16 v[26:29], v[166:169], v[190:193], v[26:29]
	v_mfma_f32_16x16x32_bf16 v[22:25], v[174:177], v[190:193], v[22:25]
	v_mfma_f32_16x16x32_bf16 v[18:21], v[166:169], v[204:207], v[18:21]
	v_mfma_f32_16x16x32_bf16 v[14:17], v[174:177], v[204:207], v[14:17]
	v_mfma_f32_16x16x32_bf16 v[10:13], v[166:169], v[212:215], v[8:11]
	v_mfma_f32_16x16x32_bf16 v[6:9], v[174:177], v[212:215], v[4:7]
	s_barrier
	s_setprio 0
	s_add_u32 s66, s66, 0x100
	s_addc_u32 s67, s67, 0
	s_add_u32 s15, s15, 0x100
	s_addc_u32 s24, s24, 0
	s_cmp_ge_i32 s0, s1
	s_mov_b32 s6, s0
	s_cbranch_scc0 .LBB0_747

.LBB0_967:
	s_add_u32 s0, s36, 0xfff80080
	s_addc_u32 s6, s37, -1
	s_add_i32 s49, 0, 0x10000
	s_cmp_eq_u32 s55, 28
	s_cselect_b32 s35, s65, s6
	s_cselect_b32 s34, s64, s0
	s_cselect_b32 s31, s67, s39
	s_cselect_b32 s30, s66, s38
	s_add_i32 s0, 0, 0x14000
	v_add_u32_e32 v144, s49, v3
	v_add_u32_e32 v160, s0, v3
	ds_read_b128 v[124:127], v144
	ds_read_b128 v[128:131], v144 offset:1024
	ds_read_b128 v[140:143], v144 offset:2048
	ds_read_b128 v[144:147], v144 offset:3072
	ds_read_b128 v[148:151], v160
	ds_read_b128 v[152:155], v160 offset:1024
	ds_read_b128 v[156:159], v160 offset:2048
	ds_read_b128 v[160:163], v160 offset:3072
	v_lshl_add_u64 v[198:199], s[36:37], 0, v[212:213]
	s_add_i32 m0, s4, 0xc000
	ds_read_b128 v[164:167], v250
	ds_read_b128 v[168:171], v250 offset:1024
	ds_read_b128 v[172:175], v250 offset:2048
	ds_read_b128 v[176:179], v250 offset:3072
	ds_read_b128 v[180:183], v250 offset:4096
	ds_read_b128 v[184:187], v250 offset:5120
	ds_read_b128 v[188:191], v250 offset:6144
	ds_read_b128 v[192:195], v250 offset:7168
	global_load_lds_dwordx4 v[198:199], off
	s_add_i32 m0, s4, 0xe000
	v_lshl_add_u64 v[198:199], s[36:37], 0, v[214:215]
	global_load_lds_dwordx4 v[198:199], off
	s_setprio 1
	s_waitcnt vmcnt(8) lgkmcnt(0)
	s_barrier
	v_mfma_f32_16x16x32_bf16 v[136:139], v[124:127], v[164:167], v[136:139]
	v_mfma_f32_16x16x32_bf16 v[132:135], v[140:143], v[164:167], v[132:135]
	v_mfma_f32_16x16x32_bf16 v[112:115], v[124:127], v[172:175], v[112:115]
	v_mfma_f32_16x16x32_bf16 v[108:111], v[140:143], v[172:175], v[108:111]
	v_mfma_f32_16x16x32_bf16 v[96:99], v[124:127], v[180:183], v[96:99]
	v_mfma_f32_16x16x32_bf16 v[92:95], v[140:143], v[180:183], v[92:95]
	v_mfma_f32_16x16x32_bf16 v[80:83], v[124:127], v[188:191], v[80:83]
	v_mfma_f32_16x16x32_bf16 v[76:79], v[140:143], v[188:191], v[76:79]
	v_mfma_f32_16x16x32_bf16 v[136:139], v[128:131], v[168:171], v[136:139]
	v_mfma_f32_16x16x32_bf16 v[132:135], v[144:147], v[168:171], v[132:135]
	v_mfma_f32_16x16x32_bf16 v[112:115], v[128:131], v[176:179], v[112:115]
	v_mfma_f32_16x16x32_bf16 v[108:111], v[144:147], v[176:179], v[108:111]
	v_mfma_f32_16x16x32_bf16 v[96:99], v[128:131], v[184:187], v[96:99]
	v_mfma_f32_16x16x32_bf16 v[92:95], v[144:147], v[184:187], v[92:95]
	v_mfma_f32_16x16x32_bf16 v[80:83], v[128:131], v[192:195], v[80:83]
	v_mfma_f32_16x16x32_bf16 v[76:79], v[144:147], v[192:195], v[76:79]
	s_setprio 0
	s_setprio 1
	v_mfma_f32_16x16x32_bf16 v[120:123], v[148:151], v[164:167], v[120:123]
	v_mfma_f32_16x16x32_bf16 v[116:119], v[156:159], v[164:167], v[116:119]
	v_mfma_f32_16x16x32_bf16 v[104:107], v[148:151], v[172:175], v[104:107]
	v_mfma_f32_16x16x32_bf16 v[100:103], v[156:159], v[172:175], v[100:103]
	v_mfma_f32_16x16x32_bf16 v[88:91], v[148:151], v[180:183], v[88:91]
	v_mfma_f32_16x16x32_bf16 v[84:87], v[156:159], v[180:183], v[84:87]
	v_mfma_f32_16x16x32_bf16 v[72:75], v[148:151], v[188:191], v[72:75]
	v_mfma_f32_16x16x32_bf16 v[68:71], v[156:159], v[188:191], v[68:71]
	v_mfma_f32_16x16x32_bf16 v[120:123], v[152:155], v[168:171], v[120:123]
	v_mfma_f32_16x16x32_bf16 v[116:119], v[160:163], v[168:171], v[116:119]
	v_mfma_f32_16x16x32_bf16 v[104:107], v[152:155], v[176:179], v[104:107]
	v_mfma_f32_16x16x32_bf16 v[100:103], v[160:163], v[176:179], v[100:103]
	v_mfma_f32_16x16x32_bf16 v[88:91], v[152:155], v[184:187], v[88:91]
	v_mfma_f32_16x16x32_bf16 v[84:87], v[160:163], v[184:187], v[84:87]
	v_mfma_f32_16x16x32_bf16 v[72:75], v[152:155], v[192:195], v[72:75]
	v_mfma_f32_16x16x32_bf16 v[68:71], v[160:163], v[192:195], v[68:71]
	s_barrier
	s_setprio 0
	s_add_i32 s6, s49, s1
	v_lshl_add_u64 v[198:199], s[30:31], 0, v[204:205]
	s_mov_b32 m0, s6
	ds_read_b128 v[164:167], v250 offset:16384
	ds_read_b128 v[168:171], v250 offset:17408
	ds_read_b128 v[172:175], v250 offset:18432
	ds_read_b128 v[176:179], v250 offset:19456
	ds_read_b128 v[180:183], v250 offset:20480
	ds_read_b128 v[184:187], v250 offset:21504
	ds_read_b128 v[188:191], v250 offset:22528
	ds_read_b128 v[192:195], v250 offset:23552
	global_load_lds_dwordx4 v[198:199], off
	s_add_i32 m0, s6, 0x2000
	s_add_u32 s68, s30, 0x80000
	v_lshl_add_u64 v[216:217], s[30:31], 0, v[200:201]
	s_addc_u32 s69, s31, 0
	s_add_i32 s0, s0, s1
	global_load_lds_dwordx4 v[216:217], off
	v_lshl_add_u64 v[218:219], s[68:69], 0, v[204:205]
	s_mov_b32 m0, s0
	global_load_lds_dwordx4 v[218:219], off
	s_add_i32 m0, s0, 0x2000
	v_lshl_add_u64 v[218:219], s[68:69], 0, v[200:201]
	global_load_lds_dwordx4 v[218:219], off
	s_mov_b32 m0, s4
	v_lshl_add_u64 v[218:219], s[34:35], 0, v[206:207]
	global_load_lds_dwordx4 v[218:219], off
	s_mov_b32 m0, s24
	v_lshl_add_u64 v[220:221], s[34:35], 0, v[202:203]
	global_load_lds_dwordx4 v[220:221], off
	s_setprio 1
	s_waitcnt vmcnt(8) lgkmcnt(0)
	s_barrier
	v_mfma_f32_16x16x32_bf16 v[64:67], v[124:127], v[164:167], v[64:67]
	v_mfma_f32_16x16x32_bf16 v[60:63], v[140:143], v[164:167], v[60:63]
	v_mfma_f32_16x16x32_bf16 v[48:51], v[124:127], v[172:175], v[48:51]
	v_mfma_f32_16x16x32_bf16 v[44:47], v[140:143], v[172:175], v[44:47]
	v_mfma_f32_16x16x32_bf16 v[32:35], v[124:127], v[180:183], v[32:35]
	v_mfma_f32_16x16x32_bf16 v[28:31], v[140:143], v[180:183], v[28:31]
	v_mfma_f32_16x16x32_bf16 v[16:19], v[124:127], v[188:191], v[16:19]
	v_mfma_f32_16x16x32_bf16 v[12:15], v[140:143], v[188:191], v[12:15]
	v_mfma_f32_16x16x32_bf16 v[64:67], v[128:131], v[168:171], v[64:67]
	v_mfma_f32_16x16x32_bf16 v[60:63], v[144:147], v[168:171], v[60:63]
	v_mfma_f32_16x16x32_bf16 v[48:51], v[128:131], v[176:179], v[48:51]
	v_mfma_f32_16x16x32_bf16 v[44:47], v[144:147], v[176:179], v[44:47]
	v_mfma_f32_16x16x32_bf16 v[32:35], v[128:131], v[184:187], v[32:35]
	v_mfma_f32_16x16x32_bf16 v[28:31], v[144:147], v[184:187], v[28:31]
	v_mfma_f32_16x16x32_bf16 v[16:19], v[128:131], v[192:195], v[16:19]
	v_mfma_f32_16x16x32_bf16 v[12:15], v[144:147], v[192:195], v[12:15]
	s_setprio 0
	s_setprio 1
	v_mfma_f32_16x16x32_bf16 v[56:59], v[148:151], v[164:167], v[56:59]
	v_mfma_f32_16x16x32_bf16 v[52:55], v[156:159], v[164:167], v[52:55]
	v_mfma_f32_16x16x32_bf16 v[40:43], v[148:151], v[172:175], v[40:43]
	v_mfma_f32_16x16x32_bf16 v[36:39], v[156:159], v[172:175], v[36:39]
	v_mfma_f32_16x16x32_bf16 v[24:27], v[148:151], v[180:183], v[24:27]
	v_mfma_f32_16x16x32_bf16 v[20:23], v[156:159], v[180:183], v[20:23]
	v_mfma_f32_16x16x32_bf16 v[8:11], v[148:151], v[188:191], v[8:11]
	v_mfma_f32_16x16x32_bf16 v[4:7], v[156:159], v[188:191], v[4:7]
	v_mfma_f32_16x16x32_bf16 v[56:59], v[152:155], v[168:171], v[56:59]
	v_mfma_f32_16x16x32_bf16 v[52:55], v[160:163], v[168:171], v[52:55]
	v_mfma_f32_16x16x32_bf16 v[40:43], v[152:155], v[176:179], v[40:43]
	v_mfma_f32_16x16x32_bf16 v[36:39], v[160:163], v[176:179], v[36:39]
	v_mfma_f32_16x16x32_bf16 v[24:27], v[152:155], v[184:187], v[24:27]
	v_mfma_f32_16x16x32_bf16 v[20:23], v[160:163], v[184:187], v[20:23]
	v_mfma_f32_16x16x32_bf16 v[8:11], v[152:155], v[192:195], v[8:11]
	v_mfma_f32_16x16x32_bf16 v[4:7], v[160:163], v[192:195], v[4:7]
	s_barrier
	s_setprio 0
	s_add_i32 s0, 0, 0x18000
	s_add_i32 s6, 0, 0x1c000
	v_add_u32_e32 v144, s0, v3
	v_add_u32_e32 v160, s6, v3
	ds_read_b128 v[124:127], v144
	ds_read_b128 v[128:131], v144 offset:1024
	ds_read_b128 v[140:143], v144 offset:2048
	ds_read_b128 v[144:147], v144 offset:3072
	ds_read_b128 v[148:151], v160
	ds_read_b128 v[152:155], v160 offset:1024
	ds_read_b128 v[156:159], v160 offset:2048
	ds_read_b128 v[160:163], v160 offset:3072
	s_add_u32 s34, s34, 0x80000
	s_addc_u32 s35, s35, 0
	s_mov_b32 m0, s25
	v_lshl_add_u64 v[222:223], s[34:35], 0, v[206:207]
	ds_read_b128 v[164:167], v250 offset:32768
	ds_read_b128 v[168:171], v250 offset:33792
	ds_read_b128 v[172:175], v250 offset:34816
	ds_read_b128 v[176:179], v250 offset:35840
	ds_read_b128 v[180:183], v250 offset:36864
	ds_read_b128 v[184:187], v250 offset:37888
	ds_read_b128 v[188:191], v250 offset:38912
	ds_read_b128 v[192:195], v250 offset:39936
	global_load_lds_dwordx4 v[222:223], off
	s_mov_b32 m0, s29
	v_lshl_add_u64 v[222:223], s[34:35], 0, v[202:203]
	global_load_lds_dwordx4 v[222:223], off
	s_setprio 1
	s_waitcnt vmcnt(8) lgkmcnt(0)
	s_barrier
	v_mfma_f32_16x16x32_bf16 v[136:139], v[124:127], v[164:167], v[136:139]
	v_mfma_f32_16x16x32_bf16 v[132:135], v[140:143], v[164:167], v[132:135]
	v_mfma_f32_16x16x32_bf16 v[112:115], v[124:127], v[172:175], v[112:115]
	v_mfma_f32_16x16x32_bf16 v[108:111], v[140:143], v[172:175], v[108:111]
	v_mfma_f32_16x16x32_bf16 v[96:99], v[124:127], v[180:183], v[96:99]
	v_mfma_f32_16x16x32_bf16 v[92:95], v[140:143], v[180:183], v[92:95]
	v_mfma_f32_16x16x32_bf16 v[80:83], v[124:127], v[188:191], v[80:83]
	v_mfma_f32_16x16x32_bf16 v[76:79], v[140:143], v[188:191], v[76:79]
	v_mfma_f32_16x16x32_bf16 v[136:139], v[128:131], v[168:171], v[136:139]
	v_mfma_f32_16x16x32_bf16 v[132:135], v[144:147], v[168:171], v[132:135]
	v_mfma_f32_16x16x32_bf16 v[112:115], v[128:131], v[176:179], v[112:115]
	v_mfma_f32_16x16x32_bf16 v[108:111], v[144:147], v[176:179], v[108:111]
	v_mfma_f32_16x16x32_bf16 v[96:99], v[128:131], v[184:187], v[96:99]
	v_mfma_f32_16x16x32_bf16 v[92:95], v[144:147], v[184:187], v[92:95]
	v_mfma_f32_16x16x32_bf16 v[80:83], v[128:131], v[192:195], v[80:83]
	v_mfma_f32_16x16x32_bf16 v[76:79], v[144:147], v[192:195], v[76:79]
	s_setprio 0
	s_setprio 1
	v_mfma_f32_16x16x32_bf16 v[120:123], v[148:151], v[164:167], v[120:123]
	v_mfma_f32_16x16x32_bf16 v[116:119], v[156:159], v[164:167], v[116:119]
	v_mfma_f32_16x16x32_bf16 v[104:107], v[148:151], v[172:175], v[104:107]
	v_mfma_f32_16x16x32_bf16 v[100:103], v[156:159], v[172:175], v[100:103]
	v_mfma_f32_16x16x32_bf16 v[88:91], v[148:151], v[180:183], v[88:91]
	v_mfma_f32_16x16x32_bf16 v[84:87], v[156:159], v[180:183], v[84:87]
	v_mfma_f32_16x16x32_bf16 v[72:75], v[148:151], v[188:191], v[72:75]
	v_mfma_f32_16x16x32_bf16 v[68:71], v[156:159], v[188:191], v[68:71]
	v_mfma_f32_16x16x32_bf16 v[120:123], v[152:155], v[168:171], v[120:123]
	v_mfma_f32_16x16x32_bf16 v[116:119], v[160:163], v[168:171], v[116:119]
	v_mfma_f32_16x16x32_bf16 v[104:107], v[152:155], v[176:179], v[104:107]
	v_mfma_f32_16x16x32_bf16 v[100:103], v[160:163], v[176:179], v[100:103]
	v_mfma_f32_16x16x32_bf16 v[88:91], v[152:155], v[184:187], v[88:91]
	v_mfma_f32_16x16x32_bf16 v[84:87], v[160:163], v[184:187], v[84:87]
	v_mfma_f32_16x16x32_bf16 v[72:75], v[152:155], v[192:195], v[72:75]
	v_mfma_f32_16x16x32_bf16 v[68:71], v[160:163], v[192:195], v[68:71]
	s_barrier
	s_setprio 0
	s_add_i32 s0, s0, s1
	v_lshl_add_u64 v[198:199], v[198:199], 0, s[90:91]
	s_mov_b32 m0, s0
	ds_read_b128 v[164:167], v250 offset:49152
	ds_read_b128 v[168:171], v250 offset:50176
	ds_read_b128 v[172:175], v250 offset:51200
	ds_read_b128 v[176:179], v250 offset:52224
	ds_read_b128 v[180:183], v250 offset:53248
	ds_read_b128 v[184:187], v250 offset:54272
	ds_read_b128 v[188:191], v250 offset:55296
	ds_read_b128 v[192:195], v250 offset:56320
	global_load_lds_dwordx4 v[198:199], off
	s_add_i32 m0, s0, 0x2000
	s_add_u32 s30, s30, 0x80080
	v_lshl_add_u64 v[198:199], v[216:217], 0, s[90:91]
	s_addc_u32 s31, s31, 0
	s_add_i32 s0, s6, s1
	global_load_lds_dwordx4 v[198:199], off
	s_mov_b32 m0, s0
	v_lshl_add_u64 v[198:199], s[30:31], 0, v[204:205]
	global_load_lds_dwordx4 v[198:199], off
	s_add_i32 m0, s0, 0x2000
	v_lshl_add_u64 v[198:199], s[30:31], 0, v[200:201]
	global_load_lds_dwordx4 v[198:199], off
	s_mov_b32 m0, s33
	v_lshl_add_u64 v[198:199], v[218:219], 0, s[90:91]
	global_load_lds_dwordx4 v[198:199], off
	s_mov_b32 m0, s40
	v_lshl_add_u64 v[198:199], v[220:221], 0, s[90:91]
	global_load_lds_dwordx4 v[198:199], off
	s_setprio 1
	s_waitcnt vmcnt(8) lgkmcnt(0)
	s_barrier
	v_mfma_f32_16x16x32_bf16 v[64:67], v[124:127], v[164:167], v[64:67]
	v_mfma_f32_16x16x32_bf16 v[60:63], v[140:143], v[164:167], v[60:63]
	v_mfma_f32_16x16x32_bf16 v[48:51], v[124:127], v[172:175], v[48:51]
	v_mfma_f32_16x16x32_bf16 v[44:47], v[140:143], v[172:175], v[44:47]
	v_mfma_f32_16x16x32_bf16 v[32:35], v[124:127], v[180:183], v[32:35]
	v_mfma_f32_16x16x32_bf16 v[28:31], v[140:143], v[180:183], v[28:31]
	v_mfma_f32_16x16x32_bf16 v[16:19], v[124:127], v[188:191], v[16:19]
	v_mfma_f32_16x16x32_bf16 v[12:15], v[140:143], v[188:191], v[12:15]
	v_mfma_f32_16x16x32_bf16 v[64:67], v[128:131], v[168:171], v[64:67]
	v_mfma_f32_16x16x32_bf16 v[60:63], v[144:147], v[168:171], v[60:63]
	v_mfma_f32_16x16x32_bf16 v[48:51], v[128:131], v[176:179], v[48:51]
	v_mfma_f32_16x16x32_bf16 v[44:47], v[144:147], v[176:179], v[44:47]
	v_mfma_f32_16x16x32_bf16 v[32:35], v[128:131], v[184:187], v[32:35]
	v_mfma_f32_16x16x32_bf16 v[28:31], v[144:147], v[184:187], v[28:31]
	v_mfma_f32_16x16x32_bf16 v[16:19], v[128:131], v[192:195], v[16:19]
	v_mfma_f32_16x16x32_bf16 v[12:15], v[144:147], v[192:195], v[12:15]
	s_setprio 0
	s_setprio 1
	v_mfma_f32_16x16x32_bf16 v[56:59], v[148:151], v[164:167], v[56:59]
	v_mfma_f32_16x16x32_bf16 v[52:55], v[156:159], v[164:167], v[52:55]
	v_mfma_f32_16x16x32_bf16 v[40:43], v[148:151], v[172:175], v[40:43]
	v_mfma_f32_16x16x32_bf16 v[36:39], v[156:159], v[172:175], v[36:39]
	v_mfma_f32_16x16x32_bf16 v[24:27], v[148:151], v[180:183], v[24:27]
	v_mfma_f32_16x16x32_bf16 v[20:23], v[156:159], v[180:183], v[20:23]
	v_mfma_f32_16x16x32_bf16 v[8:11], v[148:151], v[188:191], v[8:11]
	v_mfma_f32_16x16x32_bf16 v[4:7], v[156:159], v[188:191], v[4:7]
	v_mfma_f32_16x16x32_bf16 v[56:59], v[152:155], v[168:171], v[56:59]
	v_mfma_f32_16x16x32_bf16 v[52:55], v[160:163], v[168:171], v[52:55]
	v_mfma_f32_16x16x32_bf16 v[40:43], v[152:155], v[176:179], v[40:43]
	v_mfma_f32_16x16x32_bf16 v[36:39], v[160:163], v[176:179], v[36:39]
	v_mfma_f32_16x16x32_bf16 v[24:27], v[152:155], v[184:187], v[24:27]
	v_mfma_f32_16x16x32_bf16 v[20:23], v[160:163], v[184:187], v[20:23]
	v_mfma_f32_16x16x32_bf16 v[8:11], v[152:155], v[192:195], v[8:11]
	v_mfma_f32_16x16x32_bf16 v[4:7], v[160:163], v[192:195], v[4:7]
	s_barrier
	s_setprio 0
	s_add_i32 s55, s55, 2
	s_add_u32 s36, s36, 0x100
	s_addc_u32 s37, s37, 0
	s_add_u32 s38, s38, 0x100
	s_addc_u32 s39, s39, 0
	s_cmp_gt_u32 s55, 29
	s_cbranch_scc0 .LBB0_967
	s_and_b64 vcc, exec, s[44:45]
	s_cbranch_vccz .LBB0_970
	s_barrier

.LBB0_1017:
	s_add_u32 s0, s68, s30
	s_addc_u32 s6, s69, 0
	s_add_u32 s31, s0, 0x100
	s_addc_u32 s38, s6, 0
	s_and_b64 s[34:35], s[36:37], exec
	s_cselect_b32 vcc_hi, s65, s38
	s_cselect_b32 vcc_lo, s64, s31
	s_add_u32 s30, s74, s30
	s_addc_u32 s31, s75, 0
	s_add_u32 s34, s30, 0x100
	s_addc_u32 s35, s31, 0
	s_add_i32 s78, 0, 0x10000
	s_and_b64 s[30:31], s[36:37], exec
	s_cselect_b32 s53, s67, s35
	s_cselect_b32 s52, s66, s34
	s_add_i32 s37, 0, 0x14000
	s_add_u32 s34, s0, 0x80080
	s_addc_u32 s35, s6, 0
	s_add_i32 s73, s78, s1
	s_add_i32 m0, s4, 0xc000
	s_add_i32 s83, s4, 0xe000
	s_add_i32 s6, s73, 0x2000
	s_add_u32 s30, s52, 0x80000
	v_add_u32_e32 v144, s78, v3
	v_add_u32_e32 v160, s37, v3
	s_addc_u32 s31, s53, 0
	s_add_i32 s49, s37, s1
	ds_read_b128 v[132:135], v144
	ds_read_b128 v[136:139], v144 offset:1024
	ds_read_b128 v[140:143], v144 offset:2048
	ds_read_b128 v[144:147], v144 offset:3072
	ds_read_b128 v[148:151], v160
	ds_read_b128 v[152:155], v160 offset:1024
	ds_read_b128 v[156:159], v160 offset:2048
	ds_read_b128 v[160:163], v160 offset:3072
	s_add_i32 s63, s49, 0x2000
	s_add_i32 s54, 0, 0x18000
	s_add_i32 s61, 0, 0x1c000
	s_add_u32 s38, vcc_lo, 0x80000
	s_addc_u32 s39, vcc_hi, 0
	s_add_i32 s0, s54, s1
	s_add_i32 s45, s0, 0x2000
	s_add_u32 s36, s52, 0x80080
	s_addc_u32 s37, s53, 0
	s_add_i32 s82, s61, s1
	s_add_i32 s78, s82, 0x2000
	v_lshl_add_u64 v[198:199], s[34:35], 0, v[206:207]
	ds_read_b128 v[164:167], v236
	ds_read_b128 v[168:171], v236 offset:1024
	ds_read_b128 v[172:175], v236 offset:2048
	ds_read_b128 v[176:179], v236 offset:3072
	ds_read_b128 v[180:183], v236 offset:4096
	ds_read_b128 v[184:187], v236 offset:5120
	ds_read_b128 v[188:191], v236 offset:6144
	ds_read_b128 v[192:195], v236 offset:7168
	global_load_lds_dwordx4 v[198:199], off
	s_mov_b32 m0, s83
	v_lshl_add_u64 v[198:199], s[34:35], 0, v[202:203]
	global_load_lds_dwordx4 v[198:199], off
	s_setprio 1
	s_waitcnt vmcnt(8) lgkmcnt(0)
	s_barrier
	v_mfma_f32_16x16x32_bf16 v[128:131], v[132:135], v[164:167], v[128:131]
	v_mfma_f32_16x16x32_bf16 v[124:127], v[140:143], v[164:167], v[124:127]
	v_mfma_f32_16x16x32_bf16 v[112:115], v[132:135], v[172:175], v[112:115]
	v_mfma_f32_16x16x32_bf16 v[108:111], v[140:143], v[172:175], v[108:111]
	v_mfma_f32_16x16x32_bf16 v[96:99], v[132:135], v[180:183], v[96:99]
	v_mfma_f32_16x16x32_bf16 v[92:95], v[140:143], v[180:183], v[92:95]
	v_mfma_f32_16x16x32_bf16 v[80:83], v[132:135], v[188:191], v[80:83]
	v_mfma_f32_16x16x32_bf16 v[76:79], v[140:143], v[188:191], v[76:79]
	v_mfma_f32_16x16x32_bf16 v[128:131], v[136:139], v[168:171], v[128:131]
	v_mfma_f32_16x16x32_bf16 v[124:127], v[144:147], v[168:171], v[124:127]
	v_mfma_f32_16x16x32_bf16 v[112:115], v[136:139], v[176:179], v[112:115]
	v_mfma_f32_16x16x32_bf16 v[108:111], v[144:147], v[176:179], v[108:111]
	v_mfma_f32_16x16x32_bf16 v[96:99], v[136:139], v[184:187], v[96:99]
	v_mfma_f32_16x16x32_bf16 v[92:95], v[144:147], v[184:187], v[92:95]
	v_mfma_f32_16x16x32_bf16 v[80:83], v[136:139], v[192:195], v[80:83]
	v_mfma_f32_16x16x32_bf16 v[76:79], v[144:147], v[192:195], v[76:79]
	s_setprio 0
	s_setprio 1
	v_mfma_f32_16x16x32_bf16 v[120:123], v[148:151], v[164:167], v[120:123]
	v_mfma_f32_16x16x32_bf16 v[116:119], v[156:159], v[164:167], v[116:119]
	v_mfma_f32_16x16x32_bf16 v[104:107], v[148:151], v[172:175], v[104:107]
	v_mfma_f32_16x16x32_bf16 v[100:103], v[156:159], v[172:175], v[100:103]
	v_mfma_f32_16x16x32_bf16 v[88:91], v[148:151], v[180:183], v[88:91]
	v_mfma_f32_16x16x32_bf16 v[84:87], v[156:159], v[180:183], v[84:87]
	v_mfma_f32_16x16x32_bf16 v[72:75], v[148:151], v[188:191], v[72:75]
	v_mfma_f32_16x16x32_bf16 v[68:71], v[156:159], v[188:191], v[68:71]
	v_mfma_f32_16x16x32_bf16 v[120:123], v[152:155], v[168:171], v[120:123]
	v_mfma_f32_16x16x32_bf16 v[116:119], v[160:163], v[168:171], v[116:119]
	v_mfma_f32_16x16x32_bf16 v[104:107], v[152:155], v[176:179], v[104:107]
	v_mfma_f32_16x16x32_bf16 v[100:103], v[160:163], v[176:179], v[100:103]
	v_mfma_f32_16x16x32_bf16 v[88:91], v[152:155], v[184:187], v[88:91]
	v_mfma_f32_16x16x32_bf16 v[84:87], v[160:163], v[184:187], v[84:87]
	v_mfma_f32_16x16x32_bf16 v[72:75], v[152:155], v[192:195], v[72:75]
	v_mfma_f32_16x16x32_bf16 v[68:71], v[160:163], v[192:195], v[68:71]
	s_barrier
	s_setprio 0
	s_mov_b32 m0, s73
	v_lshl_add_u64 v[198:199], s[52:53], 0, v[204:205]
	ds_read_b128 v[164:167], v236 offset:16384
	ds_read_b128 v[168:171], v236 offset:17408
	ds_read_b128 v[172:175], v236 offset:18432
	ds_read_b128 v[176:179], v236 offset:19456
	ds_read_b128 v[180:183], v236 offset:20480
	ds_read_b128 v[184:187], v236 offset:21504
	ds_read_b128 v[188:191], v236 offset:22528
	ds_read_b128 v[192:195], v236 offset:23552
	global_load_lds_dwordx4 v[198:199], off
	v_lshl_add_u64 v[212:213], s[52:53], 0, v[200:201]
	s_mov_b32 m0, s6
	v_lshl_add_u64 v[214:215], s[30:31], 0, v[204:205]
	global_load_lds_dwordx4 v[212:213], off
	s_mov_b32 m0, s49
	global_load_lds_dwordx4 v[214:215], off
	s_mov_b32 m0, s63
	v_lshl_add_u64 v[214:215], s[30:31], 0, v[200:201]
	global_load_lds_dwordx4 v[214:215], off
	s_mov_b32 m0, s4
	v_lshl_add_u64 v[214:215], vcc, 0, v[206:207]
	global_load_lds_dwordx4 v[214:215], off
	s_mov_b32 m0, s24
	v_lshl_add_u64 v[216:217], vcc, 0, v[202:203]
	global_load_lds_dwordx4 v[216:217], off
	s_setprio 1
	s_waitcnt vmcnt(8) lgkmcnt(0)
	s_barrier
	v_mfma_f32_16x16x32_bf16 v[64:67], v[132:135], v[164:167], v[64:67]
	v_mfma_f32_16x16x32_bf16 v[60:63], v[140:143], v[164:167], v[60:63]
	v_mfma_f32_16x16x32_bf16 v[48:51], v[132:135], v[172:175], v[48:51]
	v_mfma_f32_16x16x32_bf16 v[44:47], v[140:143], v[172:175], v[44:47]
	v_mfma_f32_16x16x32_bf16 v[32:35], v[132:135], v[180:183], v[32:35]
	v_mfma_f32_16x16x32_bf16 v[28:31], v[140:143], v[180:183], v[28:31]
	v_mfma_f32_16x16x32_bf16 v[16:19], v[132:135], v[188:191], v[16:19]
	v_mfma_f32_16x16x32_bf16 v[12:15], v[140:143], v[188:191], v[12:15]
	v_mfma_f32_16x16x32_bf16 v[64:67], v[136:139], v[168:171], v[64:67]
	v_mfma_f32_16x16x32_bf16 v[60:63], v[144:147], v[168:171], v[60:63]
	v_mfma_f32_16x16x32_bf16 v[48:51], v[136:139], v[176:179], v[48:51]
	v_mfma_f32_16x16x32_bf16 v[44:47], v[144:147], v[176:179], v[44:47]
	v_mfma_f32_16x16x32_bf16 v[32:35], v[136:139], v[184:187], v[32:35]
	v_mfma_f32_16x16x32_bf16 v[28:31], v[144:147], v[184:187], v[28:31]
	v_mfma_f32_16x16x32_bf16 v[16:19], v[136:139], v[192:195], v[16:19]
	v_mfma_f32_16x16x32_bf16 v[12:15], v[144:147], v[192:195], v[12:15]
	s_setprio 0
	s_setprio 1
	v_mfma_f32_16x16x32_bf16 v[56:59], v[148:151], v[164:167], v[56:59]
	v_mfma_f32_16x16x32_bf16 v[52:55], v[156:159], v[164:167], v[52:55]
	v_mfma_f32_16x16x32_bf16 v[40:43], v[148:151], v[172:175], v[40:43]
	v_mfma_f32_16x16x32_bf16 v[36:39], v[156:159], v[172:175], v[36:39]
	v_mfma_f32_16x16x32_bf16 v[24:27], v[148:151], v[180:183], v[24:27]
	v_mfma_f32_16x16x32_bf16 v[20:23], v[156:159], v[180:183], v[20:23]
	v_mfma_f32_16x16x32_bf16 v[8:11], v[148:151], v[188:191], v[8:11]
	v_mfma_f32_16x16x32_bf16 v[4:7], v[156:159], v[188:191], v[4:7]
	v_mfma_f32_16x16x32_bf16 v[56:59], v[152:155], v[168:171], v[56:59]
	v_mfma_f32_16x16x32_bf16 v[52:55], v[160:163], v[168:171], v[52:55]
	v_mfma_f32_16x16x32_bf16 v[40:43], v[152:155], v[176:179], v[40:43]
	v_mfma_f32_16x16x32_bf16 v[36:39], v[160:163], v[176:179], v[36:39]
	v_mfma_f32_16x16x32_bf16 v[24:27], v[152:155], v[184:187], v[24:27]
	v_mfma_f32_16x16x32_bf16 v[20:23], v[160:163], v[184:187], v[20:23]
	v_mfma_f32_16x16x32_bf16 v[8:11], v[152:155], v[192:195], v[8:11]
	v_mfma_f32_16x16x32_bf16 v[4:7], v[160:163], v[192:195], v[4:7]
	s_barrier
	s_setprio 0
	v_add_u32_e32 v144, s54, v3
	v_add_u32_e32 v160, s61, v3
	ds_read_b128 v[132:135], v144
	ds_read_b128 v[136:139], v144 offset:1024
	ds_read_b128 v[140:143], v144 offset:2048
	ds_read_b128 v[144:147], v144 offset:3072
	ds_read_b128 v[148:151], v160
	ds_read_b128 v[152:155], v160 offset:1024
	ds_read_b128 v[156:159], v160 offset:2048
	ds_read_b128 v[160:163], v160 offset:3072
	s_mov_b32 m0, s25
	v_lshl_add_u64 v[218:219], s[38:39], 0, v[206:207]
	ds_read_b128 v[164:167], v236 offset:32768
	ds_read_b128 v[168:171], v236 offset:33792
	ds_read_b128 v[172:175], v236 offset:34816
	ds_read_b128 v[176:179], v236 offset:35840
	ds_read_b128 v[180:183], v236 offset:36864
	ds_read_b128 v[184:187], v236 offset:37888
	ds_read_b128 v[188:191], v236 offset:38912
	ds_read_b128 v[192:195], v236 offset:39936
	global_load_lds_dwordx4 v[218:219], off
	s_mov_b32 m0, s33
	v_lshl_add_u64 v[218:219], s[38:39], 0, v[202:203]
	global_load_lds_dwordx4 v[218:219], off
	s_setprio 1
	s_waitcnt vmcnt(8) lgkmcnt(0)
	s_barrier
	v_mfma_f32_16x16x32_bf16 v[128:131], v[132:135], v[164:167], v[128:131]
	v_mfma_f32_16x16x32_bf16 v[124:127], v[140:143], v[164:167], v[124:127]
	v_mfma_f32_16x16x32_bf16 v[112:115], v[132:135], v[172:175], v[112:115]
	v_mfma_f32_16x16x32_bf16 v[108:111], v[140:143], v[172:175], v[108:111]
	v_mfma_f32_16x16x32_bf16 v[96:99], v[132:135], v[180:183], v[96:99]
	v_mfma_f32_16x16x32_bf16 v[92:95], v[140:143], v[180:183], v[92:95]
	v_mfma_f32_16x16x32_bf16 v[80:83], v[132:135], v[188:191], v[80:83]
	v_mfma_f32_16x16x32_bf16 v[76:79], v[140:143], v[188:191], v[76:79]
	v_mfma_f32_16x16x32_bf16 v[128:131], v[136:139], v[168:171], v[128:131]
	v_mfma_f32_16x16x32_bf16 v[124:127], v[144:147], v[168:171], v[124:127]
	v_mfma_f32_16x16x32_bf16 v[112:115], v[136:139], v[176:179], v[112:115]
	v_mfma_f32_16x16x32_bf16 v[108:111], v[144:147], v[176:179], v[108:111]
	v_mfma_f32_16x16x32_bf16 v[96:99], v[136:139], v[184:187], v[96:99]
	v_mfma_f32_16x16x32_bf16 v[92:95], v[144:147], v[184:187], v[92:95]
	v_mfma_f32_16x16x32_bf16 v[80:83], v[136:139], v[192:195], v[80:83]
	v_mfma_f32_16x16x32_bf16 v[76:79], v[144:147], v[192:195], v[76:79]
	s_setprio 0
	s_setprio 1
	v_mfma_f32_16x16x32_bf16 v[120:123], v[148:151], v[164:167], v[120:123]
	v_mfma_f32_16x16x32_bf16 v[116:119], v[156:159], v[164:167], v[116:119]
	v_mfma_f32_16x16x32_bf16 v[104:107], v[148:151], v[172:175], v[104:107]
	v_mfma_f32_16x16x32_bf16 v[100:103], v[156:159], v[172:175], v[100:103]
	v_mfma_f32_16x16x32_bf16 v[88:91], v[148:151], v[180:183], v[88:91]
	v_mfma_f32_16x16x32_bf16 v[84:87], v[156:159], v[180:183], v[84:87]
	v_mfma_f32_16x16x32_bf16 v[72:75], v[148:151], v[188:191], v[72:75]
	v_mfma_f32_16x16x32_bf16 v[68:71], v[156:159], v[188:191], v[68:71]
	v_mfma_f32_16x16x32_bf16 v[120:123], v[152:155], v[168:171], v[120:123]
	v_mfma_f32_16x16x32_bf16 v[116:119], v[160:163], v[168:171], v[116:119]
	v_mfma_f32_16x16x32_bf16 v[104:107], v[152:155], v[176:179], v[104:107]
	v_mfma_f32_16x16x32_bf16 v[100:103], v[160:163], v[176:179], v[100:103]
	v_mfma_f32_16x16x32_bf16 v[88:91], v[152:155], v[184:187], v[88:91]
	v_mfma_f32_16x16x32_bf16 v[84:87], v[160:163], v[184:187], v[84:87]
	v_mfma_f32_16x16x32_bf16 v[72:75], v[152:155], v[192:195], v[72:75]
	v_mfma_f32_16x16x32_bf16 v[68:71], v[160:163], v[192:195], v[68:71]
	s_barrier
	s_setprio 0
	s_mov_b32 m0, s0
	v_lshl_add_u64 v[198:199], v[198:199], 0, s[90:91]
	ds_read_b128 v[164:167], v236 offset:49152
	ds_read_b128 v[168:171], v236 offset:50176
	ds_read_b128 v[172:175], v236 offset:51200
	ds_read_b128 v[176:179], v236 offset:52224
	ds_read_b128 v[180:183], v236 offset:53248
	ds_read_b128 v[184:187], v236 offset:54272
	ds_read_b128 v[188:191], v236 offset:55296
	ds_read_b128 v[192:195], v236 offset:56320
	global_load_lds_dwordx4 v[198:199], off
	s_mov_b32 m0, s45
	v_lshl_add_u64 v[198:199], v[212:213], 0, s[90:91]
	global_load_lds_dwordx4 v[198:199], off
	s_mov_b32 m0, s82
	v_lshl_add_u64 v[198:199], s[36:37], 0, v[204:205]
	global_load_lds_dwordx4 v[198:199], off
	s_mov_b32 m0, s78
	v_lshl_add_u64 v[198:199], s[36:37], 0, v[200:201]
	global_load_lds_dwordx4 v[198:199], off
	s_mov_b32 m0, s40
	v_lshl_add_u64 v[198:199], v[214:215], 0, s[90:91]
	global_load_lds_dwordx4 v[198:199], off
	s_mov_b32 m0, s50
	v_lshl_add_u64 v[198:199], v[216:217], 0, s[90:91]
	global_load_lds_dwordx4 v[198:199], off
	s_setprio 1
	s_waitcnt vmcnt(8) lgkmcnt(0)
	s_barrier
	v_mfma_f32_16x16x32_bf16 v[64:67], v[132:135], v[164:167], v[64:67]
	v_mfma_f32_16x16x32_bf16 v[60:63], v[140:143], v[164:167], v[60:63]
	v_mfma_f32_16x16x32_bf16 v[48:51], v[132:135], v[172:175], v[48:51]
	v_mfma_f32_16x16x32_bf16 v[44:47], v[140:143], v[172:175], v[44:47]
	v_mfma_f32_16x16x32_bf16 v[32:35], v[132:135], v[180:183], v[32:35]
	v_mfma_f32_16x16x32_bf16 v[28:31], v[140:143], v[180:183], v[28:31]
	v_mfma_f32_16x16x32_bf16 v[16:19], v[132:135], v[188:191], v[16:19]
	v_mfma_f32_16x16x32_bf16 v[12:15], v[140:143], v[188:191], v[12:15]
	v_mfma_f32_16x16x32_bf16 v[64:67], v[136:139], v[168:171], v[64:67]
	v_mfma_f32_16x16x32_bf16 v[60:63], v[144:147], v[168:171], v[60:63]
	v_mfma_f32_16x16x32_bf16 v[48:51], v[136:139], v[176:179], v[48:51]
	v_mfma_f32_16x16x32_bf16 v[44:47], v[144:147], v[176:179], v[44:47]
	v_mfma_f32_16x16x32_bf16 v[32:35], v[136:139], v[184:187], v[32:35]
	v_mfma_f32_16x16x32_bf16 v[28:31], v[144:147], v[184:187], v[28:31]
	v_mfma_f32_16x16x32_bf16 v[16:19], v[136:139], v[192:195], v[16:19]
	v_mfma_f32_16x16x32_bf16 v[12:15], v[144:147], v[192:195], v[12:15]
	s_setprio 0
	s_setprio 1
	v_mfma_f32_16x16x32_bf16 v[56:59], v[148:151], v[164:167], v[56:59]
	v_mfma_f32_16x16x32_bf16 v[52:55], v[156:159], v[164:167], v[52:55]
	v_mfma_f32_16x16x32_bf16 v[40:43], v[148:151], v[172:175], v[40:43]
	v_mfma_f32_16x16x32_bf16 v[36:39], v[156:159], v[172:175], v[36:39]
	v_mfma_f32_16x16x32_bf16 v[24:27], v[148:151], v[180:183], v[24:27]
	v_mfma_f32_16x16x32_bf16 v[20:23], v[156:159], v[180:183], v[20:23]
	v_mfma_f32_16x16x32_bf16 v[8:11], v[148:151], v[188:191], v[8:11]
	v_mfma_f32_16x16x32_bf16 v[4:7], v[156:159], v[188:191], v[4:7]
	v_mfma_f32_16x16x32_bf16 v[56:59], v[152:155], v[168:171], v[56:59]
	v_mfma_f32_16x16x32_bf16 v[52:55], v[160:163], v[168:171], v[52:55]
	v_mfma_f32_16x16x32_bf16 v[40:43], v[152:155], v[176:179], v[40:43]
	v_mfma_f32_16x16x32_bf16 v[36:39], v[160:163], v[176:179], v[36:39]
	v_mfma_f32_16x16x32_bf16 v[24:27], v[152:155], v[184:187], v[24:27]
	v_mfma_f32_16x16x32_bf16 v[20:23], v[160:163], v[184:187], v[20:23]
	v_mfma_f32_16x16x32_bf16 v[8:11], v[152:155], v[192:195], v[8:11]
	v_mfma_f32_16x16x32_bf16 v[4:7], v[160:163], v[192:195], v[4:7]
	s_barrier
	s_setprio 0
	s_movk_i32 s30, 0x100
	s_andn2_b64 vcc, exec, s[80:81]
	s_mov_b64 s[36:37], -1
	s_mov_b64 s[80:81], 0
	s_cbranch_vccz .LBB0_1017
	s_and_b64 vcc, exec, s[42:43]
	s_cbranch_vccz .LBB0_1020
	s_barrier

.LBB0_1137:
	s_add_u32 s0, s36, 0xfff80080
	s_addc_u32 s6, s37, -1
	s_add_i32 s49, 0, 0x10000
	s_cmp_eq_u32 s66, 28
	s_cselect_b32 s35, s29, s6
	s_cselect_b32 s34, s64, s0
	v_add_u32_e32 v156, s49, v157
	s_cselect_b32 s31, s23, s39
	s_cselect_b32 s30, s65, s38
	s_add_i32 s0, 0, 0x14000
	ds_read_b128 v[144:147], v156
	ds_read_b128 v[148:151], v156 offset:1024
	ds_read_b128 v[152:155], v156 offset:2048
	ds_read_b128 v[162:165], v156 offset:3072
	v_add_u32_e32 v156, s0, v157
	ds_read_b128 v[166:169], v156
	ds_read_b128 v[170:173], v156 offset:1024
	ds_read_b128 v[174:177], v156 offset:2048
	ds_read_b128 v[178:181], v156 offset:3072
	v_lshl_add_u64 v[194:195], s[36:37], 0, v[140:141]
	s_add_i32 m0, s33, 0xc000
	ds_read_b128 v[182:185], v161
	ds_read_b128 v[186:189], v161 offset:1024
	ds_read_b128 v[190:193], v161 offset:2048
	ds_read_b128 v[200:203], v161 offset:3072
	ds_read_b128 v[204:207], v161 offset:4096
	ds_read_b128 v[208:211], v161 offset:5120
	ds_read_b128 v[212:215], v161 offset:6144
	ds_read_b128 v[216:219], v161 offset:7168
	global_load_lds_dwordx4 v[194:195], off
	s_add_i32 m0, s33, 0xe000
	v_lshl_add_u64 v[194:195], s[36:37], 0, v[142:143]
	global_load_lds_dwordx4 v[194:195], off
	s_setprio 1
	s_waitcnt vmcnt(8) lgkmcnt(0)
	s_barrier
	v_mfma_f32_16x16x32_bf16 v[128:131], v[144:147], v[182:185], v[128:131]
	v_mfma_f32_16x16x32_bf16 v[124:127], v[152:155], v[182:185], v[124:127]
	v_mfma_f32_16x16x32_bf16 v[112:115], v[144:147], v[190:193], v[112:115]
	v_mfma_f32_16x16x32_bf16 v[108:111], v[152:155], v[190:193], v[108:111]
	v_mfma_f32_16x16x32_bf16 v[96:99], v[144:147], v[204:207], v[96:99]
	v_mfma_f32_16x16x32_bf16 v[92:95], v[152:155], v[204:207], v[92:95]
	v_mfma_f32_16x16x32_bf16 v[80:83], v[144:147], v[212:215], v[80:83]
	v_mfma_f32_16x16x32_bf16 v[76:79], v[152:155], v[212:215], v[76:79]
	v_mfma_f32_16x16x32_bf16 v[128:131], v[148:151], v[186:189], v[128:131]
	v_mfma_f32_16x16x32_bf16 v[124:127], v[162:165], v[186:189], v[124:127]
	v_mfma_f32_16x16x32_bf16 v[112:115], v[148:151], v[200:203], v[112:115]
	v_mfma_f32_16x16x32_bf16 v[108:111], v[162:165], v[200:203], v[108:111]
	v_mfma_f32_16x16x32_bf16 v[96:99], v[148:151], v[208:211], v[96:99]
	v_mfma_f32_16x16x32_bf16 v[92:95], v[162:165], v[208:211], v[92:95]
	v_mfma_f32_16x16x32_bf16 v[80:83], v[148:151], v[216:219], v[80:83]
	v_mfma_f32_16x16x32_bf16 v[76:79], v[162:165], v[216:219], v[76:79]
	s_setprio 0
	s_setprio 1
	v_mfma_f32_16x16x32_bf16 v[120:123], v[166:169], v[182:185], v[120:123]
	v_mfma_f32_16x16x32_bf16 v[116:119], v[174:177], v[182:185], v[116:119]
	v_mfma_f32_16x16x32_bf16 v[104:107], v[166:169], v[190:193], v[104:107]
	v_mfma_f32_16x16x32_bf16 v[100:103], v[174:177], v[190:193], v[100:103]
	v_mfma_f32_16x16x32_bf16 v[88:91], v[166:169], v[204:207], v[88:91]
	v_mfma_f32_16x16x32_bf16 v[84:87], v[174:177], v[204:207], v[84:87]
	v_mfma_f32_16x16x32_bf16 v[72:75], v[166:169], v[212:215], v[72:75]
	v_mfma_f32_16x16x32_bf16 v[68:71], v[174:177], v[212:215], v[68:71]
	v_mfma_f32_16x16x32_bf16 v[120:123], v[170:173], v[186:189], v[120:123]
	v_mfma_f32_16x16x32_bf16 v[116:119], v[178:181], v[186:189], v[116:119]
	v_mfma_f32_16x16x32_bf16 v[104:107], v[170:173], v[200:203], v[104:107]
	v_mfma_f32_16x16x32_bf16 v[100:103], v[178:181], v[200:203], v[100:103]
	v_mfma_f32_16x16x32_bf16 v[88:91], v[170:173], v[208:211], v[88:91]
	v_mfma_f32_16x16x32_bf16 v[84:87], v[178:181], v[208:211], v[84:87]
	v_mfma_f32_16x16x32_bf16 v[72:75], v[170:173], v[216:219], v[72:75]
	v_mfma_f32_16x16x32_bf16 v[68:71], v[178:181], v[216:219], v[68:71]
	s_barrier
	s_setprio 0
	s_add_i32 s6, s49, s25
	v_lshl_add_u64 v[194:195], s[30:31], 0, v[136:137]
	s_mov_b32 m0, s6
	ds_read_b128 v[182:185], v161 offset:16384
	ds_read_b128 v[186:189], v161 offset:17408
	ds_read_b128 v[190:193], v161 offset:18432
	ds_read_b128 v[200:203], v161 offset:19456
	ds_read_b128 v[204:207], v161 offset:20480
	ds_read_b128 v[208:211], v161 offset:21504
	ds_read_b128 v[212:215], v161 offset:22528
	ds_read_b128 v[216:219], v161 offset:23552
	global_load_lds_dwordx4 v[194:195], off
	s_add_i32 m0, s6, 0x2000
	s_add_u32 s68, s30, 0x80000
	v_lshl_add_u64 v[198:199], s[30:31], 0, v[132:133]
	s_addc_u32 s69, s31, 0
	s_add_i32 s0, s0, s25
	global_load_lds_dwordx4 v[198:199], off
	v_lshl_add_u64 v[220:221], s[68:69], 0, v[136:137]
	s_mov_b32 m0, s0
	global_load_lds_dwordx4 v[220:221], off
	s_add_i32 m0, s0, 0x2000
	v_lshl_add_u64 v[220:221], s[68:69], 0, v[132:133]
	global_load_lds_dwordx4 v[220:221], off
	s_mov_b32 m0, s33
	v_lshl_add_u64 v[220:221], s[34:35], 0, v[138:139]
	global_load_lds_dwordx4 v[220:221], off
	s_mov_b32 m0, s40
	v_lshl_add_u64 v[222:223], s[34:35], 0, v[134:135]
	global_load_lds_dwordx4 v[222:223], off
	s_setprio 1
	s_waitcnt vmcnt(8) lgkmcnt(0)
	s_barrier
	v_mfma_f32_16x16x32_bf16 v[64:67], v[144:147], v[182:185], v[64:67]
	v_mfma_f32_16x16x32_bf16 v[60:63], v[152:155], v[182:185], v[60:63]
	v_mfma_f32_16x16x32_bf16 v[48:51], v[144:147], v[190:193], v[48:51]
	v_mfma_f32_16x16x32_bf16 v[44:47], v[152:155], v[190:193], v[44:47]
	v_mfma_f32_16x16x32_bf16 v[32:35], v[144:147], v[204:207], v[32:35]
	v_mfma_f32_16x16x32_bf16 v[28:31], v[152:155], v[204:207], v[28:31]
	v_mfma_f32_16x16x32_bf16 v[16:19], v[144:147], v[212:215], v[16:19]
	v_mfma_f32_16x16x32_bf16 v[12:15], v[152:155], v[212:215], v[12:15]
	v_mfma_f32_16x16x32_bf16 v[64:67], v[148:151], v[186:189], v[64:67]
	v_mfma_f32_16x16x32_bf16 v[60:63], v[162:165], v[186:189], v[60:63]
	v_mfma_f32_16x16x32_bf16 v[48:51], v[148:151], v[200:203], v[48:51]
	v_mfma_f32_16x16x32_bf16 v[44:47], v[162:165], v[200:203], v[44:47]
	v_mfma_f32_16x16x32_bf16 v[32:35], v[148:151], v[208:211], v[32:35]
	v_mfma_f32_16x16x32_bf16 v[28:31], v[162:165], v[208:211], v[28:31]
	v_mfma_f32_16x16x32_bf16 v[16:19], v[148:151], v[216:219], v[16:19]
	v_mfma_f32_16x16x32_bf16 v[12:15], v[162:165], v[216:219], v[12:15]
	s_setprio 0
	s_setprio 1
	v_mfma_f32_16x16x32_bf16 v[56:59], v[166:169], v[182:185], v[56:59]
	v_mfma_f32_16x16x32_bf16 v[52:55], v[174:177], v[182:185], v[52:55]
	v_mfma_f32_16x16x32_bf16 v[40:43], v[166:169], v[190:193], v[40:43]
	v_mfma_f32_16x16x32_bf16 v[36:39], v[174:177], v[190:193], v[36:39]
	v_mfma_f32_16x16x32_bf16 v[24:27], v[166:169], v[204:207], v[24:27]
	v_mfma_f32_16x16x32_bf16 v[20:23], v[174:177], v[204:207], v[20:23]
	v_mfma_f32_16x16x32_bf16 v[8:11], v[166:169], v[212:215], v[8:11]
	v_mfma_f32_16x16x32_bf16 v[4:7], v[174:177], v[212:215], v[4:7]
	v_mfma_f32_16x16x32_bf16 v[56:59], v[170:173], v[186:189], v[56:59]
	v_mfma_f32_16x16x32_bf16 v[52:55], v[178:181], v[186:189], v[52:55]
	v_mfma_f32_16x16x32_bf16 v[40:43], v[170:173], v[200:203], v[40:43]
	v_mfma_f32_16x16x32_bf16 v[36:39], v[178:181], v[200:203], v[36:39]
	v_mfma_f32_16x16x32_bf16 v[24:27], v[170:173], v[208:211], v[24:27]
	v_mfma_f32_16x16x32_bf16 v[20:23], v[178:181], v[208:211], v[20:23]
	v_mfma_f32_16x16x32_bf16 v[8:11], v[170:173], v[216:219], v[8:11]
	v_mfma_f32_16x16x32_bf16 v[4:7], v[178:181], v[216:219], v[4:7]
	s_barrier
	s_setprio 0
	s_add_i32 s0, 0, 0x18000
	v_add_u32_e32 v156, s0, v157
	s_add_i32 s6, 0, 0x1c000
	ds_read_b128 v[144:147], v156
	ds_read_b128 v[148:151], v156 offset:1024
	ds_read_b128 v[152:155], v156 offset:2048
	ds_read_b128 v[162:165], v156 offset:3072
	v_add_u32_e32 v156, s6, v157
	ds_read_b128 v[166:169], v156
	ds_read_b128 v[170:173], v156 offset:1024
	ds_read_b128 v[174:177], v156 offset:2048
	ds_read_b128 v[178:181], v156 offset:3072
	s_add_u32 s34, s34, 0x80000
	s_addc_u32 s35, s35, 0
	s_mov_b32 m0, s50
	v_lshl_add_u64 v[224:225], s[34:35], 0, v[138:139]
	ds_read_b128 v[182:185], v161 offset:32768
	ds_read_b128 v[186:189], v161 offset:33792
	ds_read_b128 v[190:193], v161 offset:34816
	ds_read_b128 v[200:203], v161 offset:35840
	ds_read_b128 v[204:207], v161 offset:36864
	ds_read_b128 v[208:211], v161 offset:37888
	ds_read_b128 v[212:215], v161 offset:38912
	ds_read_b128 v[216:219], v161 offset:39936
	global_load_lds_dwordx4 v[224:225], off
	s_mov_b32 m0, s51
	v_lshl_add_u64 v[224:225], s[34:35], 0, v[134:135]
	global_load_lds_dwordx4 v[224:225], off
	s_setprio 1
	s_waitcnt vmcnt(8) lgkmcnt(0)
	s_barrier
	v_mfma_f32_16x16x32_bf16 v[128:131], v[144:147], v[182:185], v[128:131]
	v_mfma_f32_16x16x32_bf16 v[124:127], v[152:155], v[182:185], v[124:127]
	v_mfma_f32_16x16x32_bf16 v[112:115], v[144:147], v[190:193], v[112:115]
	v_mfma_f32_16x16x32_bf16 v[108:111], v[152:155], v[190:193], v[108:111]
	v_mfma_f32_16x16x32_bf16 v[96:99], v[144:147], v[204:207], v[96:99]
	v_mfma_f32_16x16x32_bf16 v[92:95], v[152:155], v[204:207], v[92:95]
	v_mfma_f32_16x16x32_bf16 v[80:83], v[144:147], v[212:215], v[80:83]
	v_mfma_f32_16x16x32_bf16 v[76:79], v[152:155], v[212:215], v[76:79]
	v_mfma_f32_16x16x32_bf16 v[128:131], v[148:151], v[186:189], v[128:131]
	v_mfma_f32_16x16x32_bf16 v[124:127], v[162:165], v[186:189], v[124:127]
	v_mfma_f32_16x16x32_bf16 v[112:115], v[148:151], v[200:203], v[112:115]
	v_mfma_f32_16x16x32_bf16 v[108:111], v[162:165], v[200:203], v[108:111]
	v_mfma_f32_16x16x32_bf16 v[96:99], v[148:151], v[208:211], v[96:99]
	v_mfma_f32_16x16x32_bf16 v[92:95], v[162:165], v[208:211], v[92:95]
	v_mfma_f32_16x16x32_bf16 v[80:83], v[148:151], v[216:219], v[80:83]
	v_mfma_f32_16x16x32_bf16 v[76:79], v[162:165], v[216:219], v[76:79]
	s_setprio 0
	s_setprio 1
	v_mfma_f32_16x16x32_bf16 v[120:123], v[166:169], v[182:185], v[120:123]
	v_mfma_f32_16x16x32_bf16 v[116:119], v[174:177], v[182:185], v[116:119]
	v_mfma_f32_16x16x32_bf16 v[104:107], v[166:169], v[190:193], v[104:107]
	v_mfma_f32_16x16x32_bf16 v[100:103], v[174:177], v[190:193], v[100:103]
	v_mfma_f32_16x16x32_bf16 v[88:91], v[166:169], v[204:207], v[88:91]
	v_mfma_f32_16x16x32_bf16 v[84:87], v[174:177], v[204:207], v[84:87]
	v_mfma_f32_16x16x32_bf16 v[72:75], v[166:169], v[212:215], v[72:75]
	v_mfma_f32_16x16x32_bf16 v[68:71], v[174:177], v[212:215], v[68:71]
	v_mfma_f32_16x16x32_bf16 v[120:123], v[170:173], v[186:189], v[120:123]
	v_mfma_f32_16x16x32_bf16 v[116:119], v[178:181], v[186:189], v[116:119]
	v_mfma_f32_16x16x32_bf16 v[104:107], v[170:173], v[200:203], v[104:107]
	v_mfma_f32_16x16x32_bf16 v[100:103], v[178:181], v[200:203], v[100:103]
	v_mfma_f32_16x16x32_bf16 v[88:91], v[170:173], v[208:211], v[88:91]
	v_mfma_f32_16x16x32_bf16 v[84:87], v[178:181], v[208:211], v[84:87]
	v_mfma_f32_16x16x32_bf16 v[72:75], v[170:173], v[216:219], v[72:75]
	v_mfma_f32_16x16x32_bf16 v[68:71], v[178:181], v[216:219], v[68:71]
	s_barrier
	s_setprio 0
	s_add_i32 s0, s0, s25
	v_lshl_add_u64 v[194:195], v[194:195], 0, s[90:91]
	s_mov_b32 m0, s0
	ds_read_b128 v[182:185], v161 offset:49152
	ds_read_b128 v[186:189], v161 offset:50176
	ds_read_b128 v[190:193], v161 offset:51200
	ds_read_b128 v[200:203], v161 offset:52224
	ds_read_b128 v[204:207], v161 offset:53248
	ds_read_b128 v[208:211], v161 offset:54272
	ds_read_b128 v[212:215], v161 offset:55296
	ds_read_b128 v[216:219], v161 offset:56320
	global_load_lds_dwordx4 v[194:195], off
	s_add_i32 m0, s0, 0x2000
	s_add_u32 s30, s30, 0x80080
	v_lshl_add_u64 v[194:195], v[198:199], 0, s[90:91]
	s_addc_u32 s31, s31, 0
	s_add_i32 s0, s6, s25
	global_load_lds_dwordx4 v[194:195], off
	s_mov_b32 m0, s0
	v_lshl_add_u64 v[194:195], s[30:31], 0, v[136:137]
	global_load_lds_dwordx4 v[194:195], off
	s_add_i32 m0, s0, 0x2000
	v_lshl_add_u64 v[194:195], s[30:31], 0, v[132:133]
	global_load_lds_dwordx4 v[194:195], off
	s_mov_b32 m0, s55
	v_lshl_add_u64 v[194:195], v[220:221], 0, s[90:91]
	global_load_lds_dwordx4 v[194:195], off
	s_mov_b32 m0, s60
	v_lshl_add_u64 v[194:195], v[222:223], 0, s[90:91]
	global_load_lds_dwordx4 v[194:195], off
	s_setprio 1
	s_waitcnt vmcnt(8) lgkmcnt(0)
	s_barrier
	v_mfma_f32_16x16x32_bf16 v[64:67], v[144:147], v[182:185], v[64:67]
	v_mfma_f32_16x16x32_bf16 v[60:63], v[152:155], v[182:185], v[60:63]
	v_mfma_f32_16x16x32_bf16 v[48:51], v[144:147], v[190:193], v[48:51]
	v_mfma_f32_16x16x32_bf16 v[44:47], v[152:155], v[190:193], v[44:47]
	v_mfma_f32_16x16x32_bf16 v[32:35], v[144:147], v[204:207], v[32:35]
	v_mfma_f32_16x16x32_bf16 v[28:31], v[152:155], v[204:207], v[28:31]
	v_mfma_f32_16x16x32_bf16 v[16:19], v[144:147], v[212:215], v[16:19]
	v_mfma_f32_16x16x32_bf16 v[12:15], v[152:155], v[212:215], v[12:15]
	v_mfma_f32_16x16x32_bf16 v[64:67], v[148:151], v[186:189], v[64:67]
	v_mfma_f32_16x16x32_bf16 v[60:63], v[162:165], v[186:189], v[60:63]
	v_mfma_f32_16x16x32_bf16 v[48:51], v[148:151], v[200:203], v[48:51]
	v_mfma_f32_16x16x32_bf16 v[44:47], v[162:165], v[200:203], v[44:47]
	v_mfma_f32_16x16x32_bf16 v[32:35], v[148:151], v[208:211], v[32:35]
	v_mfma_f32_16x16x32_bf16 v[28:31], v[162:165], v[208:211], v[28:31]
	v_mfma_f32_16x16x32_bf16 v[16:19], v[148:151], v[216:219], v[16:19]
	v_mfma_f32_16x16x32_bf16 v[12:15], v[162:165], v[216:219], v[12:15]
	s_setprio 0
	s_setprio 1
	v_mfma_f32_16x16x32_bf16 v[56:59], v[166:169], v[182:185], v[56:59]
	v_mfma_f32_16x16x32_bf16 v[52:55], v[174:177], v[182:185], v[52:55]
	v_mfma_f32_16x16x32_bf16 v[40:43], v[166:169], v[190:193], v[40:43]
	v_mfma_f32_16x16x32_bf16 v[36:39], v[174:177], v[190:193], v[36:39]
	v_mfma_f32_16x16x32_bf16 v[24:27], v[166:169], v[204:207], v[24:27]
	v_mfma_f32_16x16x32_bf16 v[20:23], v[174:177], v[204:207], v[20:23]
	v_mfma_f32_16x16x32_bf16 v[8:11], v[166:169], v[212:215], v[8:11]
	v_mfma_f32_16x16x32_bf16 v[4:7], v[174:177], v[212:215], v[4:7]
	v_mfma_f32_16x16x32_bf16 v[56:59], v[170:173], v[186:189], v[56:59]
	v_mfma_f32_16x16x32_bf16 v[52:55], v[178:181], v[186:189], v[52:55]
	v_mfma_f32_16x16x32_bf16 v[40:43], v[170:173], v[200:203], v[40:43]
	v_mfma_f32_16x16x32_bf16 v[36:39], v[178:181], v[200:203], v[36:39]
	v_mfma_f32_16x16x32_bf16 v[24:27], v[170:173], v[208:211], v[24:27]
	v_mfma_f32_16x16x32_bf16 v[20:23], v[178:181], v[208:211], v[20:23]
	v_mfma_f32_16x16x32_bf16 v[8:11], v[170:173], v[216:219], v[8:11]
	v_mfma_f32_16x16x32_bf16 v[4:7], v[178:181], v[216:219], v[4:7]
	s_barrier
	s_setprio 0
	s_add_i32 s66, s66, 2
	s_add_u32 s36, s36, 0x100
	s_addc_u32 s37, s37, 0
	s_add_u32 s38, s38, 0x100
	s_addc_u32 s39, s39, 0
	s_cmp_gt_u32 s66, 29
	s_cbranch_scc0 .LBB0_1137
	s_and_b64 vcc, exec, s[20:21]
	s_cbranch_vccz .LBB0_1140
	s_barrier

.LBB0_1167:
	s_add_u32 s0, s36, 0xfff80080
	s_addc_u32 s6, s37, -1
	s_add_i32 s49, 0, 0x10000
	s_cmp_eq_u32 s67, 28
	s_cselect_b32 s35, s43, s6
	s_cselect_b32 s34, s65, s0
	v_add_u32_e32 v156, s49, v157
	s_cselect_b32 s31, s29, s39
	s_cselect_b32 s30, s66, s38
	s_add_i32 s0, 0, 0x14000
	ds_read_b128 v[144:147], v156
	ds_read_b128 v[148:151], v156 offset:1024
	ds_read_b128 v[152:155], v156 offset:2048
	ds_read_b128 v[162:165], v156 offset:3072
	v_add_u32_e32 v156, s0, v157
	ds_read_b128 v[166:169], v156
	ds_read_b128 v[170:173], v156 offset:1024
	ds_read_b128 v[174:177], v156 offset:2048
	ds_read_b128 v[178:181], v156 offset:3072
	v_lshl_add_u64 v[194:195], s[36:37], 0, v[140:141]
	s_add_i32 m0, s25, 0xc000
	ds_read_b128 v[182:185], v161
	ds_read_b128 v[186:189], v161 offset:1024
	ds_read_b128 v[190:193], v161 offset:2048
	ds_read_b128 v[200:203], v161 offset:3072
	ds_read_b128 v[204:207], v161 offset:4096
	ds_read_b128 v[208:211], v161 offset:5120
	ds_read_b128 v[212:215], v161 offset:6144
	ds_read_b128 v[216:219], v161 offset:7168
	global_load_lds_dwordx4 v[194:195], off
	s_add_i32 m0, s25, 0xe000
	v_lshl_add_u64 v[194:195], s[36:37], 0, v[142:143]
	global_load_lds_dwordx4 v[194:195], off
	s_setprio 1
	s_waitcnt vmcnt(8) lgkmcnt(0)
	s_barrier
	v_mfma_f32_16x16x32_bf16 v[128:131], v[144:147], v[182:185], v[128:131]
	v_mfma_f32_16x16x32_bf16 v[124:127], v[152:155], v[182:185], v[124:127]
	v_mfma_f32_16x16x32_bf16 v[112:115], v[144:147], v[190:193], v[112:115]
	v_mfma_f32_16x16x32_bf16 v[108:111], v[152:155], v[190:193], v[108:111]
	v_mfma_f32_16x16x32_bf16 v[96:99], v[144:147], v[204:207], v[96:99]
	v_mfma_f32_16x16x32_bf16 v[92:95], v[152:155], v[204:207], v[92:95]
	v_mfma_f32_16x16x32_bf16 v[80:83], v[144:147], v[212:215], v[80:83]
	v_mfma_f32_16x16x32_bf16 v[76:79], v[152:155], v[212:215], v[76:79]
	v_mfma_f32_16x16x32_bf16 v[128:131], v[148:151], v[186:189], v[128:131]
	v_mfma_f32_16x16x32_bf16 v[124:127], v[162:165], v[186:189], v[124:127]
	v_mfma_f32_16x16x32_bf16 v[112:115], v[148:151], v[200:203], v[112:115]
	v_mfma_f32_16x16x32_bf16 v[108:111], v[162:165], v[200:203], v[108:111]
	v_mfma_f32_16x16x32_bf16 v[96:99], v[148:151], v[208:211], v[96:99]
	v_mfma_f32_16x16x32_bf16 v[92:95], v[162:165], v[208:211], v[92:95]
	v_mfma_f32_16x16x32_bf16 v[80:83], v[148:151], v[216:219], v[80:83]
	v_mfma_f32_16x16x32_bf16 v[76:79], v[162:165], v[216:219], v[76:79]
	s_setprio 0
	s_setprio 1
	v_mfma_f32_16x16x32_bf16 v[120:123], v[166:169], v[182:185], v[120:123]
	v_mfma_f32_16x16x32_bf16 v[116:119], v[174:177], v[182:185], v[116:119]
	v_mfma_f32_16x16x32_bf16 v[104:107], v[166:169], v[190:193], v[104:107]
	v_mfma_f32_16x16x32_bf16 v[100:103], v[174:177], v[190:193], v[100:103]
	v_mfma_f32_16x16x32_bf16 v[88:91], v[166:169], v[204:207], v[88:91]
	v_mfma_f32_16x16x32_bf16 v[84:87], v[174:177], v[204:207], v[84:87]
	v_mfma_f32_16x16x32_bf16 v[72:75], v[166:169], v[212:215], v[72:75]
	v_mfma_f32_16x16x32_bf16 v[68:71], v[174:177], v[212:215], v[68:71]
	v_mfma_f32_16x16x32_bf16 v[120:123], v[170:173], v[186:189], v[120:123]
	v_mfma_f32_16x16x32_bf16 v[116:119], v[178:181], v[186:189], v[116:119]
	v_mfma_f32_16x16x32_bf16 v[104:107], v[170:173], v[200:203], v[104:107]
	v_mfma_f32_16x16x32_bf16 v[100:103], v[178:181], v[200:203], v[100:103]
	v_mfma_f32_16x16x32_bf16 v[88:91], v[170:173], v[208:211], v[88:91]
	v_mfma_f32_16x16x32_bf16 v[84:87], v[178:181], v[208:211], v[84:87]
	v_mfma_f32_16x16x32_bf16 v[72:75], v[170:173], v[216:219], v[72:75]
	v_mfma_f32_16x16x32_bf16 v[68:71], v[178:181], v[216:219], v[68:71]
	s_barrier
	s_setprio 0
	s_add_i32 s6, s49, s1
	v_lshl_add_u64 v[194:195], s[30:31], 0, v[136:137]
	s_mov_b32 m0, s6
	ds_read_b128 v[182:185], v161 offset:16384
	ds_read_b128 v[186:189], v161 offset:17408
	ds_read_b128 v[190:193], v161 offset:18432
	ds_read_b128 v[200:203], v161 offset:19456
	ds_read_b128 v[204:207], v161 offset:20480
	ds_read_b128 v[208:211], v161 offset:21504
	ds_read_b128 v[212:215], v161 offset:22528
	ds_read_b128 v[216:219], v161 offset:23552
	global_load_lds_dwordx4 v[194:195], off
	s_add_i32 m0, s6, 0x2000
	s_add_u32 s68, s30, 0x80000
	v_lshl_add_u64 v[198:199], s[30:31], 0, v[132:133]
	s_addc_u32 s69, s31, 0
	s_add_i32 s0, s0, s1
	global_load_lds_dwordx4 v[198:199], off
	v_lshl_add_u64 v[220:221], s[68:69], 0, v[136:137]
	s_mov_b32 m0, s0
	global_load_lds_dwordx4 v[220:221], off
	s_add_i32 m0, s0, 0x2000
	v_lshl_add_u64 v[220:221], s[68:69], 0, v[132:133]
	global_load_lds_dwordx4 v[220:221], off
	s_mov_b32 m0, s25
	v_lshl_add_u64 v[220:221], s[34:35], 0, v[138:139]
	global_load_lds_dwordx4 v[220:221], off
	s_mov_b32 m0, s33
	v_lshl_add_u64 v[222:223], s[34:35], 0, v[134:135]
	global_load_lds_dwordx4 v[222:223], off
	s_setprio 1
	s_waitcnt vmcnt(8) lgkmcnt(0)
	s_barrier
	v_mfma_f32_16x16x32_bf16 v[64:67], v[144:147], v[182:185], v[64:67]
	v_mfma_f32_16x16x32_bf16 v[60:63], v[152:155], v[182:185], v[60:63]
	v_mfma_f32_16x16x32_bf16 v[48:51], v[144:147], v[190:193], v[48:51]
	v_mfma_f32_16x16x32_bf16 v[44:47], v[152:155], v[190:193], v[44:47]
	v_mfma_f32_16x16x32_bf16 v[32:35], v[144:147], v[204:207], v[32:35]
	v_mfma_f32_16x16x32_bf16 v[28:31], v[152:155], v[204:207], v[28:31]
	v_mfma_f32_16x16x32_bf16 v[16:19], v[144:147], v[212:215], v[16:19]
	v_mfma_f32_16x16x32_bf16 v[12:15], v[152:155], v[212:215], v[12:15]
	v_mfma_f32_16x16x32_bf16 v[64:67], v[148:151], v[186:189], v[64:67]
	v_mfma_f32_16x16x32_bf16 v[60:63], v[162:165], v[186:189], v[60:63]
	v_mfma_f32_16x16x32_bf16 v[48:51], v[148:151], v[200:203], v[48:51]
	v_mfma_f32_16x16x32_bf16 v[44:47], v[162:165], v[200:203], v[44:47]
	v_mfma_f32_16x16x32_bf16 v[32:35], v[148:151], v[208:211], v[32:35]
	v_mfma_f32_16x16x32_bf16 v[28:31], v[162:165], v[208:211], v[28:31]
	v_mfma_f32_16x16x32_bf16 v[16:19], v[148:151], v[216:219], v[16:19]
	v_mfma_f32_16x16x32_bf16 v[12:15], v[162:165], v[216:219], v[12:15]
	s_setprio 0
	s_setprio 1
	v_mfma_f32_16x16x32_bf16 v[56:59], v[166:169], v[182:185], v[56:59]
	v_mfma_f32_16x16x32_bf16 v[52:55], v[174:177], v[182:185], v[52:55]
	v_mfma_f32_16x16x32_bf16 v[40:43], v[166:169], v[190:193], v[40:43]
	v_mfma_f32_16x16x32_bf16 v[36:39], v[174:177], v[190:193], v[36:39]
	v_mfma_f32_16x16x32_bf16 v[24:27], v[166:169], v[204:207], v[24:27]
	v_mfma_f32_16x16x32_bf16 v[20:23], v[174:177], v[204:207], v[20:23]
	v_mfma_f32_16x16x32_bf16 v[8:11], v[166:169], v[212:215], v[8:11]
	v_mfma_f32_16x16x32_bf16 v[4:7], v[174:177], v[212:215], v[4:7]
	v_mfma_f32_16x16x32_bf16 v[56:59], v[170:173], v[186:189], v[56:59]
	v_mfma_f32_16x16x32_bf16 v[52:55], v[178:181], v[186:189], v[52:55]
	v_mfma_f32_16x16x32_bf16 v[40:43], v[170:173], v[200:203], v[40:43]
	v_mfma_f32_16x16x32_bf16 v[36:39], v[178:181], v[200:203], v[36:39]
	v_mfma_f32_16x16x32_bf16 v[24:27], v[170:173], v[208:211], v[24:27]
	v_mfma_f32_16x16x32_bf16 v[20:23], v[178:181], v[208:211], v[20:23]
	v_mfma_f32_16x16x32_bf16 v[8:11], v[170:173], v[216:219], v[8:11]
	v_mfma_f32_16x16x32_bf16 v[4:7], v[178:181], v[216:219], v[4:7]
	s_barrier
	s_setprio 0
	s_add_i32 s0, 0, 0x18000
	v_add_u32_e32 v156, s0, v157
	s_add_i32 s6, 0, 0x1c000
	ds_read_b128 v[144:147], v156
	ds_read_b128 v[148:151], v156 offset:1024
	ds_read_b128 v[152:155], v156 offset:2048
	ds_read_b128 v[162:165], v156 offset:3072
	v_add_u32_e32 v156, s6, v157
	ds_read_b128 v[166:169], v156
	ds_read_b128 v[170:173], v156 offset:1024
	ds_read_b128 v[174:177], v156 offset:2048
	ds_read_b128 v[178:181], v156 offset:3072
	s_add_u32 s34, s34, 0x80000
	s_addc_u32 s35, s35, 0
	s_mov_b32 m0, s40
	v_lshl_add_u64 v[224:225], s[34:35], 0, v[138:139]
	ds_read_b128 v[182:185], v161 offset:32768
	ds_read_b128 v[186:189], v161 offset:33792
	ds_read_b128 v[190:193], v161 offset:34816
	ds_read_b128 v[200:203], v161 offset:35840
	ds_read_b128 v[204:207], v161 offset:36864
	ds_read_b128 v[208:211], v161 offset:37888
	ds_read_b128 v[212:215], v161 offset:38912
	ds_read_b128 v[216:219], v161 offset:39936
	global_load_lds_dwordx4 v[224:225], off
	s_mov_b32 m0, s50
	v_lshl_add_u64 v[224:225], s[34:35], 0, v[134:135]
	global_load_lds_dwordx4 v[224:225], off
	s_setprio 1
	s_waitcnt vmcnt(8) lgkmcnt(0)
	s_barrier
	v_mfma_f32_16x16x32_bf16 v[128:131], v[144:147], v[182:185], v[128:131]
	v_mfma_f32_16x16x32_bf16 v[124:127], v[152:155], v[182:185], v[124:127]
	v_mfma_f32_16x16x32_bf16 v[112:115], v[144:147], v[190:193], v[112:115]
	v_mfma_f32_16x16x32_bf16 v[108:111], v[152:155], v[190:193], v[108:111]
	v_mfma_f32_16x16x32_bf16 v[96:99], v[144:147], v[204:207], v[96:99]
	v_mfma_f32_16x16x32_bf16 v[92:95], v[152:155], v[204:207], v[92:95]
	v_mfma_f32_16x16x32_bf16 v[80:83], v[144:147], v[212:215], v[80:83]
	v_mfma_f32_16x16x32_bf16 v[76:79], v[152:155], v[212:215], v[76:79]
	v_mfma_f32_16x16x32_bf16 v[128:131], v[148:151], v[186:189], v[128:131]
	v_mfma_f32_16x16x32_bf16 v[124:127], v[162:165], v[186:189], v[124:127]
	v_mfma_f32_16x16x32_bf16 v[112:115], v[148:151], v[200:203], v[112:115]
	v_mfma_f32_16x16x32_bf16 v[108:111], v[162:165], v[200:203], v[108:111]
	v_mfma_f32_16x16x32_bf16 v[96:99], v[148:151], v[208:211], v[96:99]
	v_mfma_f32_16x16x32_bf16 v[92:95], v[162:165], v[208:211], v[92:95]
	v_mfma_f32_16x16x32_bf16 v[80:83], v[148:151], v[216:219], v[80:83]
	v_mfma_f32_16x16x32_bf16 v[76:79], v[162:165], v[216:219], v[76:79]
	s_setprio 0
	s_setprio 1
	v_mfma_f32_16x16x32_bf16 v[120:123], v[166:169], v[182:185], v[120:123]
	v_mfma_f32_16x16x32_bf16 v[116:119], v[174:177], v[182:185], v[116:119]
	v_mfma_f32_16x16x32_bf16 v[104:107], v[166:169], v[190:193], v[104:107]
	v_mfma_f32_16x16x32_bf16 v[100:103], v[174:177], v[190:193], v[100:103]
	v_mfma_f32_16x16x32_bf16 v[88:91], v[166:169], v[204:207], v[88:91]
	v_mfma_f32_16x16x32_bf16 v[84:87], v[174:177], v[204:207], v[84:87]
	v_mfma_f32_16x16x32_bf16 v[72:75], v[166:169], v[212:215], v[72:75]
	v_mfma_f32_16x16x32_bf16 v[68:71], v[174:177], v[212:215], v[68:71]
	v_mfma_f32_16x16x32_bf16 v[120:123], v[170:173], v[186:189], v[120:123]
	v_mfma_f32_16x16x32_bf16 v[116:119], v[178:181], v[186:189], v[116:119]
	v_mfma_f32_16x16x32_bf16 v[104:107], v[170:173], v[200:203], v[104:107]
	v_mfma_f32_16x16x32_bf16 v[100:103], v[178:181], v[200:203], v[100:103]
	v_mfma_f32_16x16x32_bf16 v[88:91], v[170:173], v[208:211], v[88:91]
	v_mfma_f32_16x16x32_bf16 v[84:87], v[178:181], v[208:211], v[84:87]
	v_mfma_f32_16x16x32_bf16 v[72:75], v[170:173], v[216:219], v[72:75]
	v_mfma_f32_16x16x32_bf16 v[68:71], v[178:181], v[216:219], v[68:71]
	s_barrier
	s_setprio 0
	s_add_i32 s0, s0, s1
	v_lshl_add_u64 v[194:195], v[194:195], 0, s[90:91]
	s_mov_b32 m0, s0
	ds_read_b128 v[182:185], v161 offset:49152
	ds_read_b128 v[186:189], v161 offset:50176
	ds_read_b128 v[190:193], v161 offset:51200
	ds_read_b128 v[200:203], v161 offset:52224
	ds_read_b128 v[204:207], v161 offset:53248
	ds_read_b128 v[208:211], v161 offset:54272
	ds_read_b128 v[212:215], v161 offset:55296
	ds_read_b128 v[216:219], v161 offset:56320
	global_load_lds_dwordx4 v[194:195], off
	s_add_i32 m0, s0, 0x2000
	s_add_u32 s30, s30, 0x80080
	v_lshl_add_u64 v[194:195], v[198:199], 0, s[90:91]
	s_addc_u32 s31, s31, 0
	s_add_i32 s0, s6, s1
	global_load_lds_dwordx4 v[194:195], off
	s_mov_b32 m0, s0
	v_lshl_add_u64 v[194:195], s[30:31], 0, v[136:137]
	global_load_lds_dwordx4 v[194:195], off
	s_add_i32 m0, s0, 0x2000
	v_lshl_add_u64 v[194:195], s[30:31], 0, v[132:133]
	global_load_lds_dwordx4 v[194:195], off
	s_mov_b32 m0, s51
	v_lshl_add_u64 v[194:195], v[220:221], 0, s[90:91]
	global_load_lds_dwordx4 v[194:195], off
	s_mov_b32 m0, s55
	v_lshl_add_u64 v[194:195], v[222:223], 0, s[90:91]
	global_load_lds_dwordx4 v[194:195], off
	s_setprio 1
	s_waitcnt vmcnt(8) lgkmcnt(0)
	s_barrier
	v_mfma_f32_16x16x32_bf16 v[64:67], v[144:147], v[182:185], v[64:67]
	v_mfma_f32_16x16x32_bf16 v[60:63], v[152:155], v[182:185], v[60:63]
	v_mfma_f32_16x16x32_bf16 v[48:51], v[144:147], v[190:193], v[48:51]
	v_mfma_f32_16x16x32_bf16 v[44:47], v[152:155], v[190:193], v[44:47]
	v_mfma_f32_16x16x32_bf16 v[32:35], v[144:147], v[204:207], v[32:35]
	v_mfma_f32_16x16x32_bf16 v[28:31], v[152:155], v[204:207], v[28:31]
	v_mfma_f32_16x16x32_bf16 v[16:19], v[144:147], v[212:215], v[16:19]
	v_mfma_f32_16x16x32_bf16 v[12:15], v[152:155], v[212:215], v[12:15]
	v_mfma_f32_16x16x32_bf16 v[64:67], v[148:151], v[186:189], v[64:67]
	v_mfma_f32_16x16x32_bf16 v[60:63], v[162:165], v[186:189], v[60:63]
	v_mfma_f32_16x16x32_bf16 v[48:51], v[148:151], v[200:203], v[48:51]
	v_mfma_f32_16x16x32_bf16 v[44:47], v[162:165], v[200:203], v[44:47]
	v_mfma_f32_16x16x32_bf16 v[32:35], v[148:151], v[208:211], v[32:35]
	v_mfma_f32_16x16x32_bf16 v[28:31], v[162:165], v[208:211], v[28:31]
	v_mfma_f32_16x16x32_bf16 v[16:19], v[148:151], v[216:219], v[16:19]
	v_mfma_f32_16x16x32_bf16 v[12:15], v[162:165], v[216:219], v[12:15]
	s_setprio 0
	s_setprio 1
	v_mfma_f32_16x16x32_bf16 v[56:59], v[166:169], v[182:185], v[56:59]
	v_mfma_f32_16x16x32_bf16 v[52:55], v[174:177], v[182:185], v[52:55]
	v_mfma_f32_16x16x32_bf16 v[40:43], v[166:169], v[190:193], v[40:43]
	v_mfma_f32_16x16x32_bf16 v[36:39], v[174:177], v[190:193], v[36:39]
	v_mfma_f32_16x16x32_bf16 v[24:27], v[166:169], v[204:207], v[24:27]
	v_mfma_f32_16x16x32_bf16 v[20:23], v[174:177], v[204:207], v[20:23]
	v_mfma_f32_16x16x32_bf16 v[8:11], v[166:169], v[212:215], v[8:11]
	v_mfma_f32_16x16x32_bf16 v[4:7], v[174:177], v[212:215], v[4:7]
	v_mfma_f32_16x16x32_bf16 v[56:59], v[170:173], v[186:189], v[56:59]
	v_mfma_f32_16x16x32_bf16 v[52:55], v[178:181], v[186:189], v[52:55]
	v_mfma_f32_16x16x32_bf16 v[40:43], v[170:173], v[200:203], v[40:43]
	v_mfma_f32_16x16x32_bf16 v[36:39], v[178:181], v[200:203], v[36:39]
	v_mfma_f32_16x16x32_bf16 v[24:27], v[170:173], v[208:211], v[24:27]
	v_mfma_f32_16x16x32_bf16 v[20:23], v[178:181], v[208:211], v[20:23]
	v_mfma_f32_16x16x32_bf16 v[8:11], v[170:173], v[216:219], v[8:11]
	v_mfma_f32_16x16x32_bf16 v[4:7], v[178:181], v[216:219], v[4:7]
	s_barrier
	s_setprio 0
	s_add_i32 s67, s67, 2
	s_add_u32 s36, s36, 0x100
	s_addc_u32 s37, s37, 0
	s_add_u32 s38, s38, 0x100
	s_addc_u32 s39, s39, 0
	s_cmp_gt_u32 s67, 29
	s_cbranch_scc0 .LBB0_1167
	s_and_b64 vcc, exec, s[20:21]
	s_cbranch_vccz .LBB0_1170
	s_barrier

.LBB0_1186:
	s_add_u32 s0, s64, s30
	s_addc_u32 s6, s65, 0
	s_add_u32 s31, s0, 0x100
	s_addc_u32 s38, s6, 0
	s_and_b64 s[34:35], s[36:37], exec
	s_cselect_b32 s69, s29, s38
	s_cselect_b32 s68, s77, s31
	s_add_u32 s30, s62, s30
	s_addc_u32 s31, s63, 0
	s_add_u32 s34, s30, 0x100
	s_addc_u32 s35, s31, 0
	s_add_i32 s82, 0, 0x10000
	s_and_b64 s[30:31], s[36:37], exec
	s_cselect_b32 s53, s23, s35
	s_cselect_b32 s52, s78, s34
	s_add_i32 s37, 0, 0x14000
	s_add_u32 s34, s0, 0x10080
	s_addc_u32 s35, s6, 0
	s_add_i32 s84, s82, s4
	s_add_i32 m0, s46, 0xc000
	s_add_i32 s85, s46, 0xe000
	s_add_i32 s6, s84, 0x2000
	v_add_u32_e32 v140, s82, v142
	s_add_u32 s30, s52, 0x10000
	ds_read_b128 v[146:149], v140
	ds_read_b128 v[150:153], v140 offset:1024
	ds_read_b128 v[154:157], v140 offset:2048
	ds_read_b128 v[158:161], v140 offset:3072
	v_add_u32_e32 v140, s37, v142
	s_addc_u32 s31, s53, 0
	s_add_i32 s49, s37, s4
	ds_read_b128 v[162:165], v140
	ds_read_b128 v[166:169], v140 offset:1024
	ds_read_b128 v[170:173], v140 offset:2048
	ds_read_b128 v[174:177], v140 offset:3072
	s_add_i32 s81, s49, 0x2000
	s_add_i32 s54, 0, 0x18000
	s_add_i32 s73, 0, 0x1c000
	s_add_u32 s38, s68, 0x10000
	s_addc_u32 s39, s69, 0
	s_add_i32 s0, s54, s4
	s_add_i32 s80, s0, 0x2000
	s_add_u32 s36, s52, 0x10080
	s_addc_u32 s37, s53, 0
	s_add_i32 s83, s73, s4
	s_add_i32 s82, s83, 0x2000
	v_lshl_add_u64 v[140:141], s[34:35], 0, v[138:139]
	ds_read_b128 v[178:181], v144
	ds_read_b128 v[182:185], v144 offset:1024
	ds_read_b128 v[186:189], v144 offset:2048
	ds_read_b128 v[190:193], v144 offset:3072
	ds_read_b128 v[200:203], v144 offset:4096
	ds_read_b128 v[204:207], v144 offset:5120
	ds_read_b128 v[208:211], v144 offset:6144
	ds_read_b128 v[212:215], v144 offset:7168
	global_load_lds_dwordx4 v[140:141], off
	s_mov_b32 m0, s85
	v_lshl_add_u64 v[140:141], s[34:35], 0, v[134:135]
	global_load_lds_dwordx4 v[140:141], off
	s_setprio 1
	s_waitcnt vmcnt(8) lgkmcnt(0)
	s_barrier
	v_mfma_f32_16x16x32_bf16 v[128:131], v[146:149], v[178:181], v[128:131]
	v_mfma_f32_16x16x32_bf16 v[124:127], v[154:157], v[178:181], v[124:127]
	v_mfma_f32_16x16x32_bf16 v[120:123], v[146:149], v[186:189], v[120:123]
	v_mfma_f32_16x16x32_bf16 v[112:115], v[154:157], v[186:189], v[112:115]
	v_mfma_f32_16x16x32_bf16 v[104:107], v[146:149], v[200:203], v[104:107]
	v_mfma_f32_16x16x32_bf16 v[96:99], v[154:157], v[200:203], v[96:99]
	v_mfma_f32_16x16x32_bf16 v[88:91], v[146:149], v[208:211], v[88:91]
	v_mfma_f32_16x16x32_bf16 v[80:83], v[154:157], v[208:211], v[80:83]
	v_mfma_f32_16x16x32_bf16 v[128:131], v[150:153], v[182:185], v[128:131]
	v_mfma_f32_16x16x32_bf16 v[124:127], v[158:161], v[182:185], v[124:127]
	v_mfma_f32_16x16x32_bf16 v[120:123], v[150:153], v[190:193], v[120:123]
	v_mfma_f32_16x16x32_bf16 v[112:115], v[158:161], v[190:193], v[112:115]
	v_mfma_f32_16x16x32_bf16 v[104:107], v[150:153], v[204:207], v[104:107]
	v_mfma_f32_16x16x32_bf16 v[96:99], v[158:161], v[204:207], v[96:99]
	v_mfma_f32_16x16x32_bf16 v[88:91], v[150:153], v[212:215], v[88:91]
	v_mfma_f32_16x16x32_bf16 v[80:83], v[158:161], v[212:215], v[80:83]
	s_setprio 0
	s_setprio 1
	v_mfma_f32_16x16x32_bf16 v[116:119], v[162:165], v[178:181], v[116:119]
	v_mfma_f32_16x16x32_bf16 v[108:111], v[170:173], v[178:181], v[108:111]
	v_mfma_f32_16x16x32_bf16 v[100:103], v[162:165], v[186:189], v[100:103]
	v_mfma_f32_16x16x32_bf16 v[92:95], v[170:173], v[186:189], v[92:95]
	v_mfma_f32_16x16x32_bf16 v[84:87], v[162:165], v[200:203], v[84:87]
	v_mfma_f32_16x16x32_bf16 v[76:79], v[170:173], v[200:203], v[76:79]
	v_mfma_f32_16x16x32_bf16 v[72:75], v[162:165], v[208:211], v[72:75]
	v_mfma_f32_16x16x32_bf16 v[68:71], v[170:173], v[208:211], v[68:71]
	v_mfma_f32_16x16x32_bf16 v[116:119], v[166:169], v[182:185], v[116:119]
	v_mfma_f32_16x16x32_bf16 v[108:111], v[174:177], v[182:185], v[108:111]
	v_mfma_f32_16x16x32_bf16 v[100:103], v[166:169], v[190:193], v[100:103]
	v_mfma_f32_16x16x32_bf16 v[92:95], v[174:177], v[190:193], v[92:95]
	v_mfma_f32_16x16x32_bf16 v[84:87], v[166:169], v[204:207], v[84:87]
	v_mfma_f32_16x16x32_bf16 v[76:79], v[174:177], v[204:207], v[76:79]
	v_mfma_f32_16x16x32_bf16 v[72:75], v[166:169], v[212:215], v[72:75]
	v_mfma_f32_16x16x32_bf16 v[68:71], v[174:177], v[212:215], v[68:71]
	s_barrier
	s_setprio 0
	s_mov_b32 m0, s84
	v_lshl_add_u64 v[140:141], s[52:53], 0, v[136:137]
	ds_read_b128 v[178:181], v144 offset:16384
	ds_read_b128 v[182:185], v144 offset:17408
	ds_read_b128 v[186:189], v144 offset:18432
	ds_read_b128 v[190:193], v144 offset:19456
	ds_read_b128 v[200:203], v144 offset:20480
	ds_read_b128 v[204:207], v144 offset:21504
	ds_read_b128 v[208:211], v144 offset:22528
	ds_read_b128 v[212:215], v144 offset:23552
	global_load_lds_dwordx4 v[140:141], off
	v_lshl_add_u64 v[194:195], s[52:53], 0, v[132:133]
	s_mov_b32 m0, s6
	v_lshl_add_u64 v[198:199], s[30:31], 0, v[136:137]
	global_load_lds_dwordx4 v[194:195], off
	s_mov_b32 m0, s49
	global_load_lds_dwordx4 v[198:199], off
	s_mov_b32 m0, s81
	v_lshl_add_u64 v[198:199], s[30:31], 0, v[132:133]
	global_load_lds_dwordx4 v[198:199], off
	s_mov_b32 m0, s46
	v_lshl_add_u64 v[198:199], s[68:69], 0, v[138:139]
	global_load_lds_dwordx4 v[198:199], off
	s_mov_b32 m0, s47
	v_lshl_add_u64 v[216:217], s[68:69], 0, v[134:135]
	global_load_lds_dwordx4 v[216:217], off
	s_setprio 1
	s_waitcnt vmcnt(8) lgkmcnt(0)
	s_barrier
	v_mfma_f32_16x16x32_bf16 v[64:67], v[146:149], v[178:181], v[64:67]
	v_mfma_f32_16x16x32_bf16 v[60:63], v[154:157], v[178:181], v[60:63]
	v_mfma_f32_16x16x32_bf16 v[56:59], v[146:149], v[186:189], v[56:59]
	v_mfma_f32_16x16x32_bf16 v[48:51], v[154:157], v[186:189], v[48:51]
	v_mfma_f32_16x16x32_bf16 v[40:43], v[146:149], v[200:203], v[40:43]
	v_mfma_f32_16x16x32_bf16 v[32:35], v[154:157], v[200:203], v[32:35]
	v_mfma_f32_16x16x32_bf16 v[24:27], v[146:149], v[208:211], v[24:27]
	v_mfma_f32_16x16x32_bf16 v[16:19], v[154:157], v[208:211], v[16:19]
	v_mfma_f32_16x16x32_bf16 v[64:67], v[150:153], v[182:185], v[64:67]
	v_mfma_f32_16x16x32_bf16 v[60:63], v[158:161], v[182:185], v[60:63]
	v_mfma_f32_16x16x32_bf16 v[56:59], v[150:153], v[190:193], v[56:59]
	v_mfma_f32_16x16x32_bf16 v[48:51], v[158:161], v[190:193], v[48:51]
	v_mfma_f32_16x16x32_bf16 v[40:43], v[150:153], v[204:207], v[40:43]
	v_mfma_f32_16x16x32_bf16 v[32:35], v[158:161], v[204:207], v[32:35]
	v_mfma_f32_16x16x32_bf16 v[24:27], v[150:153], v[212:215], v[24:27]
	v_mfma_f32_16x16x32_bf16 v[16:19], v[158:161], v[212:215], v[16:19]
	s_setprio 0
	s_setprio 1
	v_mfma_f32_16x16x32_bf16 v[52:55], v[162:165], v[178:181], v[52:55]
	v_mfma_f32_16x16x32_bf16 v[44:47], v[170:173], v[178:181], v[44:47]
	v_mfma_f32_16x16x32_bf16 v[36:39], v[162:165], v[186:189], v[36:39]
	v_mfma_f32_16x16x32_bf16 v[28:31], v[170:173], v[186:189], v[28:31]
	v_mfma_f32_16x16x32_bf16 v[20:23], v[162:165], v[200:203], v[20:23]
	v_mfma_f32_16x16x32_bf16 v[12:15], v[170:173], v[200:203], v[12:15]
	v_mfma_f32_16x16x32_bf16 v[8:11], v[162:165], v[208:211], v[8:11]
	v_mfma_f32_16x16x32_bf16 v[4:7], v[170:173], v[208:211], v[4:7]
	v_mfma_f32_16x16x32_bf16 v[52:55], v[166:169], v[182:185], v[52:55]
	v_mfma_f32_16x16x32_bf16 v[44:47], v[174:177], v[182:185], v[44:47]
	v_mfma_f32_16x16x32_bf16 v[36:39], v[166:169], v[190:193], v[36:39]
	v_mfma_f32_16x16x32_bf16 v[28:31], v[174:177], v[190:193], v[28:31]
	v_mfma_f32_16x16x32_bf16 v[20:23], v[166:169], v[204:207], v[20:23]
	v_mfma_f32_16x16x32_bf16 v[12:15], v[174:177], v[204:207], v[12:15]
	v_mfma_f32_16x16x32_bf16 v[8:11], v[166:169], v[212:215], v[8:11]
	v_mfma_f32_16x16x32_bf16 v[4:7], v[174:177], v[212:215], v[4:7]
	s_barrier
	s_setprio 0
	v_add_u32_e32 v145, s54, v142
	ds_read_b128 v[146:149], v145
	ds_read_b128 v[150:153], v145 offset:1024
	ds_read_b128 v[154:157], v145 offset:2048
	ds_read_b128 v[158:161], v145 offset:3072
	v_add_u32_e32 v145, s73, v142
	ds_read_b128 v[162:165], v145
	ds_read_b128 v[166:169], v145 offset:1024
	ds_read_b128 v[170:173], v145 offset:2048
	ds_read_b128 v[174:177], v145 offset:3072
	s_mov_b32 m0, s50
	v_lshl_add_u64 v[218:219], s[38:39], 0, v[138:139]
	ds_read_b128 v[178:181], v144 offset:32768
	ds_read_b128 v[182:185], v144 offset:33792
	ds_read_b128 v[186:189], v144 offset:34816
	ds_read_b128 v[190:193], v144 offset:35840
	ds_read_b128 v[200:203], v144 offset:36864
	ds_read_b128 v[204:207], v144 offset:37888
	ds_read_b128 v[208:211], v144 offset:38912
	ds_read_b128 v[212:215], v144 offset:39936
	global_load_lds_dwordx4 v[218:219], off
	s_mov_b32 m0, s51
	v_lshl_add_u64 v[218:219], s[38:39], 0, v[134:135]
	global_load_lds_dwordx4 v[218:219], off
	s_setprio 1
	s_waitcnt vmcnt(8) lgkmcnt(0)
	s_barrier
	v_mfma_f32_16x16x32_bf16 v[128:131], v[146:149], v[178:181], v[128:131]
	v_mfma_f32_16x16x32_bf16 v[124:127], v[154:157], v[178:181], v[124:127]
	v_mfma_f32_16x16x32_bf16 v[120:123], v[146:149], v[186:189], v[120:123]
	v_mfma_f32_16x16x32_bf16 v[112:115], v[154:157], v[186:189], v[112:115]
	v_mfma_f32_16x16x32_bf16 v[104:107], v[146:149], v[200:203], v[104:107]
	v_mfma_f32_16x16x32_bf16 v[96:99], v[154:157], v[200:203], v[96:99]
	v_mfma_f32_16x16x32_bf16 v[88:91], v[146:149], v[208:211], v[88:91]
	v_mfma_f32_16x16x32_bf16 v[80:83], v[154:157], v[208:211], v[80:83]
	v_mfma_f32_16x16x32_bf16 v[128:131], v[150:153], v[182:185], v[128:131]
	v_mfma_f32_16x16x32_bf16 v[124:127], v[158:161], v[182:185], v[124:127]
	v_mfma_f32_16x16x32_bf16 v[120:123], v[150:153], v[190:193], v[120:123]
	v_mfma_f32_16x16x32_bf16 v[112:115], v[158:161], v[190:193], v[112:115]
	v_mfma_f32_16x16x32_bf16 v[104:107], v[150:153], v[204:207], v[104:107]
	v_mfma_f32_16x16x32_bf16 v[96:99], v[158:161], v[204:207], v[96:99]
	v_mfma_f32_16x16x32_bf16 v[88:91], v[150:153], v[212:215], v[88:91]
	v_mfma_f32_16x16x32_bf16 v[80:83], v[158:161], v[212:215], v[80:83]
	s_setprio 0
	s_setprio 1
	v_mfma_f32_16x16x32_bf16 v[116:119], v[162:165], v[178:181], v[116:119]
	v_mfma_f32_16x16x32_bf16 v[108:111], v[170:173], v[178:181], v[108:111]
	v_mfma_f32_16x16x32_bf16 v[100:103], v[162:165], v[186:189], v[100:103]
	v_mfma_f32_16x16x32_bf16 v[92:95], v[170:173], v[186:189], v[92:95]
	v_mfma_f32_16x16x32_bf16 v[84:87], v[162:165], v[200:203], v[84:87]
	v_mfma_f32_16x16x32_bf16 v[76:79], v[170:173], v[200:203], v[76:79]
	v_mfma_f32_16x16x32_bf16 v[72:75], v[162:165], v[208:211], v[72:75]
	v_mfma_f32_16x16x32_bf16 v[68:71], v[170:173], v[208:211], v[68:71]
	v_mfma_f32_16x16x32_bf16 v[116:119], v[166:169], v[182:185], v[116:119]
	v_mfma_f32_16x16x32_bf16 v[108:111], v[174:177], v[182:185], v[108:111]
	v_mfma_f32_16x16x32_bf16 v[100:103], v[166:169], v[190:193], v[100:103]
	v_mfma_f32_16x16x32_bf16 v[92:95], v[174:177], v[190:193], v[92:95]
	v_mfma_f32_16x16x32_bf16 v[84:87], v[166:169], v[204:207], v[84:87]
	v_mfma_f32_16x16x32_bf16 v[76:79], v[174:177], v[204:207], v[76:79]
	v_mfma_f32_16x16x32_bf16 v[72:75], v[166:169], v[212:215], v[72:75]
	v_mfma_f32_16x16x32_bf16 v[68:71], v[174:177], v[212:215], v[68:71]
	s_barrier
	s_setprio 0
	s_mov_b32 m0, s0
	v_lshl_add_u64 v[140:141], v[140:141], 0, s[90:91]
	ds_read_b128 v[178:181], v144 offset:49152
	ds_read_b128 v[182:185], v144 offset:50176
	ds_read_b128 v[186:189], v144 offset:51200
	ds_read_b128 v[190:193], v144 offset:52224
	ds_read_b128 v[200:203], v144 offset:53248
	ds_read_b128 v[204:207], v144 offset:54272
	ds_read_b128 v[208:211], v144 offset:55296
	ds_read_b128 v[212:215], v144 offset:56320
	global_load_lds_dwordx4 v[140:141], off
	s_mov_b32 m0, s80
	v_lshl_add_u64 v[140:141], v[194:195], 0, s[90:91]
	global_load_lds_dwordx4 v[140:141], off
	s_mov_b32 m0, s83
	v_lshl_add_u64 v[140:141], s[36:37], 0, v[136:137]
	global_load_lds_dwordx4 v[140:141], off
	s_mov_b32 m0, s82
	v_lshl_add_u64 v[140:141], s[36:37], 0, v[132:133]
	global_load_lds_dwordx4 v[140:141], off
	s_mov_b32 m0, s61
	v_lshl_add_u64 v[140:141], v[198:199], 0, s[90:91]
	global_load_lds_dwordx4 v[140:141], off
	s_mov_b32 m0, s74
	v_lshl_add_u64 v[140:141], v[216:217], 0, s[90:91]
	global_load_lds_dwordx4 v[140:141], off
	s_setprio 1
	s_waitcnt vmcnt(8) lgkmcnt(0)
	s_barrier
	v_mfma_f32_16x16x32_bf16 v[64:67], v[146:149], v[178:181], v[64:67]
	v_mfma_f32_16x16x32_bf16 v[60:63], v[154:157], v[178:181], v[60:63]
	v_mfma_f32_16x16x32_bf16 v[56:59], v[146:149], v[186:189], v[56:59]
	v_mfma_f32_16x16x32_bf16 v[48:51], v[154:157], v[186:189], v[48:51]
	v_mfma_f32_16x16x32_bf16 v[40:43], v[146:149], v[200:203], v[40:43]
	v_mfma_f32_16x16x32_bf16 v[32:35], v[154:157], v[200:203], v[32:35]
	v_mfma_f32_16x16x32_bf16 v[24:27], v[146:149], v[208:211], v[24:27]
	v_mfma_f32_16x16x32_bf16 v[16:19], v[154:157], v[208:211], v[16:19]
	v_mfma_f32_16x16x32_bf16 v[64:67], v[150:153], v[182:185], v[64:67]
	v_mfma_f32_16x16x32_bf16 v[60:63], v[158:161], v[182:185], v[60:63]
	v_mfma_f32_16x16x32_bf16 v[56:59], v[150:153], v[190:193], v[56:59]
	v_mfma_f32_16x16x32_bf16 v[48:51], v[158:161], v[190:193], v[48:51]
	v_mfma_f32_16x16x32_bf16 v[40:43], v[150:153], v[204:207], v[40:43]
	v_mfma_f32_16x16x32_bf16 v[32:35], v[158:161], v[204:207], v[32:35]
	v_mfma_f32_16x16x32_bf16 v[24:27], v[150:153], v[212:215], v[24:27]
	v_mfma_f32_16x16x32_bf16 v[16:19], v[158:161], v[212:215], v[16:19]
	s_setprio 0
	s_setprio 1
	v_mfma_f32_16x16x32_bf16 v[52:55], v[162:165], v[178:181], v[52:55]
	v_mfma_f32_16x16x32_bf16 v[44:47], v[170:173], v[178:181], v[44:47]
	v_mfma_f32_16x16x32_bf16 v[36:39], v[162:165], v[186:189], v[36:39]
	v_mfma_f32_16x16x32_bf16 v[28:31], v[170:173], v[186:189], v[28:31]
	v_mfma_f32_16x16x32_bf16 v[20:23], v[162:165], v[200:203], v[20:23]
	v_mfma_f32_16x16x32_bf16 v[12:15], v[170:173], v[200:203], v[12:15]
	v_mfma_f32_16x16x32_bf16 v[8:11], v[162:165], v[208:211], v[8:11]
	v_mfma_f32_16x16x32_bf16 v[4:7], v[170:173], v[208:211], v[4:7]
	v_mfma_f32_16x16x32_bf16 v[52:55], v[166:169], v[182:185], v[52:55]
	v_mfma_f32_16x16x32_bf16 v[44:47], v[174:177], v[182:185], v[44:47]
	v_mfma_f32_16x16x32_bf16 v[36:39], v[166:169], v[190:193], v[36:39]
	v_mfma_f32_16x16x32_bf16 v[28:31], v[174:177], v[190:193], v[28:31]
	v_mfma_f32_16x16x32_bf16 v[20:23], v[166:169], v[204:207], v[20:23]
	v_mfma_f32_16x16x32_bf16 v[12:15], v[174:177], v[204:207], v[12:15]
	v_mfma_f32_16x16x32_bf16 v[8:11], v[166:169], v[212:215], v[8:11]
	v_mfma_f32_16x16x32_bf16 v[4:7], v[174:177], v[212:215], v[4:7]
	s_barrier
	s_setprio 0
	s_movk_i32 s30, 0x100
	s_andn2_b64 vcc, exec, s[66:67]
	s_mov_b64 s[36:37], -1
	s_mov_b64 s[66:67], 0
	s_cbranch_vccz .LBB0_1186
	s_and_b64 vcc, exec, s[20:21]
	s_cbranch_vccz .LBB0_1189
	s_barrier

.LBB0_1273:
	s_add_i32 s74, s30, 2
	s_add_u32 s62, s36, 0x100
	s_addc_u32 s63, s37, 0
	s_add_i32 s0, 0, 0x10000
	s_cmp_eq_u32 s29, s30
	s_cselect_b32 s35, s43, s63
	s_cselect_b32 s34, s42, s62
	s_cselect_b32 s31, s45, s72
	s_cselect_b32 s30, s44, s69
	s_add_i32 s6, 0, 0x14000
	v_add_u32_e32 v144, s0, v3
	v_add_u32_e32 v160, s6, v3
	ds_read_b128 v[124:127], v144
	ds_read_b128 v[128:131], v144 offset:1024
	ds_read_b128 v[140:143], v144 offset:2048
	ds_read_b128 v[144:147], v144 offset:3072
	ds_read_b128 v[148:151], v160
	ds_read_b128 v[152:155], v160 offset:1024
	ds_read_b128 v[156:159], v160 offset:2048
	ds_read_b128 v[160:163], v160 offset:3072
	v_lshl_add_u64 v[198:199], s[36:37], 0, v[212:213]
	s_add_i32 m0, s33, 0xc000
	ds_read_b128 v[164:167], v250
	ds_read_b128 v[168:171], v250 offset:1024
	ds_read_b128 v[172:175], v250 offset:2048
	ds_read_b128 v[176:179], v250 offset:3072
	ds_read_b128 v[180:183], v250 offset:4096
	ds_read_b128 v[184:187], v250 offset:5120
	ds_read_b128 v[188:191], v250 offset:6144
	ds_read_b128 v[192:195], v250 offset:7168
	global_load_lds_dwordx4 v[198:199], off
	s_add_i32 m0, s33, 0xe000
	v_lshl_add_u64 v[198:199], s[36:37], 0, v[214:215]
	global_load_lds_dwordx4 v[198:199], off
	s_setprio 1
	s_waitcnt vmcnt(8) lgkmcnt(0)
	s_barrier
	v_mfma_f32_16x16x32_bf16 v[136:139], v[124:127], v[164:167], v[136:139]
	v_mfma_f32_16x16x32_bf16 v[132:135], v[140:143], v[164:167], v[132:135]
	v_mfma_f32_16x16x32_bf16 v[112:115], v[124:127], v[172:175], v[112:115]
	v_mfma_f32_16x16x32_bf16 v[108:111], v[140:143], v[172:175], v[108:111]
	v_mfma_f32_16x16x32_bf16 v[96:99], v[124:127], v[180:183], v[96:99]
	v_mfma_f32_16x16x32_bf16 v[92:95], v[140:143], v[180:183], v[92:95]
	v_mfma_f32_16x16x32_bf16 v[80:83], v[124:127], v[188:191], v[80:83]
	v_mfma_f32_16x16x32_bf16 v[76:79], v[140:143], v[188:191], v[76:79]
	v_mfma_f32_16x16x32_bf16 v[136:139], v[128:131], v[168:171], v[136:139]
	v_mfma_f32_16x16x32_bf16 v[132:135], v[144:147], v[168:171], v[132:135]
	v_mfma_f32_16x16x32_bf16 v[112:115], v[128:131], v[176:179], v[112:115]
	v_mfma_f32_16x16x32_bf16 v[108:111], v[144:147], v[176:179], v[108:111]
	v_mfma_f32_16x16x32_bf16 v[96:99], v[128:131], v[184:187], v[96:99]
	v_mfma_f32_16x16x32_bf16 v[92:95], v[144:147], v[184:187], v[92:95]
	v_mfma_f32_16x16x32_bf16 v[80:83], v[128:131], v[192:195], v[80:83]
	v_mfma_f32_16x16x32_bf16 v[76:79], v[144:147], v[192:195], v[76:79]
	s_setprio 0
	s_setprio 1
	v_mfma_f32_16x16x32_bf16 v[120:123], v[148:151], v[164:167], v[120:123]
	v_mfma_f32_16x16x32_bf16 v[116:119], v[156:159], v[164:167], v[116:119]
	v_mfma_f32_16x16x32_bf16 v[104:107], v[148:151], v[172:175], v[104:107]
	v_mfma_f32_16x16x32_bf16 v[100:103], v[156:159], v[172:175], v[100:103]
	v_mfma_f32_16x16x32_bf16 v[88:91], v[148:151], v[180:183], v[88:91]
	v_mfma_f32_16x16x32_bf16 v[84:87], v[156:159], v[180:183], v[84:87]
	v_mfma_f32_16x16x32_bf16 v[72:75], v[148:151], v[188:191], v[72:75]
	v_mfma_f32_16x16x32_bf16 v[68:71], v[156:159], v[188:191], v[68:71]
	v_mfma_f32_16x16x32_bf16 v[120:123], v[152:155], v[168:171], v[120:123]
	v_mfma_f32_16x16x32_bf16 v[116:119], v[160:163], v[168:171], v[116:119]
	v_mfma_f32_16x16x32_bf16 v[104:107], v[152:155], v[176:179], v[104:107]
	v_mfma_f32_16x16x32_bf16 v[100:103], v[160:163], v[176:179], v[100:103]
	v_mfma_f32_16x16x32_bf16 v[88:91], v[152:155], v[184:187], v[88:91]
	v_mfma_f32_16x16x32_bf16 v[84:87], v[160:163], v[184:187], v[84:87]
	v_mfma_f32_16x16x32_bf16 v[72:75], v[152:155], v[192:195], v[72:75]
	v_mfma_f32_16x16x32_bf16 v[68:71], v[160:163], v[192:195], v[68:71]
	s_barrier
	s_setprio 0
	s_add_i32 s0, s0, s27
	v_lshl_add_u64 v[198:199], s[30:31], 0, v[202:203]
	s_mov_b32 m0, s0
	ds_read_b128 v[164:167], v250 offset:16384
	ds_read_b128 v[168:171], v250 offset:17408
	ds_read_b128 v[172:175], v250 offset:18432
	ds_read_b128 v[176:179], v250 offset:19456
	ds_read_b128 v[180:183], v250 offset:20480
	ds_read_b128 v[184:187], v250 offset:21504
	ds_read_b128 v[188:191], v250 offset:22528
	ds_read_b128 v[192:195], v250 offset:23552
	global_load_lds_dwordx4 v[198:199], off
	s_add_i32 m0, s0, 0x2000
	s_add_u32 s36, s30, 0x204000
	v_lshl_add_u64 v[216:217], s[30:31], 0, v[206:207]
	s_addc_u32 s37, s31, 0
	s_add_i32 s0, s6, s27
	global_load_lds_dwordx4 v[216:217], off
	v_lshl_add_u64 v[218:219], s[36:37], 0, v[202:203]
	s_mov_b32 m0, s0
	global_load_lds_dwordx4 v[218:219], off
	s_add_i32 m0, s0, 0x2000
	v_lshl_add_u64 v[218:219], s[36:37], 0, v[206:207]
	global_load_lds_dwordx4 v[218:219], off
	s_mov_b32 m0, s33
	v_lshl_add_u64 v[218:219], s[34:35], 0, v[200:201]
	global_load_lds_dwordx4 v[218:219], off
	s_mov_b32 m0, s38
	v_lshl_add_u64 v[220:221], s[34:35], 0, v[204:205]
	global_load_lds_dwordx4 v[220:221], off
	s_setprio 1
	s_waitcnt vmcnt(8) lgkmcnt(0)
	s_barrier
	v_mfma_f32_16x16x32_bf16 v[64:67], v[124:127], v[164:167], v[64:67]
	v_mfma_f32_16x16x32_bf16 v[60:63], v[140:143], v[164:167], v[60:63]
	v_mfma_f32_16x16x32_bf16 v[48:51], v[124:127], v[172:175], v[48:51]
	v_mfma_f32_16x16x32_bf16 v[44:47], v[140:143], v[172:175], v[44:47]
	v_mfma_f32_16x16x32_bf16 v[32:35], v[124:127], v[180:183], v[32:35]
	v_mfma_f32_16x16x32_bf16 v[28:31], v[140:143], v[180:183], v[28:31]
	v_mfma_f32_16x16x32_bf16 v[16:19], v[124:127], v[188:191], v[16:19]
	v_mfma_f32_16x16x32_bf16 v[12:15], v[140:143], v[188:191], v[12:15]
	v_mfma_f32_16x16x32_bf16 v[64:67], v[128:131], v[168:171], v[64:67]
	v_mfma_f32_16x16x32_bf16 v[60:63], v[144:147], v[168:171], v[60:63]
	v_mfma_f32_16x16x32_bf16 v[48:51], v[128:131], v[176:179], v[48:51]
	v_mfma_f32_16x16x32_bf16 v[44:47], v[144:147], v[176:179], v[44:47]
	v_mfma_f32_16x16x32_bf16 v[32:35], v[128:131], v[184:187], v[32:35]
	v_mfma_f32_16x16x32_bf16 v[28:31], v[144:147], v[184:187], v[28:31]
	v_mfma_f32_16x16x32_bf16 v[16:19], v[128:131], v[192:195], v[16:19]
	v_mfma_f32_16x16x32_bf16 v[12:15], v[144:147], v[192:195], v[12:15]
	s_setprio 0
	s_setprio 1
	v_mfma_f32_16x16x32_bf16 v[56:59], v[148:151], v[164:167], v[56:59]
	v_mfma_f32_16x16x32_bf16 v[52:55], v[156:159], v[164:167], v[52:55]
	v_mfma_f32_16x16x32_bf16 v[40:43], v[148:151], v[172:175], v[40:43]
	v_mfma_f32_16x16x32_bf16 v[36:39], v[156:159], v[172:175], v[36:39]
	v_mfma_f32_16x16x32_bf16 v[24:27], v[148:151], v[180:183], v[24:27]
	v_mfma_f32_16x16x32_bf16 v[20:23], v[156:159], v[180:183], v[20:23]
	v_mfma_f32_16x16x32_bf16 v[8:11], v[148:151], v[188:191], v[8:11]
	v_mfma_f32_16x16x32_bf16 v[4:7], v[156:159], v[188:191], v[4:7]
	v_mfma_f32_16x16x32_bf16 v[56:59], v[152:155], v[168:171], v[56:59]
	v_mfma_f32_16x16x32_bf16 v[52:55], v[160:163], v[168:171], v[52:55]
	v_mfma_f32_16x16x32_bf16 v[40:43], v[152:155], v[176:179], v[40:43]
	v_mfma_f32_16x16x32_bf16 v[36:39], v[160:163], v[176:179], v[36:39]
	v_mfma_f32_16x16x32_bf16 v[24:27], v[152:155], v[184:187], v[24:27]
	v_mfma_f32_16x16x32_bf16 v[20:23], v[160:163], v[184:187], v[20:23]
	v_mfma_f32_16x16x32_bf16 v[8:11], v[152:155], v[192:195], v[8:11]
	v_mfma_f32_16x16x32_bf16 v[4:7], v[160:163], v[192:195], v[4:7]
	s_barrier
	s_setprio 0
	s_add_i32 s0, 0, 0x18000
	s_add_i32 s6, 0, 0x1c000
	v_add_u32_e32 v144, s0, v3
	v_add_u32_e32 v160, s6, v3
	ds_read_b128 v[124:127], v144
	ds_read_b128 v[128:131], v144 offset:1024
	ds_read_b128 v[140:143], v144 offset:2048
	ds_read_b128 v[144:147], v144 offset:3072
	ds_read_b128 v[148:151], v160
	ds_read_b128 v[152:155], v160 offset:1024
	ds_read_b128 v[156:159], v160 offset:2048
	ds_read_b128 v[160:163], v160 offset:3072
	s_add_u32 s34, s34, 0x204000
	s_addc_u32 s35, s35, 0
	s_mov_b32 m0, s39
	v_lshl_add_u64 v[222:223], s[34:35], 0, v[200:201]
	ds_read_b128 v[164:167], v250 offset:32768
	ds_read_b128 v[168:171], v250 offset:33792
	ds_read_b128 v[172:175], v250 offset:34816
	ds_read_b128 v[176:179], v250 offset:35840
	ds_read_b128 v[180:183], v250 offset:36864
	ds_read_b128 v[184:187], v250 offset:37888
	ds_read_b128 v[188:191], v250 offset:38912
	ds_read_b128 v[192:195], v250 offset:39936
	global_load_lds_dwordx4 v[222:223], off
	s_mov_b32 m0, s40
	v_lshl_add_u64 v[222:223], s[34:35], 0, v[204:205]
	global_load_lds_dwordx4 v[222:223], off
	s_setprio 1
	s_waitcnt vmcnt(8) lgkmcnt(0)
	s_barrier
	v_mfma_f32_16x16x32_bf16 v[136:139], v[124:127], v[164:167], v[136:139]
	v_mfma_f32_16x16x32_bf16 v[132:135], v[140:143], v[164:167], v[132:135]
	v_mfma_f32_16x16x32_bf16 v[112:115], v[124:127], v[172:175], v[112:115]
	v_mfma_f32_16x16x32_bf16 v[108:111], v[140:143], v[172:175], v[108:111]
	v_mfma_f32_16x16x32_bf16 v[96:99], v[124:127], v[180:183], v[96:99]
	v_mfma_f32_16x16x32_bf16 v[92:95], v[140:143], v[180:183], v[92:95]
	v_mfma_f32_16x16x32_bf16 v[80:83], v[124:127], v[188:191], v[80:83]
	v_mfma_f32_16x16x32_bf16 v[76:79], v[140:143], v[188:191], v[76:79]
	v_mfma_f32_16x16x32_bf16 v[136:139], v[128:131], v[168:171], v[136:139]
	v_mfma_f32_16x16x32_bf16 v[132:135], v[144:147], v[168:171], v[132:135]
	v_mfma_f32_16x16x32_bf16 v[112:115], v[128:131], v[176:179], v[112:115]
	v_mfma_f32_16x16x32_bf16 v[108:111], v[144:147], v[176:179], v[108:111]
	v_mfma_f32_16x16x32_bf16 v[96:99], v[128:131], v[184:187], v[96:99]
	v_mfma_f32_16x16x32_bf16 v[92:95], v[144:147], v[184:187], v[92:95]
	v_mfma_f32_16x16x32_bf16 v[80:83], v[128:131], v[192:195], v[80:83]
	v_mfma_f32_16x16x32_bf16 v[76:79], v[144:147], v[192:195], v[76:79]
	s_setprio 0
	s_setprio 1
	v_mfma_f32_16x16x32_bf16 v[120:123], v[148:151], v[164:167], v[120:123]
	v_mfma_f32_16x16x32_bf16 v[116:119], v[156:159], v[164:167], v[116:119]
	v_mfma_f32_16x16x32_bf16 v[104:107], v[148:151], v[172:175], v[104:107]
	v_mfma_f32_16x16x32_bf16 v[100:103], v[156:159], v[172:175], v[100:103]
	v_mfma_f32_16x16x32_bf16 v[88:91], v[148:151], v[180:183], v[88:91]
	v_mfma_f32_16x16x32_bf16 v[84:87], v[156:159], v[180:183], v[84:87]
	v_mfma_f32_16x16x32_bf16 v[72:75], v[148:151], v[188:191], v[72:75]
	v_mfma_f32_16x16x32_bf16 v[68:71], v[156:159], v[188:191], v[68:71]
	v_mfma_f32_16x16x32_bf16 v[120:123], v[152:155], v[168:171], v[120:123]
	v_mfma_f32_16x16x32_bf16 v[116:119], v[160:163], v[168:171], v[116:119]
	v_mfma_f32_16x16x32_bf16 v[104:107], v[152:155], v[176:179], v[104:107]
	v_mfma_f32_16x16x32_bf16 v[100:103], v[160:163], v[176:179], v[100:103]
	v_mfma_f32_16x16x32_bf16 v[88:91], v[152:155], v[184:187], v[88:91]
	v_mfma_f32_16x16x32_bf16 v[84:87], v[160:163], v[184:187], v[84:87]
	v_mfma_f32_16x16x32_bf16 v[72:75], v[152:155], v[192:195], v[72:75]
	v_mfma_f32_16x16x32_bf16 v[68:71], v[160:163], v[192:195], v[68:71]
	s_barrier
	s_setprio 0
	s_add_i32 s0, s0, s27
	v_lshl_add_u64 v[198:199], v[198:199], 0, s[90:91]
	s_mov_b32 m0, s0
	ds_read_b128 v[164:167], v250 offset:49152
	ds_read_b128 v[168:171], v250 offset:50176
	ds_read_b128 v[172:175], v250 offset:51200
	ds_read_b128 v[176:179], v250 offset:52224
	ds_read_b128 v[180:183], v250 offset:53248
	ds_read_b128 v[184:187], v250 offset:54272
	ds_read_b128 v[188:191], v250 offset:55296
	ds_read_b128 v[192:195], v250 offset:56320
	global_load_lds_dwordx4 v[198:199], off
	s_add_i32 m0, s0, 0x2000
	s_add_u32 s30, s30, 0x204080
	v_lshl_add_u64 v[198:199], v[216:217], 0, s[90:91]
	s_addc_u32 s31, s31, 0
	s_add_i32 s0, s6, s27
	global_load_lds_dwordx4 v[198:199], off
	s_mov_b32 m0, s0
	v_lshl_add_u64 v[198:199], s[30:31], 0, v[202:203]
	global_load_lds_dwordx4 v[198:199], off
	s_add_i32 m0, s0, 0x2000
	v_lshl_add_u64 v[198:199], s[30:31], 0, v[206:207]
	global_load_lds_dwordx4 v[198:199], off
	s_mov_b32 m0, s50
	v_lshl_add_u64 v[198:199], v[218:219], 0, s[90:91]
	global_load_lds_dwordx4 v[198:199], off
	s_mov_b32 m0, s51
	v_lshl_add_u64 v[198:199], v[220:221], 0, s[90:91]
	global_load_lds_dwordx4 v[198:199], off
	s_setprio 1
	s_waitcnt vmcnt(8) lgkmcnt(0)
	s_barrier
	v_mfma_f32_16x16x32_bf16 v[64:67], v[124:127], v[164:167], v[64:67]
	v_mfma_f32_16x16x32_bf16 v[60:63], v[140:143], v[164:167], v[60:63]
	v_mfma_f32_16x16x32_bf16 v[48:51], v[124:127], v[172:175], v[48:51]
	v_mfma_f32_16x16x32_bf16 v[44:47], v[140:143], v[172:175], v[44:47]
	v_mfma_f32_16x16x32_bf16 v[32:35], v[124:127], v[180:183], v[32:35]
	v_mfma_f32_16x16x32_bf16 v[28:31], v[140:143], v[180:183], v[28:31]
	v_mfma_f32_16x16x32_bf16 v[16:19], v[124:127], v[188:191], v[16:19]
	v_mfma_f32_16x16x32_bf16 v[12:15], v[140:143], v[188:191], v[12:15]
	v_mfma_f32_16x16x32_bf16 v[64:67], v[128:131], v[168:171], v[64:67]
	v_mfma_f32_16x16x32_bf16 v[60:63], v[144:147], v[168:171], v[60:63]
	v_mfma_f32_16x16x32_bf16 v[48:51], v[128:131], v[176:179], v[48:51]
	v_mfma_f32_16x16x32_bf16 v[44:47], v[144:147], v[176:179], v[44:47]
	v_mfma_f32_16x16x32_bf16 v[32:35], v[128:131], v[184:187], v[32:35]
	v_mfma_f32_16x16x32_bf16 v[28:31], v[144:147], v[184:187], v[28:31]
	v_mfma_f32_16x16x32_bf16 v[16:19], v[128:131], v[192:195], v[16:19]
	v_mfma_f32_16x16x32_bf16 v[12:15], v[144:147], v[192:195], v[12:15]
	s_setprio 0
	s_setprio 1
	v_mfma_f32_16x16x32_bf16 v[56:59], v[148:151], v[164:167], v[56:59]
	v_mfma_f32_16x16x32_bf16 v[52:55], v[156:159], v[164:167], v[52:55]
	v_mfma_f32_16x16x32_bf16 v[40:43], v[148:151], v[172:175], v[40:43]
	v_mfma_f32_16x16x32_bf16 v[36:39], v[156:159], v[172:175], v[36:39]
	v_mfma_f32_16x16x32_bf16 v[24:27], v[148:151], v[180:183], v[24:27]
	v_mfma_f32_16x16x32_bf16 v[20:23], v[156:159], v[180:183], v[20:23]
	v_mfma_f32_16x16x32_bf16 v[8:11], v[148:151], v[188:191], v[8:11]
	v_mfma_f32_16x16x32_bf16 v[4:7], v[156:159], v[188:191], v[4:7]
	v_mfma_f32_16x16x32_bf16 v[56:59], v[152:155], v[168:171], v[56:59]
	v_mfma_f32_16x16x32_bf16 v[52:55], v[160:163], v[168:171], v[52:55]
	v_mfma_f32_16x16x32_bf16 v[40:43], v[152:155], v[176:179], v[40:43]
	v_mfma_f32_16x16x32_bf16 v[36:39], v[160:163], v[176:179], v[36:39]
	v_mfma_f32_16x16x32_bf16 v[24:27], v[152:155], v[184:187], v[24:27]
	v_mfma_f32_16x16x32_bf16 v[20:23], v[160:163], v[184:187], v[20:23]
	v_mfma_f32_16x16x32_bf16 v[8:11], v[152:155], v[192:195], v[8:11]
	v_mfma_f32_16x16x32_bf16 v[4:7], v[160:163], v[192:195], v[4:7]
	s_barrier
	s_setprio 0
	s_add_u32 s69, s69, 0x100
	s_addc_u32 s72, s72, 0
	s_cmp_ge_i32 s74, s61
	s_mov_b64 s[36:37], s[62:63]
	s_mov_b32 s30, s74
	s_cbranch_scc0 .LBB0_1273
	s_and_b64 vcc, exec, s[22:23]
	s_cbranch_vccz .LBB0_1276
	s_barrier

.LBB0_1395:
	s_add_u32 s0, s36, 0xfff80080
	s_addc_u32 s6, s37, -1
	s_add_i32 s49, 0, 0x10000
	s_cmp_eq_u32 s67, 28
	s_cselect_b32 s35, s25, s6
	s_cselect_b32 s34, s33, s0
	s_cselect_b32 s31, s43, s39
	s_cselect_b32 s30, s45, s38
	s_add_i32 s0, 0, 0x14000
	v_add_u32_e32 v144, s49, v3
	v_add_u32_e32 v176, s0, v3
	ds_read_b128 v[132:135], v144
	ds_read_b128 v[136:139], v144 offset:1024
	ds_read_b128 v[140:143], v144 offset:2048
	ds_read_b128 v[144:147], v144 offset:3072
	ds_read_b128 v[164:167], v176
	ds_read_b128 v[168:171], v176 offset:1024
	ds_read_b128 v[172:175], v176 offset:2048
	ds_read_b128 v[176:179], v176 offset:3072
	v_lshl_add_u64 v[198:199], s[36:37], 0, v[160:161]
	s_add_i32 m0, s47, 0xc000
	ds_read_b128 v[180:183], v190
	ds_read_b128 v[184:187], v190 offset:1024
	ds_read_b128 v[192:195], v190 offset:2048
	ds_read_b128 v[200:203], v190 offset:3072
	ds_read_b128 v[204:207], v190 offset:4096
	ds_read_b128 v[208:211], v190 offset:5120
	ds_read_b128 v[212:215], v190 offset:6144
	ds_read_b128 v[216:219], v190 offset:7168
	global_load_lds_dwordx4 v[198:199], off
	s_add_i32 m0, s47, 0xe000
	v_lshl_add_u64 v[198:199], s[36:37], 0, v[162:163]
	global_load_lds_dwordx4 v[198:199], off
	s_setprio 1
	s_waitcnt vmcnt(8) lgkmcnt(0)
	s_barrier
	v_mfma_f32_16x16x32_bf16 v[128:131], v[132:135], v[180:183], v[128:131]
	v_mfma_f32_16x16x32_bf16 v[124:127], v[140:143], v[180:183], v[124:127]
	v_mfma_f32_16x16x32_bf16 v[112:115], v[132:135], v[192:195], v[112:115]
	v_mfma_f32_16x16x32_bf16 v[108:111], v[140:143], v[192:195], v[108:111]
	v_mfma_f32_16x16x32_bf16 v[96:99], v[132:135], v[204:207], v[96:99]
	v_mfma_f32_16x16x32_bf16 v[92:95], v[140:143], v[204:207], v[92:95]
	v_mfma_f32_16x16x32_bf16 v[80:83], v[132:135], v[212:215], v[80:83]
	v_mfma_f32_16x16x32_bf16 v[76:79], v[140:143], v[212:215], v[76:79]
	v_mfma_f32_16x16x32_bf16 v[128:131], v[136:139], v[184:187], v[128:131]
	v_mfma_f32_16x16x32_bf16 v[124:127], v[144:147], v[184:187], v[124:127]
	v_mfma_f32_16x16x32_bf16 v[112:115], v[136:139], v[200:203], v[112:115]
	v_mfma_f32_16x16x32_bf16 v[108:111], v[144:147], v[200:203], v[108:111]
	v_mfma_f32_16x16x32_bf16 v[96:99], v[136:139], v[208:211], v[96:99]
	v_mfma_f32_16x16x32_bf16 v[92:95], v[144:147], v[208:211], v[92:95]
	v_mfma_f32_16x16x32_bf16 v[80:83], v[136:139], v[216:219], v[80:83]
	v_mfma_f32_16x16x32_bf16 v[76:79], v[144:147], v[216:219], v[76:79]
	s_setprio 0
	s_setprio 1
	v_mfma_f32_16x16x32_bf16 v[120:123], v[164:167], v[180:183], v[120:123]
	v_mfma_f32_16x16x32_bf16 v[116:119], v[172:175], v[180:183], v[116:119]
	v_mfma_f32_16x16x32_bf16 v[104:107], v[164:167], v[192:195], v[104:107]
	v_mfma_f32_16x16x32_bf16 v[100:103], v[172:175], v[192:195], v[100:103]
	v_mfma_f32_16x16x32_bf16 v[88:91], v[164:167], v[204:207], v[88:91]
	v_mfma_f32_16x16x32_bf16 v[84:87], v[172:175], v[204:207], v[84:87]
	v_mfma_f32_16x16x32_bf16 v[72:75], v[164:167], v[212:215], v[72:75]
	v_mfma_f32_16x16x32_bf16 v[68:71], v[172:175], v[212:215], v[68:71]
	v_mfma_f32_16x16x32_bf16 v[120:123], v[168:171], v[184:187], v[120:123]
	v_mfma_f32_16x16x32_bf16 v[116:119], v[176:179], v[184:187], v[116:119]
	v_mfma_f32_16x16x32_bf16 v[104:107], v[168:171], v[200:203], v[104:107]
	v_mfma_f32_16x16x32_bf16 v[100:103], v[176:179], v[200:203], v[100:103]
	v_mfma_f32_16x16x32_bf16 v[88:91], v[168:171], v[208:211], v[88:91]
	v_mfma_f32_16x16x32_bf16 v[84:87], v[176:179], v[208:211], v[84:87]
	v_mfma_f32_16x16x32_bf16 v[72:75], v[168:171], v[216:219], v[72:75]
	v_mfma_f32_16x16x32_bf16 v[68:71], v[176:179], v[216:219], v[68:71]
	s_barrier
	s_setprio 0
	s_add_i32 s6, s49, s4
	v_lshl_add_u64 v[198:199], s[30:31], 0, v[152:153]
	s_mov_b32 m0, s6
	ds_read_b128 v[180:183], v190 offset:16384
	ds_read_b128 v[184:187], v190 offset:17408
	ds_read_b128 v[192:195], v190 offset:18432
	ds_read_b128 v[200:203], v190 offset:19456
	ds_read_b128 v[204:207], v190 offset:20480
	ds_read_b128 v[208:211], v190 offset:21504
	ds_read_b128 v[212:215], v190 offset:22528
	ds_read_b128 v[216:219], v190 offset:23552
	global_load_lds_dwordx4 v[198:199], off
	s_add_i32 m0, s6, 0x2000
	s_add_u32 s68, s30, 0x80000
	v_lshl_add_u64 v[220:221], s[30:31], 0, v[148:149]
	s_addc_u32 s69, s31, 0
	s_add_i32 s0, s0, s4
	global_load_lds_dwordx4 v[220:221], off
	v_lshl_add_u64 v[222:223], s[68:69], 0, v[152:153]
	s_mov_b32 m0, s0
	global_load_lds_dwordx4 v[222:223], off
	s_add_i32 m0, s0, 0x2000
	v_lshl_add_u64 v[222:223], s[68:69], 0, v[148:149]
	global_load_lds_dwordx4 v[222:223], off
	s_mov_b32 m0, s47
	v_lshl_add_u64 v[222:223], s[34:35], 0, v[154:155]
	global_load_lds_dwordx4 v[222:223], off
	s_mov_b32 m0, s52
	v_lshl_add_u64 v[224:225], s[34:35], 0, v[150:151]
	global_load_lds_dwordx4 v[224:225], off
	s_setprio 1
	s_waitcnt vmcnt(8) lgkmcnt(0)
	s_barrier
	v_mfma_f32_16x16x32_bf16 v[64:67], v[132:135], v[180:183], v[64:67]
	v_mfma_f32_16x16x32_bf16 v[60:63], v[140:143], v[180:183], v[60:63]
	v_mfma_f32_16x16x32_bf16 v[48:51], v[132:135], v[192:195], v[48:51]
	v_mfma_f32_16x16x32_bf16 v[44:47], v[140:143], v[192:195], v[44:47]
	v_mfma_f32_16x16x32_bf16 v[32:35], v[132:135], v[204:207], v[32:35]
	v_mfma_f32_16x16x32_bf16 v[28:31], v[140:143], v[204:207], v[28:31]
	v_mfma_f32_16x16x32_bf16 v[16:19], v[132:135], v[212:215], v[16:19]
	v_mfma_f32_16x16x32_bf16 v[12:15], v[140:143], v[212:215], v[12:15]
	v_mfma_f32_16x16x32_bf16 v[64:67], v[136:139], v[184:187], v[64:67]
	v_mfma_f32_16x16x32_bf16 v[60:63], v[144:147], v[184:187], v[60:63]
	v_mfma_f32_16x16x32_bf16 v[48:51], v[136:139], v[200:203], v[48:51]
	v_mfma_f32_16x16x32_bf16 v[44:47], v[144:147], v[200:203], v[44:47]
	v_mfma_f32_16x16x32_bf16 v[32:35], v[136:139], v[208:211], v[32:35]
	v_mfma_f32_16x16x32_bf16 v[28:31], v[144:147], v[208:211], v[28:31]
	v_mfma_f32_16x16x32_bf16 v[16:19], v[136:139], v[216:219], v[16:19]
	v_mfma_f32_16x16x32_bf16 v[12:15], v[144:147], v[216:219], v[12:15]
	s_setprio 0
	s_setprio 1
	v_mfma_f32_16x16x32_bf16 v[56:59], v[164:167], v[180:183], v[56:59]
	v_mfma_f32_16x16x32_bf16 v[52:55], v[172:175], v[180:183], v[52:55]
	v_mfma_f32_16x16x32_bf16 v[40:43], v[164:167], v[192:195], v[40:43]
	v_mfma_f32_16x16x32_bf16 v[36:39], v[172:175], v[192:195], v[36:39]
	v_mfma_f32_16x16x32_bf16 v[24:27], v[164:167], v[204:207], v[24:27]
	v_mfma_f32_16x16x32_bf16 v[20:23], v[172:175], v[204:207], v[20:23]
	v_mfma_f32_16x16x32_bf16 v[8:11], v[164:167], v[212:215], v[8:11]
	v_mfma_f32_16x16x32_bf16 v[4:7], v[172:175], v[212:215], v[4:7]
	v_mfma_f32_16x16x32_bf16 v[56:59], v[168:171], v[184:187], v[56:59]
	v_mfma_f32_16x16x32_bf16 v[52:55], v[176:179], v[184:187], v[52:55]
	v_mfma_f32_16x16x32_bf16 v[40:43], v[168:171], v[200:203], v[40:43]
	v_mfma_f32_16x16x32_bf16 v[36:39], v[176:179], v[200:203], v[36:39]
	v_mfma_f32_16x16x32_bf16 v[24:27], v[168:171], v[208:211], v[24:27]
	v_mfma_f32_16x16x32_bf16 v[20:23], v[176:179], v[208:211], v[20:23]
	v_mfma_f32_16x16x32_bf16 v[8:11], v[168:171], v[216:219], v[8:11]
	v_mfma_f32_16x16x32_bf16 v[4:7], v[176:179], v[216:219], v[4:7]
	s_barrier
	s_setprio 0
	s_add_i32 s0, 0, 0x18000
	s_add_i32 s6, 0, 0x1c000
	v_add_u32_e32 v144, s0, v3
	v_add_u32_e32 v176, s6, v3
	ds_read_b128 v[132:135], v144
	ds_read_b128 v[136:139], v144 offset:1024
	ds_read_b128 v[140:143], v144 offset:2048
	ds_read_b128 v[144:147], v144 offset:3072
	ds_read_b128 v[164:167], v176
	ds_read_b128 v[168:171], v176 offset:1024
	ds_read_b128 v[172:175], v176 offset:2048
	ds_read_b128 v[176:179], v176 offset:3072
	s_add_u32 s34, s34, 0x80000
	s_addc_u32 s35, s35, 0
	s_mov_b32 m0, s53
	v_lshl_add_u64 v[226:227], s[34:35], 0, v[154:155]
	ds_read_b128 v[180:183], v190 offset:32768
	ds_read_b128 v[184:187], v190 offset:33792
	ds_read_b128 v[192:195], v190 offset:34816
	ds_read_b128 v[200:203], v190 offset:35840
	ds_read_b128 v[204:207], v190 offset:36864
	ds_read_b128 v[208:211], v190 offset:37888
	ds_read_b128 v[212:215], v190 offset:38912
	ds_read_b128 v[216:219], v190 offset:39936
	global_load_lds_dwordx4 v[226:227], off
	s_mov_b32 m0, s59
	v_lshl_add_u64 v[226:227], s[34:35], 0, v[150:151]
	global_load_lds_dwordx4 v[226:227], off
	s_setprio 1
	s_waitcnt vmcnt(8) lgkmcnt(0)
	s_barrier
	v_mfma_f32_16x16x32_bf16 v[128:131], v[132:135], v[180:183], v[128:131]
	v_mfma_f32_16x16x32_bf16 v[124:127], v[140:143], v[180:183], v[124:127]
	v_mfma_f32_16x16x32_bf16 v[112:115], v[132:135], v[192:195], v[112:115]
	v_mfma_f32_16x16x32_bf16 v[108:111], v[140:143], v[192:195], v[108:111]
	v_mfma_f32_16x16x32_bf16 v[96:99], v[132:135], v[204:207], v[96:99]
	v_mfma_f32_16x16x32_bf16 v[92:95], v[140:143], v[204:207], v[92:95]
	v_mfma_f32_16x16x32_bf16 v[80:83], v[132:135], v[212:215], v[80:83]
	v_mfma_f32_16x16x32_bf16 v[76:79], v[140:143], v[212:215], v[76:79]
	v_mfma_f32_16x16x32_bf16 v[128:131], v[136:139], v[184:187], v[128:131]
	v_mfma_f32_16x16x32_bf16 v[124:127], v[144:147], v[184:187], v[124:127]
	v_mfma_f32_16x16x32_bf16 v[112:115], v[136:139], v[200:203], v[112:115]
	v_mfma_f32_16x16x32_bf16 v[108:111], v[144:147], v[200:203], v[108:111]
	v_mfma_f32_16x16x32_bf16 v[96:99], v[136:139], v[208:211], v[96:99]
	v_mfma_f32_16x16x32_bf16 v[92:95], v[144:147], v[208:211], v[92:95]
	v_mfma_f32_16x16x32_bf16 v[80:83], v[136:139], v[216:219], v[80:83]
	v_mfma_f32_16x16x32_bf16 v[76:79], v[144:147], v[216:219], v[76:79]
	s_setprio 0
	s_setprio 1
	v_mfma_f32_16x16x32_bf16 v[120:123], v[164:167], v[180:183], v[120:123]
	v_mfma_f32_16x16x32_bf16 v[116:119], v[172:175], v[180:183], v[116:119]
	v_mfma_f32_16x16x32_bf16 v[104:107], v[164:167], v[192:195], v[104:107]
	v_mfma_f32_16x16x32_bf16 v[100:103], v[172:175], v[192:195], v[100:103]
	v_mfma_f32_16x16x32_bf16 v[88:91], v[164:167], v[204:207], v[88:91]
	v_mfma_f32_16x16x32_bf16 v[84:87], v[172:175], v[204:207], v[84:87]
	v_mfma_f32_16x16x32_bf16 v[72:75], v[164:167], v[212:215], v[72:75]
	v_mfma_f32_16x16x32_bf16 v[68:71], v[172:175], v[212:215], v[68:71]
	v_mfma_f32_16x16x32_bf16 v[120:123], v[168:171], v[184:187], v[120:123]
	v_mfma_f32_16x16x32_bf16 v[116:119], v[176:179], v[184:187], v[116:119]
	v_mfma_f32_16x16x32_bf16 v[104:107], v[168:171], v[200:203], v[104:107]
	v_mfma_f32_16x16x32_bf16 v[100:103], v[176:179], v[200:203], v[100:103]
	v_mfma_f32_16x16x32_bf16 v[88:91], v[168:171], v[208:211], v[88:91]
	v_mfma_f32_16x16x32_bf16 v[84:87], v[176:179], v[208:211], v[84:87]
	v_mfma_f32_16x16x32_bf16 v[72:75], v[168:171], v[216:219], v[72:75]
	v_mfma_f32_16x16x32_bf16 v[68:71], v[176:179], v[216:219], v[68:71]
	s_barrier
	s_setprio 0
	s_add_i32 s0, s0, s4
	v_lshl_add_u64 v[198:199], v[198:199], 0, s[90:91]
	s_mov_b32 m0, s0
	ds_read_b128 v[180:183], v190 offset:49152
	ds_read_b128 v[184:187], v190 offset:50176
	ds_read_b128 v[192:195], v190 offset:51200
	ds_read_b128 v[200:203], v190 offset:52224
	ds_read_b128 v[204:207], v190 offset:53248
	ds_read_b128 v[208:211], v190 offset:54272
	ds_read_b128 v[212:215], v190 offset:55296
	ds_read_b128 v[216:219], v190 offset:56320
	global_load_lds_dwordx4 v[198:199], off
	s_add_i32 m0, s0, 0x2000
	s_add_u32 s30, s30, 0x80080
	v_lshl_add_u64 v[198:199], v[220:221], 0, s[90:91]
	s_addc_u32 s31, s31, 0
	s_add_i32 s0, s6, s4
	global_load_lds_dwordx4 v[198:199], off
	s_mov_b32 m0, s0
	v_lshl_add_u64 v[198:199], s[30:31], 0, v[152:153]
	global_load_lds_dwordx4 v[198:199], off
	s_add_i32 m0, s0, 0x2000
	v_lshl_add_u64 v[198:199], s[30:31], 0, v[148:149]
	global_load_lds_dwordx4 v[198:199], off
	s_mov_b32 m0, s40
	v_lshl_add_u64 v[198:199], v[222:223], 0, s[90:91]
	global_load_lds_dwordx4 v[198:199], off
	s_mov_b32 m0, s66
	v_lshl_add_u64 v[198:199], v[224:225], 0, s[90:91]
	global_load_lds_dwordx4 v[198:199], off
	s_setprio 1
	s_waitcnt vmcnt(8) lgkmcnt(0)
	s_barrier
	v_mfma_f32_16x16x32_bf16 v[64:67], v[132:135], v[180:183], v[64:67]
	v_mfma_f32_16x16x32_bf16 v[60:63], v[140:143], v[180:183], v[60:63]
	v_mfma_f32_16x16x32_bf16 v[48:51], v[132:135], v[192:195], v[48:51]
	v_mfma_f32_16x16x32_bf16 v[44:47], v[140:143], v[192:195], v[44:47]
	v_mfma_f32_16x16x32_bf16 v[32:35], v[132:135], v[204:207], v[32:35]
	v_mfma_f32_16x16x32_bf16 v[28:31], v[140:143], v[204:207], v[28:31]
	v_mfma_f32_16x16x32_bf16 v[16:19], v[132:135], v[212:215], v[16:19]
	v_mfma_f32_16x16x32_bf16 v[12:15], v[140:143], v[212:215], v[12:15]
	v_mfma_f32_16x16x32_bf16 v[64:67], v[136:139], v[184:187], v[64:67]
	v_mfma_f32_16x16x32_bf16 v[60:63], v[144:147], v[184:187], v[60:63]
	v_mfma_f32_16x16x32_bf16 v[48:51], v[136:139], v[200:203], v[48:51]
	v_mfma_f32_16x16x32_bf16 v[44:47], v[144:147], v[200:203], v[44:47]
	v_mfma_f32_16x16x32_bf16 v[32:35], v[136:139], v[208:211], v[32:35]
	v_mfma_f32_16x16x32_bf16 v[28:31], v[144:147], v[208:211], v[28:31]
	v_mfma_f32_16x16x32_bf16 v[16:19], v[136:139], v[216:219], v[16:19]
	v_mfma_f32_16x16x32_bf16 v[12:15], v[144:147], v[216:219], v[12:15]
	s_setprio 0
	s_setprio 1
	v_mfma_f32_16x16x32_bf16 v[56:59], v[164:167], v[180:183], v[56:59]
	v_mfma_f32_16x16x32_bf16 v[52:55], v[172:175], v[180:183], v[52:55]
	v_mfma_f32_16x16x32_bf16 v[40:43], v[164:167], v[192:195], v[40:43]
	v_mfma_f32_16x16x32_bf16 v[36:39], v[172:175], v[192:195], v[36:39]
	v_mfma_f32_16x16x32_bf16 v[24:27], v[164:167], v[204:207], v[24:27]
	v_mfma_f32_16x16x32_bf16 v[20:23], v[172:175], v[204:207], v[20:23]
	v_mfma_f32_16x16x32_bf16 v[8:11], v[164:167], v[212:215], v[8:11]
	v_mfma_f32_16x16x32_bf16 v[4:7], v[172:175], v[212:215], v[4:7]
	v_mfma_f32_16x16x32_bf16 v[56:59], v[168:171], v[184:187], v[56:59]
	v_mfma_f32_16x16x32_bf16 v[52:55], v[176:179], v[184:187], v[52:55]
	v_mfma_f32_16x16x32_bf16 v[40:43], v[168:171], v[200:203], v[40:43]
	v_mfma_f32_16x16x32_bf16 v[36:39], v[176:179], v[200:203], v[36:39]
	v_mfma_f32_16x16x32_bf16 v[24:27], v[168:171], v[208:211], v[24:27]
	v_mfma_f32_16x16x32_bf16 v[20:23], v[176:179], v[208:211], v[20:23]
	v_mfma_f32_16x16x32_bf16 v[8:11], v[168:171], v[216:219], v[8:11]
	v_mfma_f32_16x16x32_bf16 v[4:7], v[176:179], v[216:219], v[4:7]
	s_barrier
	s_setprio 0
	s_add_i32 s67, s67, 2
	s_add_u32 s36, s36, 0x100
	s_addc_u32 s37, s37, 0
	s_add_u32 s38, s38, 0x100
	s_addc_u32 s39, s39, 0
	s_cmp_gt_u32 s67, 29
	s_cbranch_scc0 .LBB0_1395
	s_and_b64 vcc, exec, s[28:29]
	s_cbranch_vccz .LBB0_1398
	s_barrier

.LBB0_1441:
	s_add_u32 s0, s62, s30
	s_addc_u32 s6, s63, 0
	s_add_u32 s31, s0, 0x100
	s_addc_u32 s46, s6, 0
	s_and_b64 s[34:35], s[38:39], exec
	s_cselect_b32 s53, s43, s46
	s_cselect_b32 s52, s75, s31
	s_add_u32 s30, s66, s30
	s_addc_u32 s31, s67, 0
	s_add_u32 s34, s30, 0x100
	s_addc_u32 s35, s31, 0
	s_add_i32 s83, 0, 0x10000
	s_and_b64 s[30:31], s[38:39], exec
	s_cselect_b32 s31, s45, s35
	s_cselect_b32 s30, s81, s34
	s_add_i32 s39, 0, 0x14000
	s_add_u32 s46, s0, 0x80080
	s_addc_u32 s47, s6, 0
	s_add_i32 s49, s83, s4
	s_add_i32 m0, s59, 0xc000
	s_add_i32 s97, s59, 0xe000
	s_add_i32 s82, s49, 0x2000
	s_add_u32 s34, s30, 0x80000
	v_add_u32_e32 v144, s83, v3
	v_add_u32_e32 v172, s39, v3
	s_addc_u32 s35, s31, 0
	s_add_i32 s85, s39, s4
	ds_read_b128 v[132:135], v144
	ds_read_b128 v[136:139], v144 offset:1024
	ds_read_b128 v[140:143], v144 offset:2048
	ds_read_b128 v[144:147], v144 offset:3072
	ds_read_b128 v[160:163], v172
	ds_read_b128 v[164:167], v172 offset:1024
	ds_read_b128 v[168:171], v172 offset:2048
	ds_read_b128 v[172:175], v172 offset:3072
	s_add_i32 s84, s85, 0x2000
	s_add_i32 s0, 0, 0x18000
	s_add_i32 s54, 0, 0x1c000
	s_add_u32 vcc_lo, s52, 0x80000
	s_addc_u32 vcc_hi, s53, 0
	s_add_i32 s73, s0, s4
	s_add_i32 s6, s73, 0x2000
	s_add_u32 s38, s30, 0x80080
	s_addc_u32 s39, s31, 0
	s_add_i32 s83, s54, s4
	s_add_i32 s96, s83, 0x2000
	v_lshl_add_u64 v[198:199], s[46:47], 0, v[154:155]
	ds_read_b128 v[176:179], v186
	ds_read_b128 v[180:183], v186 offset:1024
	ds_read_b128 v[188:191], v186 offset:2048
	ds_read_b128 v[192:195], v186 offset:3072
	ds_read_b128 v[200:203], v186 offset:4096
	ds_read_b128 v[204:207], v186 offset:5120
	ds_read_b128 v[208:211], v186 offset:6144
	ds_read_b128 v[212:215], v186 offset:7168
	global_load_lds_dwordx4 v[198:199], off
	s_mov_b32 m0, s97
	v_lshl_add_u64 v[198:199], s[46:47], 0, v[150:151]
	global_load_lds_dwordx4 v[198:199], off
	s_setprio 1
	s_waitcnt vmcnt(8) lgkmcnt(0)
	s_barrier
	v_mfma_f32_16x16x32_bf16 v[128:131], v[132:135], v[176:179], v[128:131]
	v_mfma_f32_16x16x32_bf16 v[124:127], v[140:143], v[176:179], v[124:127]
	v_mfma_f32_16x16x32_bf16 v[112:115], v[132:135], v[188:191], v[112:115]
	v_mfma_f32_16x16x32_bf16 v[108:111], v[140:143], v[188:191], v[108:111]
	v_mfma_f32_16x16x32_bf16 v[96:99], v[132:135], v[200:203], v[96:99]
	v_mfma_f32_16x16x32_bf16 v[92:95], v[140:143], v[200:203], v[92:95]
	v_mfma_f32_16x16x32_bf16 v[80:83], v[132:135], v[208:211], v[80:83]
	v_mfma_f32_16x16x32_bf16 v[76:79], v[140:143], v[208:211], v[76:79]
	v_mfma_f32_16x16x32_bf16 v[128:131], v[136:139], v[180:183], v[128:131]
	v_mfma_f32_16x16x32_bf16 v[124:127], v[144:147], v[180:183], v[124:127]
	v_mfma_f32_16x16x32_bf16 v[112:115], v[136:139], v[192:195], v[112:115]
	v_mfma_f32_16x16x32_bf16 v[108:111], v[144:147], v[192:195], v[108:111]
	v_mfma_f32_16x16x32_bf16 v[96:99], v[136:139], v[204:207], v[96:99]
	v_mfma_f32_16x16x32_bf16 v[92:95], v[144:147], v[204:207], v[92:95]
	v_mfma_f32_16x16x32_bf16 v[80:83], v[136:139], v[212:215], v[80:83]
	v_mfma_f32_16x16x32_bf16 v[76:79], v[144:147], v[212:215], v[76:79]
	s_setprio 0
	s_setprio 1
	v_mfma_f32_16x16x32_bf16 v[120:123], v[160:163], v[176:179], v[120:123]
	v_mfma_f32_16x16x32_bf16 v[116:119], v[168:171], v[176:179], v[116:119]
	v_mfma_f32_16x16x32_bf16 v[104:107], v[160:163], v[188:191], v[104:107]
	v_mfma_f32_16x16x32_bf16 v[100:103], v[168:171], v[188:191], v[100:103]
	v_mfma_f32_16x16x32_bf16 v[88:91], v[160:163], v[200:203], v[88:91]
	v_mfma_f32_16x16x32_bf16 v[84:87], v[168:171], v[200:203], v[84:87]
	v_mfma_f32_16x16x32_bf16 v[72:75], v[160:163], v[208:211], v[72:75]
	v_mfma_f32_16x16x32_bf16 v[68:71], v[168:171], v[208:211], v[68:71]
	v_mfma_f32_16x16x32_bf16 v[120:123], v[164:167], v[180:183], v[120:123]
	v_mfma_f32_16x16x32_bf16 v[116:119], v[172:175], v[180:183], v[116:119]
	v_mfma_f32_16x16x32_bf16 v[104:107], v[164:167], v[192:195], v[104:107]
	v_mfma_f32_16x16x32_bf16 v[100:103], v[172:175], v[192:195], v[100:103]
	v_mfma_f32_16x16x32_bf16 v[88:91], v[164:167], v[204:207], v[88:91]
	v_mfma_f32_16x16x32_bf16 v[84:87], v[172:175], v[204:207], v[84:87]
	v_mfma_f32_16x16x32_bf16 v[72:75], v[164:167], v[212:215], v[72:75]
	v_mfma_f32_16x16x32_bf16 v[68:71], v[172:175], v[212:215], v[68:71]
	s_barrier
	s_setprio 0
	s_mov_b32 m0, s49
	v_lshl_add_u64 v[198:199], s[30:31], 0, v[152:153]
	ds_read_b128 v[176:179], v186 offset:16384
	ds_read_b128 v[180:183], v186 offset:17408
	ds_read_b128 v[188:191], v186 offset:18432
	ds_read_b128 v[192:195], v186 offset:19456
	ds_read_b128 v[200:203], v186 offset:20480
	ds_read_b128 v[204:207], v186 offset:21504
	ds_read_b128 v[208:211], v186 offset:22528
	ds_read_b128 v[212:215], v186 offset:23552
	global_load_lds_dwordx4 v[198:199], off
	v_lshl_add_u64 v[216:217], s[30:31], 0, v[148:149]
	s_mov_b32 m0, s82
	v_lshl_add_u64 v[218:219], s[34:35], 0, v[152:153]
	global_load_lds_dwordx4 v[216:217], off
	s_mov_b32 m0, s85
	global_load_lds_dwordx4 v[218:219], off
	s_mov_b32 m0, s84
	v_lshl_add_u64 v[218:219], s[34:35], 0, v[148:149]
	global_load_lds_dwordx4 v[218:219], off
	s_mov_b32 m0, s59
	v_lshl_add_u64 v[218:219], s[52:53], 0, v[154:155]
	global_load_lds_dwordx4 v[218:219], off
	s_mov_b32 m0, s40
	v_lshl_add_u64 v[220:221], s[52:53], 0, v[150:151]
	global_load_lds_dwordx4 v[220:221], off
	s_setprio 1
	s_waitcnt vmcnt(8) lgkmcnt(0)
	s_barrier
	v_mfma_f32_16x16x32_bf16 v[64:67], v[132:135], v[176:179], v[64:67]
	v_mfma_f32_16x16x32_bf16 v[60:63], v[140:143], v[176:179], v[60:63]
	v_mfma_f32_16x16x32_bf16 v[48:51], v[132:135], v[188:191], v[48:51]
	v_mfma_f32_16x16x32_bf16 v[44:47], v[140:143], v[188:191], v[44:47]
	v_mfma_f32_16x16x32_bf16 v[32:35], v[132:135], v[200:203], v[32:35]
	v_mfma_f32_16x16x32_bf16 v[28:31], v[140:143], v[200:203], v[28:31]
	v_mfma_f32_16x16x32_bf16 v[16:19], v[132:135], v[208:211], v[16:19]
	v_mfma_f32_16x16x32_bf16 v[12:15], v[140:143], v[208:211], v[12:15]
	v_mfma_f32_16x16x32_bf16 v[64:67], v[136:139], v[180:183], v[64:67]
	v_mfma_f32_16x16x32_bf16 v[60:63], v[144:147], v[180:183], v[60:63]
	v_mfma_f32_16x16x32_bf16 v[48:51], v[136:139], v[192:195], v[48:51]
	v_mfma_f32_16x16x32_bf16 v[44:47], v[144:147], v[192:195], v[44:47]
	v_mfma_f32_16x16x32_bf16 v[32:35], v[136:139], v[204:207], v[32:35]
	v_mfma_f32_16x16x32_bf16 v[28:31], v[144:147], v[204:207], v[28:31]
	v_mfma_f32_16x16x32_bf16 v[16:19], v[136:139], v[212:215], v[16:19]
	v_mfma_f32_16x16x32_bf16 v[12:15], v[144:147], v[212:215], v[12:15]
	s_setprio 0
	s_setprio 1
	v_mfma_f32_16x16x32_bf16 v[56:59], v[160:163], v[176:179], v[56:59]
	v_mfma_f32_16x16x32_bf16 v[52:55], v[168:171], v[176:179], v[52:55]
	v_mfma_f32_16x16x32_bf16 v[40:43], v[160:163], v[188:191], v[40:43]
	v_mfma_f32_16x16x32_bf16 v[36:39], v[168:171], v[188:191], v[36:39]
	v_mfma_f32_16x16x32_bf16 v[24:27], v[160:163], v[200:203], v[24:27]
	v_mfma_f32_16x16x32_bf16 v[20:23], v[168:171], v[200:203], v[20:23]
	v_mfma_f32_16x16x32_bf16 v[8:11], v[160:163], v[208:211], v[8:11]
	v_mfma_f32_16x16x32_bf16 v[4:7], v[168:171], v[208:211], v[4:7]
	v_mfma_f32_16x16x32_bf16 v[56:59], v[164:167], v[180:183], v[56:59]
	v_mfma_f32_16x16x32_bf16 v[52:55], v[172:175], v[180:183], v[52:55]
	v_mfma_f32_16x16x32_bf16 v[40:43], v[164:167], v[192:195], v[40:43]
	v_mfma_f32_16x16x32_bf16 v[36:39], v[172:175], v[192:195], v[36:39]
	v_mfma_f32_16x16x32_bf16 v[24:27], v[164:167], v[204:207], v[24:27]
	v_mfma_f32_16x16x32_bf16 v[20:23], v[172:175], v[204:207], v[20:23]
	v_mfma_f32_16x16x32_bf16 v[8:11], v[164:167], v[212:215], v[8:11]
	v_mfma_f32_16x16x32_bf16 v[4:7], v[172:175], v[212:215], v[4:7]
	s_barrier
	s_setprio 0
	v_add_u32_e32 v144, s0, v3
	v_add_u32_e32 v172, s54, v3
	ds_read_b128 v[132:135], v144
	ds_read_b128 v[136:139], v144 offset:1024
	ds_read_b128 v[140:143], v144 offset:2048
	ds_read_b128 v[144:147], v144 offset:3072
	ds_read_b128 v[160:163], v172
	ds_read_b128 v[164:167], v172 offset:1024
	ds_read_b128 v[168:171], v172 offset:2048
	ds_read_b128 v[172:175], v172 offset:3072
	s_mov_b32 m0, s55
	v_lshl_add_u64 v[222:223], vcc, 0, v[154:155]
	ds_read_b128 v[176:179], v186 offset:32768
	ds_read_b128 v[180:183], v186 offset:33792
	ds_read_b128 v[188:191], v186 offset:34816
	ds_read_b128 v[192:195], v186 offset:35840
	ds_read_b128 v[200:203], v186 offset:36864
	ds_read_b128 v[204:207], v186 offset:37888
	ds_read_b128 v[208:211], v186 offset:38912
	ds_read_b128 v[212:215], v186 offset:39936
	global_load_lds_dwordx4 v[222:223], off
	s_mov_b32 m0, s50
	v_lshl_add_u64 v[222:223], vcc, 0, v[150:151]
	global_load_lds_dwordx4 v[222:223], off
	s_setprio 1
	s_waitcnt vmcnt(8) lgkmcnt(0)
	s_barrier
	v_mfma_f32_16x16x32_bf16 v[128:131], v[132:135], v[176:179], v[128:131]
	v_mfma_f32_16x16x32_bf16 v[124:127], v[140:143], v[176:179], v[124:127]
	v_mfma_f32_16x16x32_bf16 v[112:115], v[132:135], v[188:191], v[112:115]
	v_mfma_f32_16x16x32_bf16 v[108:111], v[140:143], v[188:191], v[108:111]
	v_mfma_f32_16x16x32_bf16 v[96:99], v[132:135], v[200:203], v[96:99]
	v_mfma_f32_16x16x32_bf16 v[92:95], v[140:143], v[200:203], v[92:95]
	v_mfma_f32_16x16x32_bf16 v[80:83], v[132:135], v[208:211], v[80:83]
	v_mfma_f32_16x16x32_bf16 v[76:79], v[140:143], v[208:211], v[76:79]
	v_mfma_f32_16x16x32_bf16 v[128:131], v[136:139], v[180:183], v[128:131]
	v_mfma_f32_16x16x32_bf16 v[124:127], v[144:147], v[180:183], v[124:127]
	v_mfma_f32_16x16x32_bf16 v[112:115], v[136:139], v[192:195], v[112:115]
	v_mfma_f32_16x16x32_bf16 v[108:111], v[144:147], v[192:195], v[108:111]
	v_mfma_f32_16x16x32_bf16 v[96:99], v[136:139], v[204:207], v[96:99]
	v_mfma_f32_16x16x32_bf16 v[92:95], v[144:147], v[204:207], v[92:95]
	v_mfma_f32_16x16x32_bf16 v[80:83], v[136:139], v[212:215], v[80:83]
	v_mfma_f32_16x16x32_bf16 v[76:79], v[144:147], v[212:215], v[76:79]
	s_setprio 0
	s_setprio 1
	v_mfma_f32_16x16x32_bf16 v[120:123], v[160:163], v[176:179], v[120:123]
	v_mfma_f32_16x16x32_bf16 v[116:119], v[168:171], v[176:179], v[116:119]
	v_mfma_f32_16x16x32_bf16 v[104:107], v[160:163], v[188:191], v[104:107]
	v_mfma_f32_16x16x32_bf16 v[100:103], v[168:171], v[188:191], v[100:103]
	v_mfma_f32_16x16x32_bf16 v[88:91], v[160:163], v[200:203], v[88:91]
	v_mfma_f32_16x16x32_bf16 v[84:87], v[168:171], v[200:203], v[84:87]
	v_mfma_f32_16x16x32_bf16 v[72:75], v[160:163], v[208:211], v[72:75]
	v_mfma_f32_16x16x32_bf16 v[68:71], v[168:171], v[208:211], v[68:71]
	v_mfma_f32_16x16x32_bf16 v[120:123], v[164:167], v[180:183], v[120:123]
	v_mfma_f32_16x16x32_bf16 v[116:119], v[172:175], v[180:183], v[116:119]
	v_mfma_f32_16x16x32_bf16 v[104:107], v[164:167], v[192:195], v[104:107]
	v_mfma_f32_16x16x32_bf16 v[100:103], v[172:175], v[192:195], v[100:103]
	v_mfma_f32_16x16x32_bf16 v[88:91], v[164:167], v[204:207], v[88:91]
	v_mfma_f32_16x16x32_bf16 v[84:87], v[172:175], v[204:207], v[84:87]
	v_mfma_f32_16x16x32_bf16 v[72:75], v[164:167], v[212:215], v[72:75]
	v_mfma_f32_16x16x32_bf16 v[68:71], v[172:175], v[212:215], v[68:71]
	s_barrier
	s_setprio 0
	s_mov_b32 m0, s73
	v_lshl_add_u64 v[198:199], v[198:199], 0, s[90:91]
	ds_read_b128 v[176:179], v186 offset:49152
	ds_read_b128 v[180:183], v186 offset:50176
	ds_read_b128 v[188:191], v186 offset:51200
	ds_read_b128 v[192:195], v186 offset:52224
	ds_read_b128 v[200:203], v186 offset:53248
	ds_read_b128 v[204:207], v186 offset:54272
	ds_read_b128 v[208:211], v186 offset:55296
	ds_read_b128 v[212:215], v186 offset:56320
	global_load_lds_dwordx4 v[198:199], off
	s_mov_b32 m0, s6
	v_lshl_add_u64 v[198:199], v[216:217], 0, s[90:91]
	global_load_lds_dwordx4 v[198:199], off
	s_mov_b32 m0, s83
	v_lshl_add_u64 v[198:199], s[38:39], 0, v[152:153]
	global_load_lds_dwordx4 v[198:199], off
	s_mov_b32 m0, s96
	v_lshl_add_u64 v[198:199], s[38:39], 0, v[148:149]
	global_load_lds_dwordx4 v[198:199], off
	s_mov_b32 m0, s1
	v_lshl_add_u64 v[198:199], v[218:219], 0, s[90:91]
	global_load_lds_dwordx4 v[198:199], off
	s_mov_b32 m0, s24
	v_lshl_add_u64 v[198:199], v[220:221], 0, s[90:91]
	global_load_lds_dwordx4 v[198:199], off
	s_setprio 1
	s_waitcnt vmcnt(8) lgkmcnt(0)
	s_barrier
	v_mfma_f32_16x16x32_bf16 v[64:67], v[132:135], v[176:179], v[64:67]
	v_mfma_f32_16x16x32_bf16 v[60:63], v[140:143], v[176:179], v[60:63]
	v_mfma_f32_16x16x32_bf16 v[48:51], v[132:135], v[188:191], v[48:51]
	v_mfma_f32_16x16x32_bf16 v[44:47], v[140:143], v[188:191], v[44:47]
	v_mfma_f32_16x16x32_bf16 v[32:35], v[132:135], v[200:203], v[32:35]
	v_mfma_f32_16x16x32_bf16 v[28:31], v[140:143], v[200:203], v[28:31]
	v_mfma_f32_16x16x32_bf16 v[16:19], v[132:135], v[208:211], v[16:19]
	v_mfma_f32_16x16x32_bf16 v[12:15], v[140:143], v[208:211], v[12:15]
	v_mfma_f32_16x16x32_bf16 v[64:67], v[136:139], v[180:183], v[64:67]
	v_mfma_f32_16x16x32_bf16 v[60:63], v[144:147], v[180:183], v[60:63]
	v_mfma_f32_16x16x32_bf16 v[48:51], v[136:139], v[192:195], v[48:51]
	v_mfma_f32_16x16x32_bf16 v[44:47], v[144:147], v[192:195], v[44:47]
	v_mfma_f32_16x16x32_bf16 v[32:35], v[136:139], v[204:207], v[32:35]
	v_mfma_f32_16x16x32_bf16 v[28:31], v[144:147], v[204:207], v[28:31]
	v_mfma_f32_16x16x32_bf16 v[16:19], v[136:139], v[212:215], v[16:19]
	v_mfma_f32_16x16x32_bf16 v[12:15], v[144:147], v[212:215], v[12:15]
	s_setprio 0
	s_setprio 1
	v_mfma_f32_16x16x32_bf16 v[56:59], v[160:163], v[176:179], v[56:59]
	v_mfma_f32_16x16x32_bf16 v[52:55], v[168:171], v[176:179], v[52:55]
	v_mfma_f32_16x16x32_bf16 v[40:43], v[160:163], v[188:191], v[40:43]
	v_mfma_f32_16x16x32_bf16 v[36:39], v[168:171], v[188:191], v[36:39]
	v_mfma_f32_16x16x32_bf16 v[24:27], v[160:163], v[200:203], v[24:27]
	v_mfma_f32_16x16x32_bf16 v[20:23], v[168:171], v[200:203], v[20:23]
	v_mfma_f32_16x16x32_bf16 v[8:11], v[160:163], v[208:211], v[8:11]
	v_mfma_f32_16x16x32_bf16 v[4:7], v[168:171], v[208:211], v[4:7]
	v_mfma_f32_16x16x32_bf16 v[56:59], v[164:167], v[180:183], v[56:59]
	v_mfma_f32_16x16x32_bf16 v[52:55], v[172:175], v[180:183], v[52:55]
	v_mfma_f32_16x16x32_bf16 v[40:43], v[164:167], v[192:195], v[40:43]
	v_mfma_f32_16x16x32_bf16 v[36:39], v[172:175], v[192:195], v[36:39]
	v_mfma_f32_16x16x32_bf16 v[24:27], v[164:167], v[204:207], v[24:27]
	v_mfma_f32_16x16x32_bf16 v[20:23], v[172:175], v[204:207], v[20:23]
	v_mfma_f32_16x16x32_bf16 v[8:11], v[164:167], v[212:215], v[8:11]
	v_mfma_f32_16x16x32_bf16 v[4:7], v[172:175], v[212:215], v[4:7]
	s_barrier
	s_setprio 0
	s_movk_i32 s30, 0x100
	s_andn2_b64 vcc, exec, s[36:37]
	s_mov_b64 s[38:39], -1
	s_mov_b64 s[36:37], 0
	s_cbranch_vccz .LBB0_1441
	s_and_b64 vcc, exec, s[28:29]
	s_cbranch_vccz .LBB0_1444
	s_barrier
